# v30 plus the redundant s_waitcnt lgkmcnt(0) between s_setprio 1 and the first MFMA of every compute segment removed
# speedup vs baseline: 1.0051x; 1.0051x over previous
; #define PG8_STAGE(bufoff, gbase, voff) do { _Pragma("unroll") for (int _i = 0; _i < 2; ++_i) \
;         __builtin_amdgcn_global_load_lds((const unsigned*)((const char*)(gbase) + (voff)[_i]), (LAS unsigned*)(lds + (bufoff) + ldsw + _i * 8192), 16, 0, 0); } while (0)
; #define PG8_LDA(dst, b, h) do { _Pragma("unroll") for (int m = 0; m < 4; ++m) _Pragma("unroll") for (int k = 0; k < 2; ++k) dst[m][k] = *(const LAS bf16x8*)(lds + PG8_SA(b, h) + aoff + m * 2048 + k * 1024); } while (0)
; #define PG8_LDB(dst, b, h) do { _Pragma("unroll") for (int n = 0; n < 2; ++n) _Pragma("unroll") for (int k = 0; k < 2; ++k) dst[n][k] = *(const LAS bf16x8*)(lds + PG8_SB(b, h) + boff + n * 2048 + k * 1024); } while (0)
; #define PG8_WAIT_V(n) asm volatile("s_waitcnt vmcnt(" #n ")" ::: "memory")
; template <class Epi, class Sched, bool ALIGN_EPI = false, bool SP2 = false, bool TWOA = false, bool AGM = false>
; __device__ __forceinline__ void gemm_phase(LAS unsigned char* lds, const Gemm g, const Sched& S, const Epi& E, int wid) {
;     ...
;             const bool last = (t == nt - 2);
;             const char* cA2 = TWOA ? (const char*)g.A2 + (cA - (const char*)g.A) - (size_t)nh * kstepA : cA;
;             const char* a1_ = (TWOA && t + 1 >= nh ? cA2 : cA) + (size_t)(t + 1) * kstepA;
;             const char* a2_ = last ? nA : (TWOA && t + 2 >= nh ? cA2 : cA) + (size_t)(t + 2) * kstepA; const char* a1 = a1_; const char* a2 = a2_; const char* b2 = last ? nB : cB + (size_t)(t + 2) * kstep;
;             if constexpr (TWOA) { asm volatile("" : "+s"(a1)); asm volatile("" : "+s"(a2)); }
;             const char* a3 = a2 + kstepA; const char* b3 = b2 + kstep;
;             if (last && has_next) S.a_ready(nxt);
;             if constexpr (has_mid<Epi>::value) { if (t == nh) E.mid(acc, cur, wr, wc, fr, fq); }
;             if constexpr (SP2) {
;             PG8_LDB(B0, 0, 0); PG8_LDB(B1, 0, 1); PG8_SCHED; PG8_LDA(At, 0, 0); PG8_STAGE(PG8_SA(1, 1), a1 + hstepA, voffA);
;             PG8_WAIT_V(8); PG8_WAIT_L(0); PG8_BAR; PG8_MMA(0, 0, At, B0); PG8_MMA(0, 1, At, B1); PG8_BAR; PG8_SCHED;
;             PG8_LDA(At, 0, 1); PG8_STAGE(PG8_SB(0, 0), b2, voffB); PG8_STAGE(PG8_SB(0, 1), b2 + hstep, voffB); PG8_STAGE(PG8_SA(0, 0), a2, voffA);
;             PG8_WAIT_V(8); PG8_WAIT_L(0); PG8_BAR; PG8_MMA(1, 0, At, B0); PG8_MMA(1, 1, At, B1); PG8_BAR; PG8_SCHED;
.LBB0_230:
	ds_read_b128 v[146:149], v155
	ds_read_b128 v[160:163], v155 offset:1024
	ds_read_b128 v[164:167], v155 offset:2048
	ds_read_b128 v[168:171], v155 offset:3072
	ds_read_b128 v[172:175], v156
	ds_read_b128 v[176:179], v156 offset:1024
	ds_read_b128 v[180:183], v156 offset:2048
	ds_read_b128 v[184:187], v156 offset:3072
	s_add_u32 s12, s10, 0xfff00080
	s_addc_u32 s13, s11, -1
	s_cmp_eq_u32 s70, 60
	s_cselect_b32 s67, s7, s13
	s_cselect_b32 s66, s9, s12
	s_cselect_b32 s13, s53, s69
	s_cselect_b32 s12, s55, s68
	s_add_i32 m0, s76, 0xc000
	ds_read_b128 v[188:191], v157
	ds_read_b128 v[192:195], v157 offset:1024
	ds_read_b128 v[196:199], v157 offset:2048
	ds_read_b128 v[200:203], v157 offset:3072
	ds_read_b128 v[204:207], v157 offset:4096
	ds_read_b128 v[208:211], v157 offset:5120
	ds_read_b128 v[212:215], v157 offset:6144
	ds_read_b128 v[216:219], v157 offset:7168
	global_load_lds_dwordx4 v138, s[10:11]
	s_add_i32 m0, s76, 0xe000
	s_nop 0
	global_load_lds_dwordx4 v140, s[10:11]
	s_waitcnt vmcnt(8)
	s_waitcnt lgkmcnt(0)
	s_barrier
	s_setprio 1
	v_mfma_f32_16x16x32_bf16 v[124:127], v[146:149], v[188:191], v[124:127]
	v_mfma_f32_16x16x32_bf16 v[120:123], v[164:167], v[188:191], v[120:123]
	v_mfma_f32_16x16x32_bf16 v[108:111], v[146:149], v[196:199], v[108:111]
	v_mfma_f32_16x16x32_bf16 v[104:107], v[164:167], v[196:199], v[104:107]
	v_mfma_f32_16x16x32_bf16 v[92:95], v[146:149], v[204:207], v[92:95]
	v_mfma_f32_16x16x32_bf16 v[88:91], v[164:167], v[204:207], v[88:91]
	v_mfma_f32_16x16x32_bf16 v[76:79], v[146:149], v[212:215], v[76:79]
	v_mfma_f32_16x16x32_bf16 v[72:75], v[164:167], v[212:215], v[72:75]
	v_mfma_f32_16x16x32_bf16 v[124:127], v[160:163], v[192:195], v[124:127]
	v_mfma_f32_16x16x32_bf16 v[120:123], v[168:171], v[192:195], v[120:123]
	v_mfma_f32_16x16x32_bf16 v[108:111], v[160:163], v[200:203], v[108:111]
	v_mfma_f32_16x16x32_bf16 v[104:107], v[168:171], v[200:203], v[104:107]
	v_mfma_f32_16x16x32_bf16 v[92:95], v[160:163], v[208:211], v[92:95]
	v_mfma_f32_16x16x32_bf16 v[88:91], v[168:171], v[208:211], v[88:91]
	v_mfma_f32_16x16x32_bf16 v[76:79], v[160:163], v[216:219], v[76:79]
	v_mfma_f32_16x16x32_bf16 v[72:75], v[168:171], v[216:219], v[72:75]
	s_setprio 0
	s_setprio 1
	v_mfma_f32_16x16x32_bf16 v[116:119], v[172:175], v[188:191], v[116:119]
	v_mfma_f32_16x16x32_bf16 v[112:115], v[180:183], v[188:191], v[112:115]
	v_mfma_f32_16x16x32_bf16 v[100:103], v[172:175], v[196:199], v[100:103]
	v_mfma_f32_16x16x32_bf16 v[96:99], v[180:183], v[196:199], v[96:99]
	v_mfma_f32_16x16x32_bf16 v[84:87], v[172:175], v[204:207], v[84:87]
	v_mfma_f32_16x16x32_bf16 v[80:83], v[180:183], v[204:207], v[80:83]
	v_mfma_f32_16x16x32_bf16 v[68:71], v[172:175], v[212:215], v[68:71]
	v_mfma_f32_16x16x32_bf16 v[64:67], v[180:183], v[212:215], v[64:67]
	v_mfma_f32_16x16x32_bf16 v[116:119], v[176:179], v[192:195], v[116:119]
	v_mfma_f32_16x16x32_bf16 v[112:115], v[184:187], v[192:195], v[112:115]
	v_mfma_f32_16x16x32_bf16 v[100:103], v[176:179], v[200:203], v[100:103]
	v_mfma_f32_16x16x32_bf16 v[96:99], v[184:187], v[200:203], v[96:99]
	v_mfma_f32_16x16x32_bf16 v[84:87], v[176:179], v[208:211], v[84:87]
	v_mfma_f32_16x16x32_bf16 v[80:83], v[184:187], v[208:211], v[80:83]
	v_mfma_f32_16x16x32_bf16 v[68:71], v[176:179], v[216:219], v[68:71]
	v_mfma_f32_16x16x32_bf16 v[64:67], v[184:187], v[216:219], v[64:67]
	s_setprio 0
	s_barrier
	s_add_i32 s34, s95, s75
	s_mov_b32 m0, s34
	ds_read_b128 v[188:191], v157 offset:16384
	ds_read_b128 v[192:195], v157 offset:17408
	ds_read_b128 v[196:199], v157 offset:18432
	ds_read_b128 v[200:203], v157 offset:19456
	ds_read_b128 v[204:207], v157 offset:20480
	ds_read_b128 v[208:211], v157 offset:21504
	ds_read_b128 v[212:215], v157 offset:22528
	ds_read_b128 v[216:219], v157 offset:23552
	global_load_lds_dwordx4 v130, s[12:13]
	s_add_i32 m0, s34, 0x2000
	s_add_u32 s34, s12, 0x100000
	s_addc_u32 s35, s13, 0
	s_add_i32 s71, s96, s75
	global_load_lds_dwordx4 v134, s[12:13]
	s_mov_b32 m0, s71
	s_nop 0
	global_load_lds_dwordx4 v130, s[34:35]
	s_add_i32 m0, s71, 0x2000
	s_nop 0
	global_load_lds_dwordx4 v134, s[34:35]
	s_mov_b32 m0, s76
	s_nop 0
	global_load_lds_dwordx4 v128, s[66:67]
	s_mov_b32 m0, s77
	s_nop 0
	global_load_lds_dwordx4 v132, s[66:67]
	s_waitcnt vmcnt(8)
	s_waitcnt lgkmcnt(0)
	s_barrier
	s_setprio 1
	v_mfma_f32_16x16x32_bf16 v[60:63], v[146:149], v[188:191], v[60:63]
	v_mfma_f32_16x16x32_bf16 v[56:59], v[164:167], v[188:191], v[56:59]
	v_mfma_f32_16x16x32_bf16 v[44:47], v[146:149], v[196:199], v[44:47]
	v_mfma_f32_16x16x32_bf16 v[40:43], v[164:167], v[196:199], v[40:43]
	v_mfma_f32_16x16x32_bf16 v[28:31], v[146:149], v[204:207], v[28:31]
	v_mfma_f32_16x16x32_bf16 v[24:27], v[164:167], v[204:207], v[24:27]
	v_mfma_f32_16x16x32_bf16 v[12:15], v[146:149], v[212:215], v[12:15]
	v_mfma_f32_16x16x32_bf16 v[8:11], v[164:167], v[212:215], v[8:11]
	v_mfma_f32_16x16x32_bf16 v[60:63], v[160:163], v[192:195], v[60:63]
	v_mfma_f32_16x16x32_bf16 v[56:59], v[168:171], v[192:195], v[56:59]
	v_mfma_f32_16x16x32_bf16 v[44:47], v[160:163], v[200:203], v[44:47]
	v_mfma_f32_16x16x32_bf16 v[40:43], v[168:171], v[200:203], v[40:43]
	v_mfma_f32_16x16x32_bf16 v[28:31], v[160:163], v[208:211], v[28:31]
	v_mfma_f32_16x16x32_bf16 v[24:27], v[168:171], v[208:211], v[24:27]
	v_mfma_f32_16x16x32_bf16 v[12:15], v[160:163], v[216:219], v[12:15]
	v_mfma_f32_16x16x32_bf16 v[8:11], v[168:171], v[216:219], v[8:11]
	s_setprio 0
	s_setprio 1
	v_mfma_f32_16x16x32_bf16 v[52:55], v[172:175], v[188:191], v[52:55]
	v_mfma_f32_16x16x32_bf16 v[48:51], v[180:183], v[188:191], v[48:51]
	v_mfma_f32_16x16x32_bf16 v[36:39], v[172:175], v[196:199], v[36:39]
	v_mfma_f32_16x16x32_bf16 v[32:35], v[180:183], v[196:199], v[32:35]
	v_mfma_f32_16x16x32_bf16 v[20:23], v[172:175], v[204:207], v[20:23]
	v_mfma_f32_16x16x32_bf16 v[16:19], v[180:183], v[204:207], v[16:19]
	v_mfma_f32_16x16x32_bf16 v[4:7], v[172:175], v[212:215], v[4:7]
	v_mfma_f32_16x16x32_bf16 v[0:3], v[180:183], v[212:215], v[0:3]
	v_mfma_f32_16x16x32_bf16 v[52:55], v[176:179], v[192:195], v[52:55]
	v_mfma_f32_16x16x32_bf16 v[48:51], v[184:187], v[192:195], v[48:51]
	v_mfma_f32_16x16x32_bf16 v[36:39], v[176:179], v[200:203], v[36:39]
	v_mfma_f32_16x16x32_bf16 v[32:35], v[184:187], v[200:203], v[32:35]
	v_mfma_f32_16x16x32_bf16 v[20:23], v[176:179], v[208:211], v[20:23]
	v_mfma_f32_16x16x32_bf16 v[16:19], v[184:187], v[208:211], v[16:19]
	v_mfma_f32_16x16x32_bf16 v[4:7], v[176:179], v[216:219], v[4:7]
	v_mfma_f32_16x16x32_bf16 v[0:3], v[184:187], v[216:219], v[0:3]
	s_setprio 0
	s_barrier
; #define PG8_STAGE(bufoff, gbase, voff) do { _Pragma("unroll") for (int _i = 0; _i < 2; ++_i) \
;         __builtin_amdgcn_global_load_lds((const unsigned*)((const char*)(gbase) + (voff)[_i]), (LAS unsigned*)(lds + (bufoff) + ldsw + _i * 8192), 16, 0, 0); } while (0)
; #define PG8_LDA(dst, b, h) do { _Pragma("unroll") for (int m = 0; m < 4; ++m) _Pragma("unroll") for (int k = 0; k < 2; ++k) dst[m][k] = *(const LAS bf16x8*)(lds + PG8_SA(b, h) + aoff + m * 2048 + k * 1024); } while (0)
; #define PG8_LDB(dst, b, h) do { _Pragma("unroll") for (int n = 0; n < 2; ++n) _Pragma("unroll") for (int k = 0; k < 2; ++k) dst[n][k] = *(const LAS bf16x8*)(lds + PG8_SB(b, h) + boff + n * 2048 + k * 1024); } while (0)
; #define PG8_MMA(ai, bj, At, Bt) do { __builtin_amdgcn_s_setprio(1); _Pragma("unroll") for (int m = 0; m < 4; ++m) _Pragma("unroll") for (int n = 0; n < 2; ++n) _Pragma("unroll") for (int k = 0; k < 2; ++k) \
;         acc[ai][bj][m][n] = __builtin_amdgcn_mfma_f32_16x16x32_bf16(Bt[n][k], At[m][k], acc[ai][bj][m][n], 0, 0, 0); __builtin_amdgcn_s_setprio(0); } while (0)
; #define PG8_WAIT_V(n) asm volatile("s_waitcnt vmcnt(" #n ")" ::: "memory")
; #define PG8_WAIT_L(n) asm volatile("s_waitcnt lgkmcnt(" #n ")" ::: "memory")
; #define PG8_BAR __builtin_amdgcn_s_barrier()
; #define PG8_SCHED __builtin_amdgcn_sched_barrier(0)
; template <class Epi, class Sched, bool ALIGN_EPI = false, bool SP2 = false, bool TWOA = false, bool AGM = false>
; __device__ __forceinline__ void gemm_phase(LAS unsigned char* lds, const Gemm g, const Sched& S, const Epi& E, int wid) {
;     ...
;             PG8_LDB(B0, 1, 0); PG8_LDB(B1, 1, 1); PG8_SCHED; PG8_LDA(At, 1, 0); PG8_STAGE(PG8_SA(0, 1), a2 + hstepA, voffA);
;             PG8_WAIT_V(8); PG8_WAIT_L(0); PG8_BAR; PG8_MMA(0, 0, At, B0); PG8_MMA(0, 1, At, B1); PG8_BAR; PG8_SCHED;
;             PG8_LDA(At, 1, 1); PG8_STAGE(PG8_SB(1, 0), b3, voffB); PG8_STAGE(PG8_SB(1, 1), b3 + hstep, voffB); PG8_STAGE(PG8_SA(1, 0), a3, voffA);
;             PG8_WAIT_V(8); PG8_WAIT_L(0); PG8_BAR; PG8_MMA(1, 0, At, B0); PG8_MMA(1, 1, At, B1); PG8_BAR; PG8_SCHED;
;     ...
;         }
;         if constexpr (ALIGN_EPI) { if (wr == 0) PG8_BAR; }
	s_add_i32 s71, 0, 0x18000
	v_add_u32_e32 v136, s71, v153
	s_add_i32 s72, 0, 0x1c000
	ds_read_b128 v[146:149], v136
	ds_read_b128 v[160:163], v136 offset:1024
	ds_read_b128 v[164:167], v136 offset:2048
	ds_read_b128 v[168:171], v136 offset:3072
	v_add_u32_e32 v136, s72, v153
	ds_read_b128 v[172:175], v136
	ds_read_b128 v[176:179], v136 offset:1024
	ds_read_b128 v[180:183], v136 offset:2048
	ds_read_b128 v[184:187], v136 offset:3072
	s_add_u32 s34, s66, 0x100000
	s_addc_u32 s35, s67, 0
	s_mov_b32 m0, s81
	ds_read_b128 v[188:191], v157 offset:32768
	ds_read_b128 v[192:195], v157 offset:33792
	ds_read_b128 v[196:199], v157 offset:34816
	ds_read_b128 v[200:203], v157 offset:35840
	ds_read_b128 v[204:207], v157 offset:36864
	ds_read_b128 v[208:211], v157 offset:37888
	ds_read_b128 v[212:215], v157 offset:38912
	ds_read_b128 v[216:219], v157 offset:39936
	global_load_lds_dwordx4 v128, s[34:35]
	s_mov_b32 m0, s82
	s_nop 0
	global_load_lds_dwordx4 v132, s[34:35]
	s_waitcnt vmcnt(8)
	s_waitcnt lgkmcnt(0)
	s_barrier
	s_setprio 1
	v_mfma_f32_16x16x32_bf16 v[124:127], v[146:149], v[188:191], v[124:127]
	v_mfma_f32_16x16x32_bf16 v[120:123], v[164:167], v[188:191], v[120:123]
	v_mfma_f32_16x16x32_bf16 v[108:111], v[146:149], v[196:199], v[108:111]
	v_mfma_f32_16x16x32_bf16 v[104:107], v[164:167], v[196:199], v[104:107]
	v_mfma_f32_16x16x32_bf16 v[92:95], v[146:149], v[204:207], v[92:95]
	v_mfma_f32_16x16x32_bf16 v[88:91], v[164:167], v[204:207], v[88:91]
	v_mfma_f32_16x16x32_bf16 v[76:79], v[146:149], v[212:215], v[76:79]
	v_mfma_f32_16x16x32_bf16 v[72:75], v[164:167], v[212:215], v[72:75]
	v_mfma_f32_16x16x32_bf16 v[124:127], v[160:163], v[192:195], v[124:127]
	v_mfma_f32_16x16x32_bf16 v[120:123], v[168:171], v[192:195], v[120:123]
	v_mfma_f32_16x16x32_bf16 v[108:111], v[160:163], v[200:203], v[108:111]
	v_mfma_f32_16x16x32_bf16 v[104:107], v[168:171], v[200:203], v[104:107]
	v_mfma_f32_16x16x32_bf16 v[92:95], v[160:163], v[208:211], v[92:95]
	v_mfma_f32_16x16x32_bf16 v[88:91], v[168:171], v[208:211], v[88:91]
	v_mfma_f32_16x16x32_bf16 v[76:79], v[160:163], v[216:219], v[76:79]
	v_mfma_f32_16x16x32_bf16 v[72:75], v[168:171], v[216:219], v[72:75]
	s_setprio 0
	s_setprio 1
	v_mfma_f32_16x16x32_bf16 v[116:119], v[172:175], v[188:191], v[116:119]
	v_mfma_f32_16x16x32_bf16 v[112:115], v[180:183], v[188:191], v[112:115]
	v_mfma_f32_16x16x32_bf16 v[100:103], v[172:175], v[196:199], v[100:103]
	v_mfma_f32_16x16x32_bf16 v[96:99], v[180:183], v[196:199], v[96:99]
	v_mfma_f32_16x16x32_bf16 v[84:87], v[172:175], v[204:207], v[84:87]
	v_mfma_f32_16x16x32_bf16 v[80:83], v[180:183], v[204:207], v[80:83]
	v_mfma_f32_16x16x32_bf16 v[68:71], v[172:175], v[212:215], v[68:71]
	v_mfma_f32_16x16x32_bf16 v[64:67], v[180:183], v[212:215], v[64:67]
	v_mfma_f32_16x16x32_bf16 v[116:119], v[176:179], v[192:195], v[116:119]
	v_mfma_f32_16x16x32_bf16 v[112:115], v[184:187], v[192:195], v[112:115]
	v_mfma_f32_16x16x32_bf16 v[100:103], v[176:179], v[200:203], v[100:103]
	v_mfma_f32_16x16x32_bf16 v[96:99], v[184:187], v[200:203], v[96:99]
	v_mfma_f32_16x16x32_bf16 v[84:87], v[176:179], v[208:211], v[84:87]
	v_mfma_f32_16x16x32_bf16 v[80:83], v[184:187], v[208:211], v[80:83]
	v_mfma_f32_16x16x32_bf16 v[68:71], v[176:179], v[216:219], v[68:71]
	v_mfma_f32_16x16x32_bf16 v[64:67], v[184:187], v[216:219], v[64:67]
	s_setprio 0
	s_barrier
	s_add_i32 s34, s71, s75
	s_add_u32 s98, s12, s46
	s_addc_u32 s99, s13, s47
	s_mov_b32 m0, s34
	ds_read_b128 v[188:191], v157 offset:49152
	ds_read_b128 v[192:195], v157 offset:50176
	ds_read_b128 v[196:199], v157 offset:51200
	ds_read_b128 v[200:203], v157 offset:52224
	ds_read_b128 v[204:207], v157 offset:53248
	ds_read_b128 v[208:211], v157 offset:54272
	ds_read_b128 v[212:215], v157 offset:55296
	ds_read_b128 v[216:219], v157 offset:56320
	global_load_lds_dwordx4 v130, s[98:99]
	s_add_i32 m0, s34, 0x2000
	s_add_u32 s12, s12, 0x100080
	s_addc_u32 s13, s13, 0
	s_add_i32 s34, s72, s75
	global_load_lds_dwordx4 v134, s[98:99]
	s_mov_b32 m0, s34
	s_nop 0
	global_load_lds_dwordx4 v130, s[12:13]
	s_add_i32 m0, s34, 0x2000
	s_nop 0
	global_load_lds_dwordx4 v134, s[12:13]
	s_add_u32 s100, s66, s46
	s_addc_u32 s101, s67, s47
	s_mov_b32 m0, s88
	s_nop 0
	global_load_lds_dwordx4 v128, s[100:101]
	s_mov_b32 m0, s89
	s_nop 0
	global_load_lds_dwordx4 v132, s[100:101]
	s_waitcnt vmcnt(8)
	s_waitcnt lgkmcnt(0)
	s_barrier
	s_setprio 1
	v_mfma_f32_16x16x32_bf16 v[60:63], v[146:149], v[188:191], v[60:63]
	v_mfma_f32_16x16x32_bf16 v[56:59], v[164:167], v[188:191], v[56:59]
	v_mfma_f32_16x16x32_bf16 v[44:47], v[146:149], v[196:199], v[44:47]
	v_mfma_f32_16x16x32_bf16 v[40:43], v[164:167], v[196:199], v[40:43]
	v_mfma_f32_16x16x32_bf16 v[28:31], v[146:149], v[204:207], v[28:31]
	v_mfma_f32_16x16x32_bf16 v[24:27], v[164:167], v[204:207], v[24:27]
	v_mfma_f32_16x16x32_bf16 v[12:15], v[146:149], v[212:215], v[12:15]
	v_mfma_f32_16x16x32_bf16 v[8:11], v[164:167], v[212:215], v[8:11]
	v_mfma_f32_16x16x32_bf16 v[60:63], v[160:163], v[192:195], v[60:63]
	v_mfma_f32_16x16x32_bf16 v[56:59], v[168:171], v[192:195], v[56:59]
	v_mfma_f32_16x16x32_bf16 v[44:47], v[160:163], v[200:203], v[44:47]
	v_mfma_f32_16x16x32_bf16 v[40:43], v[168:171], v[200:203], v[40:43]
	v_mfma_f32_16x16x32_bf16 v[28:31], v[160:163], v[208:211], v[28:31]
	v_mfma_f32_16x16x32_bf16 v[24:27], v[168:171], v[208:211], v[24:27]
	v_mfma_f32_16x16x32_bf16 v[12:15], v[160:163], v[216:219], v[12:15]
	v_mfma_f32_16x16x32_bf16 v[8:11], v[168:171], v[216:219], v[8:11]
	s_setprio 0
	s_setprio 1
	v_mfma_f32_16x16x32_bf16 v[52:55], v[172:175], v[188:191], v[52:55]
	v_mfma_f32_16x16x32_bf16 v[48:51], v[180:183], v[188:191], v[48:51]
	v_mfma_f32_16x16x32_bf16 v[36:39], v[172:175], v[196:199], v[36:39]
	v_mfma_f32_16x16x32_bf16 v[32:35], v[180:183], v[196:199], v[32:35]
	v_mfma_f32_16x16x32_bf16 v[20:23], v[172:175], v[204:207], v[20:23]
	v_mfma_f32_16x16x32_bf16 v[16:19], v[180:183], v[204:207], v[16:19]
	v_mfma_f32_16x16x32_bf16 v[4:7], v[172:175], v[212:215], v[4:7]
	v_mfma_f32_16x16x32_bf16 v[0:3], v[180:183], v[212:215], v[0:3]
	v_mfma_f32_16x16x32_bf16 v[52:55], v[176:179], v[192:195], v[52:55]
	v_mfma_f32_16x16x32_bf16 v[48:51], v[184:187], v[192:195], v[48:51]
	v_mfma_f32_16x16x32_bf16 v[36:39], v[176:179], v[200:203], v[36:39]
	v_mfma_f32_16x16x32_bf16 v[32:35], v[184:187], v[200:203], v[32:35]
	v_mfma_f32_16x16x32_bf16 v[20:23], v[176:179], v[208:211], v[20:23]
	v_mfma_f32_16x16x32_bf16 v[16:19], v[184:187], v[208:211], v[16:19]
	v_mfma_f32_16x16x32_bf16 v[4:7], v[176:179], v[216:219], v[4:7]
	v_mfma_f32_16x16x32_bf16 v[0:3], v[184:187], v[216:219], v[0:3]
	s_setprio 0
	s_barrier
	s_add_i32 s70, s70, 2
	s_add_u32 s10, s10, 0x100
	s_addc_u32 s11, s11, 0
	s_add_u32 s68, s68, 0x100
	s_addc_u32 s69, s69, 0
	s_cmp_gt_u32 s70, 61
	s_cbranch_scc0 .LBB0_230
	s_and_b64 vcc, exec, s[50:51]
	s_cbranch_vccz .LBB0_233
	s_barrier

; #define PG8_STAGE(bufoff, gbase, voff) do { _Pragma("unroll") for (int _i = 0; _i < 2; ++_i) \
;         __builtin_amdgcn_global_load_lds((const unsigned*)((const char*)(gbase) + (voff)[_i]), (LAS unsigned*)(lds + (bufoff) + ldsw + _i * 8192), 16, 0, 0); } while (0)
; #define PG8_LDA(dst, b, h) do { _Pragma("unroll") for (int m = 0; m < 4; ++m) _Pragma("unroll") for (int k = 0; k < 2; ++k) dst[m][k] = *(const LAS bf16x8*)(lds + PG8_SA(b, h) + aoff + m * 2048 + k * 1024); } while (0)
; #define PG8_LDB(dst, b, h) do { _Pragma("unroll") for (int n = 0; n < 2; ++n) _Pragma("unroll") for (int k = 0; k < 2; ++k) dst[n][k] = *(const LAS bf16x8*)(lds + PG8_SB(b, h) + boff + n * 2048 + k * 1024); } while (0)
; #define PG8_MMA(ai, bj, At, Bt) do { __builtin_amdgcn_s_setprio(1); _Pragma("unroll") for (int m = 0; m < 4; ++m) _Pragma("unroll") for (int n = 0; n < 2; ++n) _Pragma("unroll") for (int k = 0; k < 2; ++k) \
;         acc[ai][bj][m][n] = __builtin_amdgcn_mfma_f32_16x16x32_bf16(Bt[n][k], At[m][k], acc[ai][bj][m][n], 0, 0, 0); __builtin_amdgcn_s_setprio(0); } while (0)
; #define PG8_WAIT_V(n) asm volatile("s_waitcnt vmcnt(" #n ")" ::: "memory")
; #define PG8_WAIT_L(n) asm volatile("s_waitcnt lgkmcnt(" #n ")" ::: "memory")
; #define PG8_BAR __builtin_amdgcn_s_barrier()
; #define PG8_SCHED __builtin_amdgcn_sched_barrier(0)
; template <class Epi, class Sched, bool ALIGN_EPI = false, bool SP2 = false, bool TWOA = false, bool AGM = false>
; __device__ __forceinline__ void gemm_phase(LAS unsigned char* lds, const Gemm g, const Sched& S, const Epi& E, int wid) {
;     ...
;             PG8_LDB(B0, 0, 0); PG8_LDB(B1, 0, 1); PG8_SCHED; PG8_LDA(At, 0, 0); PG8_STAGE(PG8_SA(1, 1), a1 + hstepA, voffA);
;             PG8_WAIT_V(8); PG8_WAIT_L(0); PG8_BAR; PG8_MMA(0, 0, At, B0); PG8_MMA(0, 1, At, B1); PG8_BAR; PG8_SCHED;
;             PG8_LDA(At, 0, 1); PG8_STAGE(PG8_SB(0, 0), b2, voffB); PG8_STAGE(PG8_SB(0, 1), b2 + hstep, voffB); PG8_STAGE(PG8_SA(0, 0), a2, voffA);
;             PG8_WAIT_V(8); PG8_WAIT_L(0); PG8_BAR; PG8_MMA(1, 0, At, B0); PG8_MMA(1, 1, At, B1); PG8_BAR; PG8_SCHED;
.LBB0_523:
	ds_read_b128 v[0:3], v137
	ds_read_b128 v[4:7], v137 offset:1024
	ds_read_b128 v[8:11], v137 offset:2048
	ds_read_b128 v[12:15], v137 offset:3072
	ds_read_b128 v[16:19], v138
	ds_read_b128 v[20:23], v138 offset:1024
	ds_read_b128 v[24:27], v138 offset:2048
	ds_read_b128 v[28:31], v138 offset:3072
	s_ashr_i32 s27, s26, 31
	s_lshl_b64 s[30:31], s[26:27], 17
	s_add_u32 s30, s3, s30
	s_addc_u32 s31, s50, s31
	s_and_b64 s[34:35], s[36:37], exec
	s_cselect_b32 s47, s31, s41
	s_cselect_b32 s46, s30, s40
	s_ashr_i32 s25, s24, 31
	s_lshl_b64 s[34:35], s[24:25], 17
	s_add_u32 s38, s51, s34
	s_addc_u32 s39, s52, s35
	s_and_b64 s[34:35], s[36:37], exec
	s_cselect_b32 s43, s39, s45
	s_cselect_b32 s42, s38, s44
	s_add_u32 s34, s40, 0x10080
	s_addc_u32 s35, s41, 0
	s_mov_b32 m0, s66
	v_lshl_add_u64 v[64:65], s[34:35], 0, v[134:135]
	ds_read_b128 v[32:35], v139
	ds_read_b128 v[36:39], v139 offset:1024
	ds_read_b128 v[40:43], v139 offset:2048
	ds_read_b128 v[44:47], v139 offset:3072
	ds_read_b128 v[48:51], v139 offset:4096
	ds_read_b128 v[52:55], v139 offset:5120
	ds_read_b128 v[56:59], v139 offset:6144
	ds_read_b128 v[60:63], v139 offset:7168
	global_load_lds_dwordx4 v[64:65], off
	v_lshl_add_u64 v[64:65], s[34:35], 0, v[130:131]
	s_mov_b32 m0, s67
	s_nop 0
	global_load_lds_dwordx4 v[64:65], off
	s_waitcnt vmcnt(8)
	s_waitcnt lgkmcnt(0)
	s_barrier
	s_setprio 1
	v_mfma_f32_16x16x32_bf16 v[64:67], v[0:3], v[32:35], 0
	v_mfma_f32_16x16x32_bf16 v[68:71], v[8:11], v[32:35], 0
	v_mfma_f32_16x16x32_bf16 v[72:75], v[0:3], v[40:43], 0
	v_mfma_f32_16x16x32_bf16 v[76:79], v[8:11], v[40:43], 0
	v_mfma_f32_16x16x32_bf16 v[80:83], v[0:3], v[48:51], 0
	v_mfma_f32_16x16x32_bf16 v[84:87], v[8:11], v[48:51], 0
	v_mfma_f32_16x16x32_bf16 v[88:91], v[0:3], v[56:59], 0
	v_mfma_f32_16x16x32_bf16 v[92:95], v[8:11], v[56:59], 0
	v_mfma_f32_16x16x32_bf16 v[64:67], v[4:7], v[36:39], v[64:67]
	v_mfma_f32_16x16x32_bf16 v[68:71], v[12:15], v[36:39], v[68:71]
	v_mfma_f32_16x16x32_bf16 v[72:75], v[4:7], v[44:47], v[72:75]
	v_mfma_f32_16x16x32_bf16 v[76:79], v[12:15], v[44:47], v[76:79]
	v_mfma_f32_16x16x32_bf16 v[80:83], v[4:7], v[52:55], v[80:83]
	v_mfma_f32_16x16x32_bf16 v[84:87], v[12:15], v[52:55], v[84:87]
	v_mfma_f32_16x16x32_bf16 v[88:91], v[4:7], v[60:63], v[88:91]
	v_mfma_f32_16x16x32_bf16 v[92:95], v[12:15], v[60:63], v[92:95]
	s_setprio 0
	s_setprio 1
	v_mfma_f32_16x16x32_bf16 v[96:99], v[16:19], v[32:35], 0
	v_mfma_f32_16x16x32_bf16 v[32:35], v[24:27], v[32:35], 0
	v_mfma_f32_16x16x32_bf16 v[96:99], v[20:23], v[36:39], v[96:99]
	v_mfma_f32_16x16x32_bf16 v[32:35], v[28:31], v[36:39], v[32:35]
	v_mfma_f32_16x16x32_bf16 v[36:39], v[16:19], v[40:43], 0
	v_mfma_f32_16x16x32_bf16 v[40:43], v[24:27], v[40:43], 0
	v_mfma_f32_16x16x32_bf16 v[36:39], v[20:23], v[44:47], v[36:39]
	v_mfma_f32_16x16x32_bf16 v[40:43], v[28:31], v[44:47], v[40:43]
	v_mfma_f32_16x16x32_bf16 v[44:47], v[16:19], v[48:51], 0
	v_mfma_f32_16x16x32_bf16 v[48:51], v[24:27], v[48:51], 0
	v_mfma_f32_16x16x32_bf16 v[44:47], v[20:23], v[52:55], v[44:47]
	v_mfma_f32_16x16x32_bf16 v[48:51], v[28:31], v[52:55], v[48:51]
	v_mfma_f32_16x16x32_bf16 v[52:55], v[16:19], v[56:59], 0
	v_mfma_f32_16x16x32_bf16 v[56:59], v[24:27], v[56:59], 0
	v_mfma_f32_16x16x32_bf16 v[52:55], v[20:23], v[60:63], v[52:55]
	v_mfma_f32_16x16x32_bf16 v[56:59], v[28:31], v[60:63], v[56:59]
	s_setprio 0
	s_barrier
	v_lshl_add_u64 v[206:207], s[44:45], 0, v[132:133]
	s_mov_b32 m0, s68
	v_lshl_add_u64 v[142:143], v[206:207], 0, s[20:21]
	v_lshl_add_u64 v[208:209], s[44:45], 0, v[128:129]
	s_add_u32 s34, s44, 0x10100
	ds_read_b128 v[60:63], v139 offset:16384
	ds_read_b128 v[100:103], v139 offset:17408
	ds_read_b128 v[104:107], v139 offset:18432
	ds_read_b128 v[108:111], v139 offset:19456
	ds_read_b128 v[112:115], v139 offset:20480
	ds_read_b128 v[116:119], v139 offset:21504
	ds_read_b128 v[120:123], v139 offset:22528
	ds_read_b128 v[124:127], v139 offset:23552
	global_load_lds_dwordx4 v[142:143], off
	v_lshl_add_u64 v[142:143], v[208:209], 0, s[20:21]
	s_mov_b32 m0, s69
	s_addc_u32 s35, s45, 0
	global_load_lds_dwordx4 v[142:143], off
	v_lshl_add_u64 v[142:143], s[34:35], 0, v[132:133]
	s_mov_b32 m0, s70
	v_lshl_add_u64 v[210:211], s[40:41], 0, v[134:135]
	global_load_lds_dwordx4 v[142:143], off
	v_lshl_add_u64 v[142:143], s[34:35], 0, v[128:129]
	s_mov_b32 m0, s71
	v_lshl_add_u64 v[212:213], s[40:41], 0, v[130:131]
	global_load_lds_dwordx4 v[142:143], off
	v_lshl_add_u64 v[142:143], v[210:211], 0, s[20:21]
	s_mov_b32 m0, s53
	s_nop 0
	global_load_lds_dwordx4 v[142:143], off
	v_lshl_add_u64 v[142:143], v[212:213], 0, s[20:21]
	s_mov_b32 m0, s54
	s_nop 0
	global_load_lds_dwordx4 v[142:143], off
	s_waitcnt vmcnt(8)
	s_waitcnt lgkmcnt(0)
	s_barrier
; #define PG8_STAGE(bufoff, gbase, voff) do { _Pragma("unroll") for (int _i = 0; _i < 2; ++_i) \
;         __builtin_amdgcn_global_load_lds((const unsigned*)((const char*)(gbase) + (voff)[_i]), (LAS unsigned*)(lds + (bufoff) + ldsw + _i * 8192), 16, 0, 0); } while (0)
; #define PG8_LDA(dst, b, h) do { _Pragma("unroll") for (int m = 0; m < 4; ++m) _Pragma("unroll") for (int k = 0; k < 2; ++k) dst[m][k] = *(const LAS bf16x8*)(lds + PG8_SA(b, h) + aoff + m * 2048 + k * 1024); } while (0)
; #define PG8_LDB(dst, b, h) do { _Pragma("unroll") for (int n = 0; n < 2; ++n) _Pragma("unroll") for (int k = 0; k < 2; ++k) dst[n][k] = *(const LAS bf16x8*)(lds + PG8_SB(b, h) + boff + n * 2048 + k * 1024); } while (0)
; #define PG8_MMA(ai, bj, At, Bt) do { __builtin_amdgcn_s_setprio(1); _Pragma("unroll") for (int m = 0; m < 4; ++m) _Pragma("unroll") for (int n = 0; n < 2; ++n) _Pragma("unroll") for (int k = 0; k < 2; ++k) \
;         acc[ai][bj][m][n] = __builtin_amdgcn_mfma_f32_16x16x32_bf16(Bt[n][k], At[m][k], acc[ai][bj][m][n], 0, 0, 0); __builtin_amdgcn_s_setprio(0); } while (0)
; #define PG8_WAIT_V(n) asm volatile("s_waitcnt vmcnt(" #n ")" ::: "memory")
; #define PG8_WAIT_L(n) asm volatile("s_waitcnt lgkmcnt(" #n ")" ::: "memory")
; #define PG8_BAR __builtin_amdgcn_s_barrier()
; #define PG8_SCHED __builtin_amdgcn_sched_barrier(0)
; template <class Epi, class Sched, bool ALIGN_EPI = false, bool SP2 = false, bool TWOA = false, bool AGM = false>
; __device__ __forceinline__ void gemm_phase(LAS unsigned char* lds, const Gemm g, const Sched& S, const Epi& E, int wid) {
;     ...
;             PG8_WAIT_V(8); PG8_WAIT_L(0); PG8_BAR; PG8_MMA(1, 0, At, B0); PG8_MMA(1, 1, At, B1); PG8_BAR; PG8_SCHED;
;             PG8_LDB(B0, 1, 0); PG8_LDB(B1, 1, 1); PG8_SCHED; PG8_LDA(At, 1, 0); PG8_STAGE(PG8_SA(0, 1), a2 + hstepA, voffA);
;             PG8_WAIT_V(8); PG8_WAIT_L(0); PG8_BAR; PG8_MMA(0, 0, At, B0); PG8_MMA(0, 1, At, B1); PG8_BAR; PG8_SCHED;
;             PG8_LDA(At, 1, 1); PG8_STAGE(PG8_SB(1, 0), b3, voffB); PG8_STAGE(PG8_SB(1, 1), b3 + hstep, voffB); PG8_STAGE(PG8_SA(1, 0), a3, voffA);
	s_setprio 1
	v_mfma_f32_16x16x32_bf16 v[142:145], v[0:3], v[60:63], 0
	v_mfma_f32_16x16x32_bf16 v[150:153], v[0:3], v[104:107], 0
	v_mfma_f32_16x16x32_bf16 v[158:161], v[0:3], v[112:115], 0
	v_mfma_f32_16x16x32_bf16 v[0:3], v[0:3], v[120:123], 0
	v_mfma_f32_16x16x32_bf16 v[142:145], v[4:7], v[100:103], v[142:145]
	v_mfma_f32_16x16x32_bf16 v[150:153], v[4:7], v[108:111], v[150:153]
	v_mfma_f32_16x16x32_bf16 v[158:161], v[4:7], v[116:119], v[158:161]
	v_mfma_f32_16x16x32_bf16 v[0:3], v[4:7], v[124:127], v[0:3]
	v_mfma_f32_16x16x32_bf16 v[4:7], v[8:11], v[120:123], 0
	v_mfma_f32_16x16x32_bf16 v[146:149], v[8:11], v[60:63], 0
	v_mfma_f32_16x16x32_bf16 v[154:157], v[8:11], v[104:107], 0
	v_mfma_f32_16x16x32_bf16 v[162:165], v[8:11], v[112:115], 0
	v_mfma_f32_16x16x32_bf16 v[4:7], v[12:15], v[124:127], v[4:7]
	v_mfma_f32_16x16x32_bf16 v[146:149], v[12:15], v[100:103], v[146:149]
	v_mfma_f32_16x16x32_bf16 v[154:157], v[12:15], v[108:111], v[154:157]
	v_mfma_f32_16x16x32_bf16 v[162:165], v[12:15], v[116:119], v[162:165]
	s_setprio 0
	s_setprio 1
	v_mfma_f32_16x16x32_bf16 v[8:11], v[16:19], v[60:63], 0
	v_mfma_f32_16x16x32_bf16 v[12:15], v[24:27], v[60:63], 0
	v_mfma_f32_16x16x32_bf16 v[8:11], v[20:23], v[100:103], v[8:11]
	v_mfma_f32_16x16x32_bf16 v[12:15], v[28:31], v[100:103], v[12:15]
	v_mfma_f32_16x16x32_bf16 v[60:63], v[16:19], v[104:107], 0
	v_mfma_f32_16x16x32_bf16 v[100:103], v[24:27], v[104:107], 0
	v_mfma_f32_16x16x32_bf16 v[104:107], v[16:19], v[112:115], 0
	v_mfma_f32_16x16x32_bf16 v[16:19], v[16:19], v[120:123], 0
	v_mfma_f32_16x16x32_bf16 v[60:63], v[20:23], v[108:111], v[60:63]
	v_mfma_f32_16x16x32_bf16 v[100:103], v[28:31], v[108:111], v[100:103]
	v_mfma_f32_16x16x32_bf16 v[104:107], v[20:23], v[116:119], v[104:107]
	v_mfma_f32_16x16x32_bf16 v[108:111], v[24:27], v[112:115], 0
	v_mfma_f32_16x16x32_bf16 v[16:19], v[20:23], v[124:127], v[16:19]
	v_mfma_f32_16x16x32_bf16 v[20:23], v[24:27], v[120:123], 0
	v_mfma_f32_16x16x32_bf16 v[108:111], v[28:31], v[116:119], v[108:111]
	v_mfma_f32_16x16x32_bf16 v[20:23], v[28:31], v[124:127], v[20:23]
	s_setprio 0
	s_barrier
	ds_read_b128 v[24:27], v140
	ds_read_b128 v[28:31], v140 offset:1024
	ds_read_b128 v[112:115], v140 offset:2048
	ds_read_b128 v[116:119], v140 offset:3072
	ds_read_b128 v[120:123], v141
	ds_read_b128 v[124:127], v141 offset:1024
	ds_read_b128 v[166:169], v141 offset:2048
	ds_read_b128 v[170:173], v141 offset:3072
	s_add_u32 s34, s40, 0x10100
	s_addc_u32 s35, s41, 0
	s_mov_b32 m0, s55
	v_lshl_add_u64 v[214:215], s[34:35], 0, v[134:135]
	ds_read_b128 v[174:177], v139 offset:32768
	ds_read_b128 v[178:181], v139 offset:33792
	ds_read_b128 v[182:185], v139 offset:34816
	ds_read_b128 v[186:189], v139 offset:35840
	ds_read_b128 v[190:193], v139 offset:36864
	ds_read_b128 v[194:197], v139 offset:37888
	ds_read_b128 v[198:201], v139 offset:38912
	ds_read_b128 v[202:205], v139 offset:39936
	global_load_lds_dwordx4 v[214:215], off
	v_lshl_add_u64 v[214:215], s[34:35], 0, v[130:131]
	s_mov_b32 m0, s56
	s_nop 0
	global_load_lds_dwordx4 v[214:215], off
	s_waitcnt vmcnt(8)
	s_waitcnt lgkmcnt(0)
	s_barrier
	s_setprio 1
	v_mfma_f32_16x16x32_bf16 v[64:67], v[24:27], v[174:177], v[64:67]
	v_mfma_f32_16x16x32_bf16 v[68:71], v[112:115], v[174:177], v[68:71]
	v_mfma_f32_16x16x32_bf16 v[72:75], v[24:27], v[182:185], v[72:75]
	v_mfma_f32_16x16x32_bf16 v[76:79], v[112:115], v[182:185], v[76:79]
	v_mfma_f32_16x16x32_bf16 v[80:83], v[24:27], v[190:193], v[80:83]
	v_mfma_f32_16x16x32_bf16 v[84:87], v[112:115], v[190:193], v[84:87]
	v_mfma_f32_16x16x32_bf16 v[88:91], v[24:27], v[198:201], v[88:91]
	v_mfma_f32_16x16x32_bf16 v[92:95], v[112:115], v[198:201], v[92:95]
	v_mfma_f32_16x16x32_bf16 v[64:67], v[28:31], v[178:181], v[64:67]
	v_mfma_f32_16x16x32_bf16 v[68:71], v[116:119], v[178:181], v[68:71]
	v_mfma_f32_16x16x32_bf16 v[72:75], v[28:31], v[186:189], v[72:75]
	v_mfma_f32_16x16x32_bf16 v[76:79], v[116:119], v[186:189], v[76:79]
	v_mfma_f32_16x16x32_bf16 v[80:83], v[28:31], v[194:197], v[80:83]
	v_mfma_f32_16x16x32_bf16 v[84:87], v[116:119], v[194:197], v[84:87]
	v_mfma_f32_16x16x32_bf16 v[88:91], v[28:31], v[202:205], v[88:91]
	v_mfma_f32_16x16x32_bf16 v[92:95], v[116:119], v[202:205], v[92:95]
	s_setprio 0
	s_setprio 1
	v_mfma_f32_16x16x32_bf16 v[96:99], v[120:123], v[174:177], v[96:99]
	v_mfma_f32_16x16x32_bf16 v[32:35], v[166:169], v[174:177], v[32:35]
	v_mfma_f32_16x16x32_bf16 v[36:39], v[120:123], v[182:185], v[36:39]
	v_mfma_f32_16x16x32_bf16 v[40:43], v[166:169], v[182:185], v[40:43]
	v_mfma_f32_16x16x32_bf16 v[44:47], v[120:123], v[190:193], v[44:47]
	v_mfma_f32_16x16x32_bf16 v[48:51], v[166:169], v[190:193], v[48:51]
	v_mfma_f32_16x16x32_bf16 v[52:55], v[120:123], v[198:201], v[52:55]
	v_mfma_f32_16x16x32_bf16 v[56:59], v[166:169], v[198:201], v[56:59]
	v_mfma_f32_16x16x32_bf16 v[96:99], v[124:127], v[178:181], v[96:99]
	v_mfma_f32_16x16x32_bf16 v[32:35], v[170:173], v[178:181], v[32:35]
	v_mfma_f32_16x16x32_bf16 v[36:39], v[124:127], v[186:189], v[36:39]
	v_mfma_f32_16x16x32_bf16 v[40:43], v[170:173], v[186:189], v[40:43]
	v_mfma_f32_16x16x32_bf16 v[44:47], v[124:127], v[194:197], v[44:47]
	v_mfma_f32_16x16x32_bf16 v[48:51], v[170:173], v[194:197], v[48:51]
	v_mfma_f32_16x16x32_bf16 v[52:55], v[124:127], v[202:205], v[52:55]
	v_mfma_f32_16x16x32_bf16 v[56:59], v[170:173], v[202:205], v[56:59]
	s_setprio 0
	s_barrier
; #define PG8_STAGE(bufoff, gbase, voff) do { _Pragma("unroll") for (int _i = 0; _i < 2; ++_i) \
;         __builtin_amdgcn_global_load_lds((const unsigned*)((const char*)(gbase) + (voff)[_i]), (LAS unsigned*)(lds + (bufoff) + ldsw + _i * 8192), 16, 0, 0); } while (0)
; #define PG8_LDA(dst, b, h) do { _Pragma("unroll") for (int m = 0; m < 4; ++m) _Pragma("unroll") for (int k = 0; k < 2; ++k) dst[m][k] = *(const LAS bf16x8*)(lds + PG8_SA(b, h) + aoff + m * 2048 + k * 1024); } while (0)
; #define PG8_LDB(dst, b, h) do { _Pragma("unroll") for (int n = 0; n < 2; ++n) _Pragma("unroll") for (int k = 0; k < 2; ++k) dst[n][k] = *(const LAS bf16x8*)(lds + PG8_SB(b, h) + boff + n * 2048 + k * 1024); } while (0)
; #define PG8_MMA(ai, bj, At, Bt) do { __builtin_amdgcn_s_setprio(1); _Pragma("unroll") for (int m = 0; m < 4; ++m) _Pragma("unroll") for (int n = 0; n < 2; ++n) _Pragma("unroll") for (int k = 0; k < 2; ++k) \
;         acc[ai][bj][m][n] = __builtin_amdgcn_mfma_f32_16x16x32_bf16(Bt[n][k], At[m][k], acc[ai][bj][m][n], 0, 0, 0); __builtin_amdgcn_s_setprio(0); } while (0)
; #define PG8_BAR __builtin_amdgcn_s_barrier()
; template <class Epi, class Sched, bool ALIGN_EPI = false, bool SP2 = false, bool TWOA = false, bool AGM = false>
; __device__ __forceinline__ void gemm_phase(LAS unsigned char* lds, const Gemm g, const Sched& S, const Epi& E, int wid) {
;     ...
;             PG8_LDB(B0, 0, 0); PG8_LDB(B1, 0, 1); PG8_SCHED; PG8_LDA(At, 0, 0); PG8_STAGE(PG8_SA(1, 1), a1 + hstepA, voffA);
;             PG8_WAIT_V(8); PG8_WAIT_L(0); PG8_BAR; PG8_MMA(0, 0, At, B0); PG8_MMA(0, 1, At, B1); PG8_BAR; PG8_SCHED;
;             PG8_LDA(At, 0, 1); PG8_STAGE(PG8_SB(0, 0), b2, voffB); PG8_STAGE(PG8_SB(0, 1), b2 + hstep, voffB); PG8_STAGE(PG8_SA(0, 0), a2, voffA);
;             PG8_WAIT_V(8); PG8_WAIT_L(0); PG8_BAR; PG8_MMA(1, 0, At, B0); PG8_MMA(1, 1, At, B1); PG8_BAR; PG8_SCHED;
;             PG8_LDB(B0, 1, 0); PG8_LDB(B1, 1, 1); PG8_SCHED; PG8_LDA(At, 1, 0); PG8_STAGE(PG8_SA(0, 1), a2 + hstepA, voffA);
;             PG8_WAIT_V(8); PG8_WAIT_L(0); PG8_BAR; PG8_MMA(0, 0, At, B0); PG8_MMA(0, 1, At, B1); PG8_BAR; PG8_SCHED;
;             PG8_LDA(At, 1, 1); PG8_STAGE(PG8_SB(1, 0), b3, voffB); PG8_STAGE(PG8_SB(1, 1), b3 + hstep, voffB); PG8_STAGE(PG8_SA(1, 0), a3, voffA);
;             PG8_WAIT_V(8); PG8_WAIT_L(0); PG8_BAR; PG8_MMA(1, 0, At, B0); PG8_MMA(1, 1, At, B1); PG8_BAR; PG8_SCHED;
	s_mov_b32 m0, s72
	v_lshl_add_u64 v[206:207], v[206:207], 0, s[22:23]
	s_add_u32 s34, s44, 0x10180
	ds_read_b128 v[174:177], v139 offset:49152
	ds_read_b128 v[178:181], v139 offset:50176
	ds_read_b128 v[182:185], v139 offset:51200
	ds_read_b128 v[186:189], v139 offset:52224
	ds_read_b128 v[190:193], v139 offset:53248
	ds_read_b128 v[194:197], v139 offset:54272
	ds_read_b128 v[198:201], v139 offset:55296
	ds_read_b128 v[202:205], v139 offset:56320
	global_load_lds_dwordx4 v[206:207], off
	v_lshl_add_u64 v[206:207], v[208:209], 0, s[22:23]
	s_mov_b32 m0, s73
	s_addc_u32 s35, s45, 0
	global_load_lds_dwordx4 v[206:207], off
	v_lshl_add_u64 v[206:207], s[34:35], 0, v[132:133]
	s_mov_b32 m0, s74
	s_nop 0
	global_load_lds_dwordx4 v[206:207], off
	v_lshl_add_u64 v[206:207], s[34:35], 0, v[128:129]
	s_mov_b32 m0, s75
	s_nop 0
	global_load_lds_dwordx4 v[206:207], off
	v_lshl_add_u64 v[206:207], v[210:211], 0, s[22:23]
	s_mov_b32 m0, s57
	s_nop 0
	global_load_lds_dwordx4 v[206:207], off
	v_lshl_add_u64 v[206:207], v[212:213], 0, s[22:23]
	s_mov_b32 m0, s64
	s_nop 0
	global_load_lds_dwordx4 v[206:207], off
	s_waitcnt vmcnt(8)
	s_waitcnt lgkmcnt(0)
	s_barrier
	s_setprio 1
	v_mfma_f32_16x16x32_bf16 v[0:3], v[24:27], v[198:201], v[0:3]
	v_mfma_f32_16x16x32_bf16 v[4:7], v[112:115], v[198:201], v[4:7]
	v_mfma_f32_16x16x32_bf16 v[142:145], v[24:27], v[174:177], v[142:145]
	v_mfma_f32_16x16x32_bf16 v[146:149], v[112:115], v[174:177], v[146:149]
	v_mfma_f32_16x16x32_bf16 v[150:153], v[24:27], v[182:185], v[150:153]
	v_mfma_f32_16x16x32_bf16 v[154:157], v[112:115], v[182:185], v[154:157]
	v_mfma_f32_16x16x32_bf16 v[158:161], v[24:27], v[190:193], v[158:161]
	v_mfma_f32_16x16x32_bf16 v[162:165], v[112:115], v[190:193], v[162:165]
	v_mfma_f32_16x16x32_bf16 v[0:3], v[28:31], v[202:205], v[0:3]
	v_mfma_f32_16x16x32_bf16 v[4:7], v[116:119], v[202:205], v[4:7]
	v_mfma_f32_16x16x32_bf16 v[142:145], v[28:31], v[178:181], v[142:145]
	v_mfma_f32_16x16x32_bf16 v[146:149], v[116:119], v[178:181], v[146:149]
	v_mfma_f32_16x16x32_bf16 v[150:153], v[28:31], v[186:189], v[150:153]
	v_mfma_f32_16x16x32_bf16 v[154:157], v[116:119], v[186:189], v[154:157]
	v_mfma_f32_16x16x32_bf16 v[158:161], v[28:31], v[194:197], v[158:161]
	v_mfma_f32_16x16x32_bf16 v[162:165], v[116:119], v[194:197], v[162:165]
	s_setprio 0
	s_setprio 1
	v_mfma_f32_16x16x32_bf16 v[8:11], v[120:123], v[174:177], v[8:11]
	v_mfma_f32_16x16x32_bf16 v[12:15], v[166:169], v[174:177], v[12:15]
	v_mfma_f32_16x16x32_bf16 v[24:27], v[120:123], v[182:185], v[60:63]
	v_mfma_f32_16x16x32_bf16 v[28:31], v[166:169], v[182:185], v[100:103]
	v_mfma_f32_16x16x32_bf16 v[60:63], v[120:123], v[190:193], v[104:107]
	v_mfma_f32_16x16x32_bf16 v[100:103], v[166:169], v[190:193], v[108:111]
	v_mfma_f32_16x16x32_bf16 v[16:19], v[120:123], v[198:201], v[16:19]
	v_mfma_f32_16x16x32_bf16 v[20:23], v[166:169], v[198:201], v[20:23]
	v_mfma_f32_16x16x32_bf16 v[8:11], v[124:127], v[178:181], v[8:11]
	v_mfma_f32_16x16x32_bf16 v[12:15], v[170:173], v[178:181], v[12:15]
	v_mfma_f32_16x16x32_bf16 v[24:27], v[124:127], v[186:189], v[24:27]
	v_mfma_f32_16x16x32_bf16 v[28:31], v[170:173], v[186:189], v[28:31]
	v_mfma_f32_16x16x32_bf16 v[60:63], v[124:127], v[194:197], v[60:63]
	v_mfma_f32_16x16x32_bf16 v[100:103], v[170:173], v[194:197], v[100:103]
	v_mfma_f32_16x16x32_bf16 v[16:19], v[124:127], v[202:205], v[16:19]
	v_mfma_f32_16x16x32_bf16 v[20:23], v[170:173], v[202:205], v[20:23]
	s_setprio 0
	s_barrier
	ds_read_b128 v[104:107], v137
	ds_read_b128 v[108:111], v137 offset:1024
	ds_read_b128 v[112:115], v137 offset:2048
	ds_read_b128 v[116:119], v137 offset:3072
	ds_read_b128 v[120:123], v138
	ds_read_b128 v[124:127], v138 offset:1024
	ds_read_b128 v[166:169], v138 offset:2048
	ds_read_b128 v[170:173], v138 offset:3072
	s_add_u32 s34, s40, 0x10180
	s_addc_u32 s35, s41, 0
	s_mov_b32 m0, s66
	v_lshl_add_u64 v[206:207], s[34:35], 0, v[134:135]
	ds_read_b128 v[174:177], v139
	ds_read_b128 v[178:181], v139 offset:1024
	ds_read_b128 v[182:185], v139 offset:2048
	ds_read_b128 v[186:189], v139 offset:3072
	ds_read_b128 v[190:193], v139 offset:4096
	ds_read_b128 v[194:197], v139 offset:5120
	ds_read_b128 v[198:201], v139 offset:6144
	ds_read_b128 v[202:205], v139 offset:7168
	global_load_lds_dwordx4 v[206:207], off
	v_lshl_add_u64 v[206:207], s[34:35], 0, v[130:131]
	s_mov_b32 m0, s67
	s_nop 0
	global_load_lds_dwordx4 v[206:207], off
	s_waitcnt vmcnt(8)
	s_waitcnt lgkmcnt(0)
	s_barrier
	s_setprio 1
	v_mfma_f32_16x16x32_bf16 v[88:91], v[104:107], v[198:201], v[88:91]
	v_mfma_f32_16x16x32_bf16 v[64:67], v[104:107], v[174:177], v[64:67]
	v_mfma_f32_16x16x32_bf16 v[68:71], v[112:115], v[174:177], v[68:71]
	v_mfma_f32_16x16x32_bf16 v[72:75], v[104:107], v[182:185], v[72:75]
	v_mfma_f32_16x16x32_bf16 v[76:79], v[112:115], v[182:185], v[76:79]
	v_mfma_f32_16x16x32_bf16 v[80:83], v[104:107], v[190:193], v[80:83]
	v_mfma_f32_16x16x32_bf16 v[84:87], v[112:115], v[190:193], v[84:87]
	v_mfma_f32_16x16x32_bf16 v[206:209], v[108:111], v[202:205], v[88:91]
	v_mfma_f32_16x16x32_bf16 v[88:91], v[112:115], v[198:201], v[92:95]
	v_mfma_f32_16x16x32_bf16 v[64:67], v[108:111], v[178:181], v[64:67]
	v_mfma_f32_16x16x32_bf16 v[68:71], v[116:119], v[178:181], v[68:71]
	v_mfma_f32_16x16x32_bf16 v[72:75], v[108:111], v[186:189], v[72:75]
	v_mfma_f32_16x16x32_bf16 v[76:79], v[116:119], v[186:189], v[76:79]
	v_mfma_f32_16x16x32_bf16 v[80:83], v[108:111], v[194:197], v[80:83]
	v_mfma_f32_16x16x32_bf16 v[84:87], v[116:119], v[194:197], v[84:87]
	v_mfma_f32_16x16x32_bf16 v[92:95], v[116:119], v[202:205], v[88:91]
	s_setprio 0
	s_setprio 1
	v_mfma_f32_16x16x32_bf16 v[48:51], v[166:169], v[190:193], v[48:51]
	v_mfma_f32_16x16x32_bf16 v[88:91], v[120:123], v[174:177], v[96:99]
	v_mfma_f32_16x16x32_bf16 v[32:35], v[166:169], v[174:177], v[32:35]
	v_mfma_f32_16x16x32_bf16 v[36:39], v[120:123], v[182:185], v[36:39]
	v_mfma_f32_16x16x32_bf16 v[40:43], v[166:169], v[182:185], v[40:43]
	v_mfma_f32_16x16x32_bf16 v[44:47], v[120:123], v[190:193], v[44:47]
	v_mfma_f32_16x16x32_bf16 v[174:177], v[170:173], v[194:197], v[48:51]
	v_mfma_f32_16x16x32_bf16 v[48:51], v[120:123], v[198:201], v[52:55]
	v_mfma_f32_16x16x32_bf16 v[32:35], v[170:173], v[178:181], v[32:35]
	v_mfma_f32_16x16x32_bf16 v[36:39], v[124:127], v[186:189], v[36:39]
	v_mfma_f32_16x16x32_bf16 v[40:43], v[170:173], v[186:189], v[40:43]
	v_mfma_f32_16x16x32_bf16 v[44:47], v[124:127], v[194:197], v[44:47]
	v_mfma_f32_16x16x32_bf16 v[52:55], v[124:127], v[202:205], v[48:51]
	v_mfma_f32_16x16x32_bf16 v[48:51], v[166:169], v[198:201], v[56:59]
	v_mfma_f32_16x16x32_bf16 v[210:213], v[124:127], v[178:181], v[88:91]
	v_mfma_f32_16x16x32_bf16 v[178:181], v[170:173], v[202:205], v[48:51]
	s_setprio 0
	s_barrier
; #define PG8_STAGE(bufoff, gbase, voff) do { _Pragma("unroll") for (int _i = 0; _i < 2; ++_i) \
;         __builtin_amdgcn_global_load_lds((const unsigned*)((const char*)(gbase) + (voff)[_i]), (LAS unsigned*)(lds + (bufoff) + ldsw + _i * 8192), 16, 0, 0); } while (0)
; #define PG8_LDA(dst, b, h) do { _Pragma("unroll") for (int m = 0; m < 4; ++m) _Pragma("unroll") for (int k = 0; k < 2; ++k) dst[m][k] = *(const LAS bf16x8*)(lds + PG8_SA(b, h) + aoff + m * 2048 + k * 1024); } while (0)
; #define PG8_LDB(dst, b, h) do { _Pragma("unroll") for (int n = 0; n < 2; ++n) _Pragma("unroll") for (int k = 0; k < 2; ++k) dst[n][k] = *(const LAS bf16x8*)(lds + PG8_SB(b, h) + boff + n * 2048 + k * 1024); } while (0)
; #define PG8_MMA(ai, bj, At, Bt) do { __builtin_amdgcn_s_setprio(1); _Pragma("unroll") for (int m = 0; m < 4; ++m) _Pragma("unroll") for (int n = 0; n < 2; ++n) _Pragma("unroll") for (int k = 0; k < 2; ++k) \
;         acc[ai][bj][m][n] = __builtin_amdgcn_mfma_f32_16x16x32_bf16(Bt[n][k], At[m][k], acc[ai][bj][m][n], 0, 0, 0); __builtin_amdgcn_s_setprio(0); } while (0)
; #define PG8_WAIT_V(n) asm volatile("s_waitcnt vmcnt(" #n ")" ::: "memory")
; #define PG8_WAIT_L(n) asm volatile("s_waitcnt lgkmcnt(" #n ")" ::: "memory")
; #define PG8_BAR __builtin_amdgcn_s_barrier()
; #define PG8_SCHED __builtin_amdgcn_sched_barrier(0)
; template <class Epi, class Sched, bool ALIGN_EPI = false, bool SP2 = false, bool TWOA = false, bool AGM = false>
; __device__ __forceinline__ void gemm_phase(LAS unsigned char* lds, const Gemm g, const Sched& S, const Epi& E, int wid) {
;     ...
;             PG8_LDB(B0, 0, 0); PG8_LDB(B1, 0, 1); PG8_SCHED; PG8_LDA(At, 0, 0); PG8_STAGE(PG8_SA(1, 1), a1 + hstepA, voffA);
;             PG8_WAIT_V(8); PG8_WAIT_L(0); PG8_BAR; PG8_MMA(0, 0, At, B0); PG8_MMA(0, 1, At, B1); PG8_BAR; PG8_SCHED;
;             PG8_LDA(At, 0, 1); PG8_STAGE(PG8_SB(0, 0), b2, voffB); PG8_STAGE(PG8_SB(0, 1), b2 + hstep, voffB); PG8_STAGE(PG8_SA(0, 0), a2, voffA);
;             PG8_WAIT_V(8); PG8_WAIT_L(0); PG8_BAR; PG8_MMA(1, 0, At, B0); PG8_MMA(1, 1, At, B1); PG8_BAR; PG8_SCHED;
;             PG8_LDB(B0, 1, 0); PG8_LDB(B1, 1, 1); PG8_SCHED; PG8_LDA(At, 1, 0); PG8_STAGE(PG8_SA(0, 1), a2 + hstepA, voffA);
;             PG8_WAIT_V(8); PG8_WAIT_L(0); PG8_BAR; PG8_MMA(0, 0, At, B0); PG8_MMA(0, 1, At, B1); PG8_BAR; PG8_SCHED;
	s_mov_b32 m0, s68
	v_lshl_add_u64 v[246:247], s[42:43], 0, v[132:133]
	s_add_u32 s34, s42, 0x10000
	s_nop 0
	ds_read_b128 v[48:51], v139 offset:16384
	ds_read_b128 v[56:59], v139 offset:17408
	ds_read_b128 v[88:91], v139 offset:18432
	ds_read_b128 v[96:99], v139 offset:19456
	ds_read_b128 v[182:185], v139 offset:20480
	ds_read_b128 v[186:189], v139 offset:21504
	ds_read_b128 v[190:193], v139 offset:22528
	ds_read_b128 v[194:197], v139 offset:23552
	global_load_lds_dwordx4 v[246:247], off
	v_lshl_add_u64 v[248:249], s[42:43], 0, v[128:129]
	s_mov_b32 m0, s69
	s_addc_u32 s35, s43, 0
	global_load_lds_dwordx4 v[248:249], off
	v_lshl_add_u64 v[198:199], s[34:35], 0, v[132:133]
	s_mov_b32 m0, s70
	v_lshl_add_u64 v[250:251], s[46:47], 0, v[134:135]
	global_load_lds_dwordx4 v[198:199], off
	v_lshl_add_u64 v[198:199], s[34:35], 0, v[128:129]
	s_mov_b32 m0, s71
	v_lshl_add_u64 v[252:253], s[46:47], 0, v[130:131]
	global_load_lds_dwordx4 v[198:199], off
	s_mov_b32 m0, s53
	s_nop 0
	global_load_lds_dwordx4 v[250:251], off
	s_mov_b32 m0, s54
	s_nop 0
	global_load_lds_dwordx4 v[252:253], off
	s_waitcnt vmcnt(8)
	s_waitcnt lgkmcnt(0)
	s_barrier
	s_setprio 1
	v_mfma_f32_16x16x32_bf16 v[0:3], v[104:107], v[190:193], v[0:3]
	v_mfma_f32_16x16x32_bf16 v[4:7], v[112:115], v[190:193], v[4:7]
	v_mfma_f32_16x16x32_bf16 v[142:145], v[104:107], v[48:51], v[142:145]
	v_mfma_f32_16x16x32_bf16 v[146:149], v[112:115], v[48:51], v[146:149]
	v_mfma_f32_16x16x32_bf16 v[150:153], v[104:107], v[88:91], v[150:153]
	v_mfma_f32_16x16x32_bf16 v[154:157], v[112:115], v[88:91], v[154:157]
	v_mfma_f32_16x16x32_bf16 v[158:161], v[104:107], v[182:185], v[158:161]
	v_mfma_f32_16x16x32_bf16 v[162:165], v[112:115], v[182:185], v[162:165]
	v_mfma_f32_16x16x32_bf16 v[0:3], v[108:111], v[194:197], v[0:3]
	v_mfma_f32_16x16x32_bf16 v[4:7], v[116:119], v[194:197], v[4:7]
	v_mfma_f32_16x16x32_bf16 v[142:145], v[108:111], v[56:59], v[142:145]
	v_mfma_f32_16x16x32_bf16 v[146:149], v[116:119], v[56:59], v[146:149]
	v_mfma_f32_16x16x32_bf16 v[150:153], v[108:111], v[96:99], v[150:153]
	v_mfma_f32_16x16x32_bf16 v[154:157], v[116:119], v[96:99], v[154:157]
	v_mfma_f32_16x16x32_bf16 v[158:161], v[108:111], v[186:189], v[158:161]
	v_mfma_f32_16x16x32_bf16 v[162:165], v[116:119], v[186:189], v[162:165]
	s_setprio 0
	s_setprio 1
	v_mfma_f32_16x16x32_bf16 v[8:11], v[120:123], v[48:51], v[8:11]
	v_mfma_f32_16x16x32_bf16 v[198:201], v[124:127], v[56:59], v[8:11]
	v_mfma_f32_16x16x32_bf16 v[8:11], v[166:169], v[48:51], v[12:15]
	v_mfma_f32_16x16x32_bf16 v[12:15], v[170:173], v[56:59], v[8:11]
	v_mfma_f32_16x16x32_bf16 v[8:11], v[120:123], v[88:91], v[24:27]
	v_mfma_f32_16x16x32_bf16 v[202:205], v[124:127], v[96:99], v[8:11]
	v_mfma_f32_16x16x32_bf16 v[8:11], v[166:169], v[88:91], v[28:31]
	v_mfma_f32_16x16x32_bf16 v[28:31], v[170:173], v[96:99], v[8:11]
	v_mfma_f32_16x16x32_bf16 v[8:11], v[120:123], v[182:185], v[60:63]
	v_mfma_f32_16x16x32_bf16 v[214:217], v[124:127], v[186:189], v[8:11]
	v_mfma_f32_16x16x32_bf16 v[8:11], v[166:169], v[182:185], v[100:103]
	v_mfma_f32_16x16x32_bf16 v[182:185], v[170:173], v[186:189], v[8:11]
	v_mfma_f32_16x16x32_bf16 v[8:11], v[120:123], v[190:193], v[16:19]
	v_mfma_f32_16x16x32_bf16 v[186:189], v[124:127], v[194:197], v[8:11]
	v_mfma_f32_16x16x32_bf16 v[8:11], v[166:169], v[190:193], v[20:23]
	v_mfma_f32_16x16x32_bf16 v[166:169], v[170:173], v[194:197], v[8:11]
	s_setprio 0
	s_barrier
	s_nop 4
	ds_read_b128 v[8:11], v140
	ds_read_b128 v[20:23], v140 offset:1024
	ds_read_b128 v[170:173], v140 offset:2048
	ds_read_b128 v[190:193], v140 offset:3072
	ds_read_b128 v[194:197], v141
	ds_read_b128 v[218:221], v141 offset:1024
	ds_read_b128 v[222:225], v141 offset:2048
	ds_read_b128 v[226:229], v141 offset:3072
	s_add_u32 s34, s46, 0x10000
	s_addc_u32 s35, s47, 0
	s_mov_b32 m0, s55
	v_lshl_add_u64 v[48:49], s[34:35], 0, v[134:135]
	ds_read_b128 v[16:19], v139 offset:32768
	ds_read_b128 v[24:27], v139 offset:33792
	ds_read_b128 v[60:63], v139 offset:34816
	ds_read_b128 v[100:103], v139 offset:35840
	ds_read_b128 v[230:233], v139 offset:36864
	ds_read_b128 v[234:237], v139 offset:37888
	ds_read_b128 v[238:241], v139 offset:38912
	ds_read_b128 v[242:245], v139 offset:39936
	global_load_lds_dwordx4 v[48:49], off
	v_lshl_add_u64 v[48:49], s[34:35], 0, v[130:131]
	s_mov_b32 m0, s56
	s_nop 0
	global_load_lds_dwordx4 v[48:49], off
	s_waitcnt vmcnt(8)
	s_waitcnt lgkmcnt(0)
	s_barrier
; #define PG8_STAGE(bufoff, gbase, voff) do { _Pragma("unroll") for (int _i = 0; _i < 2; ++_i) \
;         __builtin_amdgcn_global_load_lds((const unsigned*)((const char*)(gbase) + (voff)[_i]), (LAS unsigned*)(lds + (bufoff) + ldsw + _i * 8192), 16, 0, 0); } while (0)
; #define PG8_LDA(dst, b, h) do { _Pragma("unroll") for (int m = 0; m < 4; ++m) _Pragma("unroll") for (int k = 0; k < 2; ++k) dst[m][k] = *(const LAS bf16x8*)(lds + PG8_SA(b, h) + aoff + m * 2048 + k * 1024); } while (0)
; #define PG8_LDB(dst, b, h) do { _Pragma("unroll") for (int n = 0; n < 2; ++n) _Pragma("unroll") for (int k = 0; k < 2; ++k) dst[n][k] = *(const LAS bf16x8*)(lds + PG8_SB(b, h) + boff + n * 2048 + k * 1024); } while (0)
; #define PG8_MMA(ai, bj, At, Bt) do { __builtin_amdgcn_s_setprio(1); _Pragma("unroll") for (int m = 0; m < 4; ++m) _Pragma("unroll") for (int n = 0; n < 2; ++n) _Pragma("unroll") for (int k = 0; k < 2; ++k) \
;         acc[ai][bj][m][n] = __builtin_amdgcn_mfma_f32_16x16x32_bf16(Bt[n][k], At[m][k], acc[ai][bj][m][n], 0, 0, 0); __builtin_amdgcn_s_setprio(0); } while (0)
; #define PG8_WAIT_V(n) asm volatile("s_waitcnt vmcnt(" #n ")" ::: "memory")
; #define PG8_WAIT_L(n) asm volatile("s_waitcnt lgkmcnt(" #n ")" ::: "memory")
; #define PG8_BAR __builtin_amdgcn_s_barrier()
; #define PG8_SCHED __builtin_amdgcn_sched_barrier(0)
; template <class Epi, class Sched, bool ALIGN_EPI = false, bool SP2 = false, bool TWOA = false, bool AGM = false>
; __device__ __forceinline__ void gemm_phase(LAS unsigned char* lds, const Gemm g, const Sched& S, const Epi& E, int wid) {
;     ...
;             PG8_LDB(B0, 1, 0); PG8_LDB(B1, 1, 1); PG8_SCHED; PG8_LDA(At, 1, 0); PG8_STAGE(PG8_SA(0, 1), a2 + hstepA, voffA);
;             PG8_WAIT_V(8); PG8_WAIT_L(0); PG8_BAR; PG8_MMA(0, 0, At, B0); PG8_MMA(0, 1, At, B1); PG8_BAR; PG8_SCHED;
;             PG8_LDA(At, 1, 1); PG8_STAGE(PG8_SB(1, 0), b3, voffB); PG8_STAGE(PG8_SB(1, 1), b3 + hstep, voffB); PG8_STAGE(PG8_SA(1, 0), a3, voffA);
;             PG8_WAIT_V(8); PG8_WAIT_L(0); PG8_BAR; PG8_MMA(1, 0, At, B0); PG8_MMA(1, 1, At, B1); PG8_BAR; PG8_SCHED;
;     ...
;         if constexpr (ALIGN_EPI) { if (wr == 0) PG8_BAR; }
;         if constexpr (!Epi::AFTER_DRAIN) { E(acc, cur, wr, wc, fr, fq); S.done(cur); }
;         if (!has_next) break;
	s_setprio 1
	v_mfma_f32_16x16x32_bf16 v[48:51], v[8:11], v[16:19], v[64:67]
	v_mfma_f32_16x16x32_bf16 v[120:123], v[20:23], v[24:27], v[48:51]
	v_mfma_f32_16x16x32_bf16 v[48:51], v[170:173], v[16:19], v[68:71]
	v_mfma_f32_16x16x32_bf16 v[112:115], v[190:193], v[24:27], v[48:51]
	v_mfma_f32_16x16x32_bf16 v[48:51], v[8:11], v[60:63], v[72:75]
	v_mfma_f32_16x16x32_bf16 v[104:107], v[20:23], v[100:103], v[48:51]
	v_mfma_f32_16x16x32_bf16 v[48:51], v[170:173], v[60:63], v[76:79]
	v_mfma_f32_16x16x32_bf16 v[96:99], v[190:193], v[100:103], v[48:51]
	v_mfma_f32_16x16x32_bf16 v[48:51], v[8:11], v[230:233], v[80:83]
	v_mfma_f32_16x16x32_bf16 v[88:91], v[20:23], v[234:237], v[48:51]
	v_mfma_f32_16x16x32_bf16 v[48:51], v[170:173], v[230:233], v[84:87]
	v_mfma_f32_16x16x32_bf16 v[80:83], v[190:193], v[234:237], v[48:51]
	v_mfma_f32_16x16x32_bf16 v[48:51], v[8:11], v[238:241], v[206:209]
	v_mfma_f32_16x16x32_bf16 v[56:59], v[20:23], v[242:245], v[48:51]
	v_mfma_f32_16x16x32_bf16 v[48:51], v[170:173], v[238:241], v[92:95]
	v_mfma_f32_16x16x32_bf16 v[48:51], v[190:193], v[242:245], v[48:51]
	s_setprio 0
	s_setprio 1
	v_mfma_f32_16x16x32_bf16 v[64:67], v[194:197], v[16:19], v[210:213]
	v_mfma_f32_16x16x32_bf16 v[16:19], v[222:225], v[16:19], v[32:35]
	v_mfma_f32_16x16x32_bf16 v[116:119], v[226:229], v[24:27], v[16:19]
	v_mfma_f32_16x16x32_bf16 v[16:19], v[194:197], v[60:63], v[36:39]
	v_mfma_f32_16x16x32_bf16 v[108:111], v[218:221], v[100:103], v[16:19]
	v_mfma_f32_16x16x32_bf16 v[16:19], v[222:225], v[60:63], v[40:43]
	v_mfma_f32_16x16x32_bf16 v[100:103], v[226:229], v[100:103], v[16:19]
	v_mfma_f32_16x16x32_bf16 v[16:19], v[194:197], v[230:233], v[44:47]
	v_mfma_f32_16x16x32_bf16 v[92:95], v[218:221], v[234:237], v[16:19]
	v_mfma_f32_16x16x32_bf16 v[16:19], v[222:225], v[230:233], v[174:177]
	v_mfma_f32_16x16x32_bf16 v[84:87], v[226:229], v[234:237], v[16:19]
	v_mfma_f32_16x16x32_bf16 v[16:19], v[194:197], v[238:241], v[52:55]
	v_mfma_f32_16x16x32_bf16 v[60:63], v[218:221], v[242:245], v[16:19]
	v_mfma_f32_16x16x32_bf16 v[16:19], v[222:225], v[238:241], v[178:181]
	v_mfma_f32_16x16x32_bf16 v[124:127], v[218:221], v[24:27], v[64:67]
	v_mfma_f32_16x16x32_bf16 v[52:55], v[226:229], v[242:245], v[16:19]
	s_setprio 0
	s_barrier
	s_mov_b32 m0, s72
	s_nop 2
	v_lshl_add_u64 v[16:17], v[246:247], 0, s[12:13]
	s_add_u32 s34, s42, 0x10080
	ds_read_b128 v[36:39], v139 offset:49152
	ds_read_b128 v[44:47], v139 offset:50176
	ds_read_b128 v[174:177], v139 offset:51200
	ds_read_b128 v[178:181], v139 offset:52224
	ds_read_b128 v[206:209], v139 offset:53248
	ds_read_b128 v[210:213], v139 offset:54272
	ds_read_b128 v[230:233], v139 offset:55296
	ds_read_b128 v[234:237], v139 offset:56320
	global_load_lds_dwordx4 v[16:17], off
	v_lshl_add_u64 v[16:17], v[248:249], 0, s[12:13]
	s_mov_b32 m0, s73
	s_addc_u32 s35, s43, 0
	global_load_lds_dwordx4 v[16:17], off
	v_lshl_add_u64 v[16:17], s[34:35], 0, v[132:133]
	s_mov_b32 m0, s74
	s_nop 0
	global_load_lds_dwordx4 v[16:17], off
	v_lshl_add_u64 v[16:17], s[34:35], 0, v[128:129]
	s_mov_b32 m0, s75
	s_nop 0
	global_load_lds_dwordx4 v[16:17], off
	v_lshl_add_u64 v[16:17], v[250:251], 0, s[12:13]
	s_mov_b32 m0, s57
	s_nop 0
	global_load_lds_dwordx4 v[16:17], off
	v_lshl_add_u64 v[16:17], v[252:253], 0, s[12:13]
	s_mov_b32 m0, s64
	s_nop 0
	global_load_lds_dwordx4 v[16:17], off
	s_waitcnt vmcnt(8)
	s_waitcnt lgkmcnt(0)
	s_barrier
	s_setprio 1
	v_mfma_f32_16x16x32_bf16 v[16:19], v[8:11], v[36:39], v[142:145]
	v_mfma_f32_16x16x32_bf16 v[72:75], v[20:23], v[44:47], v[16:19]
	v_mfma_f32_16x16x32_bf16 v[16:19], v[170:173], v[36:39], v[146:149]
	v_mfma_f32_16x16x32_bf16 v[64:67], v[190:193], v[44:47], v[16:19]
	v_mfma_f32_16x16x32_bf16 v[16:19], v[8:11], v[174:177], v[150:153]
	v_mfma_f32_16x16x32_bf16 v[40:43], v[20:23], v[178:181], v[16:19]
	v_mfma_f32_16x16x32_bf16 v[16:19], v[170:173], v[174:177], v[154:157]
	v_mfma_f32_16x16x32_bf16 v[32:35], v[190:193], v[178:181], v[16:19]
	v_mfma_f32_16x16x32_bf16 v[16:19], v[8:11], v[206:209], v[158:161]
	v_mfma_f32_16x16x32_bf16 v[0:3], v[8:11], v[230:233], v[0:3]
	v_mfma_f32_16x16x32_bf16 v[24:27], v[20:23], v[210:213], v[16:19]
	v_mfma_f32_16x16x32_bf16 v[16:19], v[170:173], v[206:209], v[162:165]
	v_mfma_f32_16x16x32_bf16 v[8:11], v[20:23], v[234:237], v[0:3]
	v_mfma_f32_16x16x32_bf16 v[0:3], v[170:173], v[230:233], v[4:7]
	v_mfma_f32_16x16x32_bf16 v[16:19], v[190:193], v[210:213], v[16:19]
	v_mfma_f32_16x16x32_bf16 v[0:3], v[190:193], v[234:237], v[0:3]
	s_setprio 0
	s_setprio 1
	v_mfma_f32_16x16x32_bf16 v[4:7], v[194:197], v[36:39], v[198:201]
	v_mfma_f32_16x16x32_bf16 v[76:79], v[218:221], v[44:47], v[4:7]
	v_mfma_f32_16x16x32_bf16 v[4:7], v[222:225], v[36:39], v[12:15]
	v_mfma_f32_16x16x32_bf16 v[68:71], v[226:229], v[44:47], v[4:7]
	v_mfma_f32_16x16x32_bf16 v[4:7], v[194:197], v[174:177], v[202:205]
	v_mfma_f32_16x16x32_bf16 v[44:47], v[218:221], v[178:181], v[4:7]
	v_mfma_f32_16x16x32_bf16 v[4:7], v[222:225], v[174:177], v[28:31]
	v_mfma_f32_16x16x32_bf16 v[36:39], v[226:229], v[178:181], v[4:7]
	v_mfma_f32_16x16x32_bf16 v[4:7], v[194:197], v[206:209], v[214:217]
	v_mfma_f32_16x16x32_bf16 v[28:31], v[218:221], v[210:213], v[4:7]
	v_mfma_f32_16x16x32_bf16 v[4:7], v[222:225], v[206:209], v[182:185]
	v_mfma_f32_16x16x32_bf16 v[20:23], v[226:229], v[210:213], v[4:7]
	v_mfma_f32_16x16x32_bf16 v[4:7], v[194:197], v[230:233], v[186:189]
	v_mfma_f32_16x16x32_bf16 v[12:15], v[218:221], v[234:237], v[4:7]
	v_mfma_f32_16x16x32_bf16 v[4:7], v[222:225], v[230:233], v[166:169]
	v_mfma_f32_16x16x32_bf16 v[4:7], v[226:229], v[234:237], v[4:7]
	s_setprio 0
	s_barrier
	s_and_b64 vcc, exec, s[4:5]
	s_cbranch_vccnz .LBB0_525
	s_barrier

; #define PG8_STAGE(bufoff, gbase, voff) do { _Pragma("unroll") for (int _i = 0; _i < 2; ++_i) \
;         __builtin_amdgcn_global_load_lds((const unsigned*)((const char*)(gbase) + (voff)[_i]), (LAS unsigned*)(lds + (bufoff) + ldsw + _i * 8192), 16, 0, 0); } while (0)
; #define PG8_LDA(dst, b, h) do { _Pragma("unroll") for (int m = 0; m < 4; ++m) _Pragma("unroll") for (int k = 0; k < 2; ++k) dst[m][k] = *(const LAS bf16x8*)(lds + PG8_SA(b, h) + aoff + m * 2048 + k * 1024); } while (0)
; #define PG8_LDB(dst, b, h) do { _Pragma("unroll") for (int n = 0; n < 2; ++n) _Pragma("unroll") for (int k = 0; k < 2; ++k) dst[n][k] = *(const LAS bf16x8*)(lds + PG8_SB(b, h) + boff + n * 2048 + k * 1024); } while (0)
; template <class Epi, class Sched, bool ALIGN_EPI = false, bool SP2 = false, bool TWOA = false, bool AGM = false>
; __device__ __forceinline__ void gemm_phase(LAS unsigned char* lds, const Gemm g, const Sched& S, const Epi& E, int wid) {
;     ...
;         const char* nA = has_next ? (const char*)g.A + (size_t)nxt.pm * tstepA : cA; const char* nB = has_next ? (const char*)g.Bt + (size_t)nxt.pn * tstep : cB;
;         for (int t = 0; t < nt; t += 2) {
;             const bool last = (t == nt - 2);
;             const char* cA2 = TWOA ? (const char*)g.A2 + (cA - (const char*)g.A) - (size_t)nh * kstepA : cA;
;             const char* a1_ = (TWOA && t + 1 >= nh ? cA2 : cA) + (size_t)(t + 1) * kstepA;
;             const char* a2_ = last ? nA : (TWOA && t + 2 >= nh ? cA2 : cA) + (size_t)(t + 2) * kstepA; const char* a1 = a1_; const char* a2 = a2_; const char* b2 = last ? nB : cB + (size_t)(t + 2) * kstep;
;             if constexpr (TWOA) { asm volatile("" : "+s"(a1)); asm volatile("" : "+s"(a2)); }
;             const char* a3 = a2 + kstepA; const char* b3 = b2 + kstep;
;             if (last && has_next) S.a_ready(nxt);
;             if constexpr (has_mid<Epi>::value) { if (t == nh) E.mid(acc, cur, wr, wc, fr, fq); }
;             if constexpr (SP2) {
;             PG8_LDB(B0, 0, 0); PG8_LDB(B1, 0, 1); PG8_SCHED; PG8_LDA(At, 0, 0); PG8_STAGE(PG8_SA(1, 1), a1 + hstepA, voffA);
;             PG8_WAIT_V(8); PG8_WAIT_L(0); PG8_BAR; PG8_MMA(0, 0, At, B0); PG8_MMA(0, 1, At, B1); PG8_BAR; PG8_SCHED;
;             PG8_LDA(At, 0, 1); PG8_STAGE(PG8_SB(0, 0), b2, voffB); PG8_STAGE(PG8_SB(0, 1), b2 + hstep, voffB); PG8_STAGE(PG8_SA(0, 0), a2, voffA);
.LBB0_682:
	s_ashr_i32 s37, s36, 31
	s_lshl_b64 s[34:35], s[36:37], 17
	s_add_u32 s38, s8, s34
	s_addc_u32 s39, s9, s35
	s_and_b64 s[34:35], s[42:43], exec
	s_cselect_b32 s37, s39, s55
	s_cselect_b32 s80, s38, s54
	s_ashr_i32 s31, s30, 31
	s_lshl_b64 s[34:35], s[30:31], 18
	s_add_u32 s40, s68, s34
	s_addc_u32 s41, s69, s35
	s_and_b64 s[34:35], s[42:43], exec
	s_cselect_b32 s31, s41, s53
	s_cselect_b32 s82, s40, s52
	s_sub_u32 s34, s54, s8
	s_subb_u32 s35, s55, s9
	s_add_u32 s50, s72, s34
	s_addc_u32 s51, s73, s35
	s_add_u32 s34, s54, 0x80
	s_addc_u32 s35, s55, 0
	s_add_u32 s56, s54, 0x100
	s_addc_u32 s57, s55, 0
	ds_read_b128 v[4:7], v157
	ds_read_b128 v[8:11], v157 offset:1024
	ds_read_b128 v[12:15], v157 offset:2048
	ds_read_b128 v[16:19], v157 offset:3072
	ds_read_b128 v[20:23], v158
	ds_read_b128 v[24:27], v158 offset:1024
	ds_read_b128 v[28:31], v158 offset:2048
	ds_read_b128 v[32:35], v158 offset:3072
	s_add_u32 s34, s34, 0x10000
	s_addc_u32 s35, s35, 0
	s_add_i32 s83, s45, 0xc000
	v_lshl_add_u64 v[64:65], s[34:35], 0, v[134:135]
	s_mov_b32 m0, s83
	s_add_i32 s84, s45, 0xe000
	ds_read_b128 v[0:3], v137
	ds_read_b128 v[36:39], v137 offset:1024
	ds_read_b128 v[40:43], v137 offset:2048
	ds_read_b128 v[44:47], v137 offset:3072
	ds_read_b128 v[48:51], v137 offset:4096
	ds_read_b128 v[52:55], v137 offset:5120
	ds_read_b128 v[56:59], v137 offset:6144
	ds_read_b128 v[60:63], v137 offset:7168
	global_load_lds_dwordx4 v[64:65], off
	v_lshl_add_u64 v[64:65], s[34:35], 0, v[130:131]
	s_mov_b32 m0, s84
	s_nop 0
	global_load_lds_dwordx4 v[64:65], off
	s_waitcnt vmcnt(8)
	s_waitcnt lgkmcnt(0)
	s_barrier
	s_setprio 1
	v_mfma_f32_16x16x32_bf16 v[64:67], v[4:7], v[0:3], 0
	v_mfma_f32_16x16x32_bf16 v[68:71], v[12:15], v[0:3], 0
	v_mfma_f32_16x16x32_bf16 v[72:75], v[4:7], v[40:43], 0
	v_mfma_f32_16x16x32_bf16 v[76:79], v[12:15], v[40:43], 0
	v_mfma_f32_16x16x32_bf16 v[80:83], v[4:7], v[48:51], 0
	v_mfma_f32_16x16x32_bf16 v[84:87], v[12:15], v[48:51], 0
	v_mfma_f32_16x16x32_bf16 v[88:91], v[4:7], v[56:59], 0
	v_mfma_f32_16x16x32_bf16 v[92:95], v[12:15], v[56:59], 0
	v_mfma_f32_16x16x32_bf16 v[64:67], v[8:11], v[36:39], v[64:67]
	v_mfma_f32_16x16x32_bf16 v[68:71], v[16:19], v[36:39], v[68:71]
	v_mfma_f32_16x16x32_bf16 v[72:75], v[8:11], v[44:47], v[72:75]
	v_mfma_f32_16x16x32_bf16 v[76:79], v[16:19], v[44:47], v[76:79]
	v_mfma_f32_16x16x32_bf16 v[80:83], v[8:11], v[52:55], v[80:83]
	v_mfma_f32_16x16x32_bf16 v[84:87], v[16:19], v[52:55], v[84:87]
	v_mfma_f32_16x16x32_bf16 v[88:91], v[8:11], v[60:63], v[88:91]
	v_mfma_f32_16x16x32_bf16 v[92:95], v[16:19], v[60:63], v[92:95]
	s_setprio 0
	s_setprio 1
	v_mfma_f32_16x16x32_bf16 v[96:99], v[20:23], v[0:3], 0
	v_mfma_f32_16x16x32_bf16 v[0:3], v[28:31], v[0:3], 0
	v_mfma_f32_16x16x32_bf16 v[96:99], v[24:27], v[36:39], v[96:99]
	v_mfma_f32_16x16x32_bf16 v[36:39], v[32:35], v[36:39], v[0:3]
	v_mfma_f32_16x16x32_bf16 v[0:3], v[20:23], v[40:43], 0
	v_mfma_f32_16x16x32_bf16 v[100:103], v[24:27], v[44:47], v[0:3]
	v_mfma_f32_16x16x32_bf16 v[0:3], v[28:31], v[40:43], 0
	v_mfma_f32_16x16x32_bf16 v[40:43], v[32:35], v[44:47], v[0:3]
	v_mfma_f32_16x16x32_bf16 v[0:3], v[20:23], v[48:51], 0
	v_mfma_f32_16x16x32_bf16 v[44:47], v[24:27], v[52:55], v[0:3]
	v_mfma_f32_16x16x32_bf16 v[0:3], v[28:31], v[48:51], 0
	v_mfma_f32_16x16x32_bf16 v[48:51], v[32:35], v[52:55], v[0:3]
	v_mfma_f32_16x16x32_bf16 v[0:3], v[20:23], v[56:59], 0
	v_mfma_f32_16x16x32_bf16 v[52:55], v[24:27], v[60:63], v[0:3]
	v_mfma_f32_16x16x32_bf16 v[0:3], v[28:31], v[56:59], 0
	v_mfma_f32_16x16x32_bf16 v[56:59], v[32:35], v[60:63], v[0:3]
	s_setprio 0
	s_barrier
	s_nop 4
	v_lshl_add_u64 v[0:1], s[52:53], 0, v[132:133]
	s_add_i32 s85, s76, s3
	v_lshl_add_u64 v[2:3], v[0:1], 0, s[22:23]
	s_mov_b32 m0, s85
	s_add_i32 s86, s85, 0x2000
	ds_read_b128 v[60:63], v137 offset:16384
	ds_read_b128 v[104:107], v137 offset:17408
	ds_read_b128 v[108:111], v137 offset:18432
	ds_read_b128 v[112:115], v137 offset:19456
	ds_read_b128 v[116:119], v137 offset:20480
	ds_read_b128 v[120:123], v137 offset:21504
	ds_read_b128 v[124:127], v137 offset:22528
	ds_read_b128 v[160:163], v137 offset:23552
	global_load_lds_dwordx4 v[2:3], off
	v_lshl_add_u64 v[2:3], s[52:53], 0, v[128:129]
	s_add_u32 s34, s52, 0x20100
	v_lshl_add_u64 v[140:141], v[2:3], 0, s[22:23]
	s_mov_b32 m0, s86
	s_addc_u32 s35, s53, 0
	s_add_i32 s87, s77, s3
	global_load_lds_dwordx4 v[140:141], off
	v_lshl_add_u64 v[140:141], s[34:35], 0, v[132:133]
	s_mov_b32 m0, s87
	s_add_i32 s88, s87, 0x2000
	global_load_lds_dwordx4 v[140:141], off
	v_lshl_add_u64 v[140:141], s[34:35], 0, v[128:129]
	s_mov_b32 m0, s88
	v_lshl_add_u64 v[142:143], s[56:57], 0, v[130:131]
	global_load_lds_dwordx4 v[140:141], off
	v_lshl_add_u64 v[140:141], s[56:57], 0, v[134:135]
	s_mov_b32 m0, s45
	s_nop 0
	global_load_lds_dwordx4 v[140:141], off
	s_mov_b32 m0, s47
	s_nop 0
	global_load_lds_dwordx4 v[142:143], off
	s_waitcnt vmcnt(8)
	s_waitcnt lgkmcnt(0)
	s_barrier
; #define PG8_STAGE(bufoff, gbase, voff) do { _Pragma("unroll") for (int _i = 0; _i < 2; ++_i) \
;         __builtin_amdgcn_global_load_lds((const unsigned*)((const char*)(gbase) + (voff)[_i]), (LAS unsigned*)(lds + (bufoff) + ldsw + _i * 8192), 16, 0, 0); } while (0)
; #define PG8_LDA(dst, b, h) do { _Pragma("unroll") for (int m = 0; m < 4; ++m) _Pragma("unroll") for (int k = 0; k < 2; ++k) dst[m][k] = *(const LAS bf16x8*)(lds + PG8_SA(b, h) + aoff + m * 2048 + k * 1024); } while (0)
; #define PG8_LDB(dst, b, h) do { _Pragma("unroll") for (int n = 0; n < 2; ++n) _Pragma("unroll") for (int k = 0; k < 2; ++k) dst[n][k] = *(const LAS bf16x8*)(lds + PG8_SB(b, h) + boff + n * 2048 + k * 1024); } while (0)
; #define PG8_MMA(ai, bj, At, Bt) do { __builtin_amdgcn_s_setprio(1); _Pragma("unroll") for (int m = 0; m < 4; ++m) _Pragma("unroll") for (int n = 0; n < 2; ++n) _Pragma("unroll") for (int k = 0; k < 2; ++k) \
;         acc[ai][bj][m][n] = __builtin_amdgcn_mfma_f32_16x16x32_bf16(Bt[n][k], At[m][k], acc[ai][bj][m][n], 0, 0, 0); __builtin_amdgcn_s_setprio(0); } while (0)
; #define PG8_WAIT_V(n) asm volatile("s_waitcnt vmcnt(" #n ")" ::: "memory")
; #define PG8_WAIT_L(n) asm volatile("s_waitcnt lgkmcnt(" #n ")" ::: "memory")
; #define PG8_BAR __builtin_amdgcn_s_barrier()
; #define PG8_SCHED __builtin_amdgcn_sched_barrier(0)
; template <class Epi, class Sched, bool ALIGN_EPI = false, bool SP2 = false, bool TWOA = false, bool AGM = false>
; __device__ __forceinline__ void gemm_phase(LAS unsigned char* lds, const Gemm g, const Sched& S, const Epi& E, int wid) {
;     ...
;             PG8_LDA(At, 0, 1); PG8_STAGE(PG8_SB(0, 0), b2, voffB); PG8_STAGE(PG8_SB(0, 1), b2 + hstep, voffB); PG8_STAGE(PG8_SA(0, 0), a2, voffA);
;             PG8_WAIT_V(8); PG8_WAIT_L(0); PG8_BAR; PG8_MMA(1, 0, At, B0); PG8_MMA(1, 1, At, B1); PG8_BAR; PG8_SCHED;
;             PG8_LDB(B0, 1, 0); PG8_LDB(B1, 1, 1); PG8_SCHED; PG8_LDA(At, 1, 0); PG8_STAGE(PG8_SA(0, 1), a2 + hstepA, voffA);
;             PG8_WAIT_V(8); PG8_WAIT_L(0); PG8_BAR; PG8_MMA(0, 0, At, B0); PG8_MMA(0, 1, At, B1); PG8_BAR; PG8_SCHED;
;             PG8_LDA(At, 1, 1); PG8_STAGE(PG8_SB(1, 0), b3, voffB); PG8_STAGE(PG8_SB(1, 1), b3 + hstep, voffB); PG8_STAGE(PG8_SA(1, 0), a3, voffA);
	s_setprio 1
	v_mfma_f32_16x16x32_bf16 v[164:167], v[4:7], v[60:63], 0
	v_mfma_f32_16x16x32_bf16 v[172:175], v[4:7], v[108:111], 0
	v_mfma_f32_16x16x32_bf16 v[180:183], v[4:7], v[116:119], 0
	v_mfma_f32_16x16x32_bf16 v[4:7], v[4:7], v[124:127], 0
	v_mfma_f32_16x16x32_bf16 v[164:167], v[8:11], v[104:107], v[164:167]
	v_mfma_f32_16x16x32_bf16 v[172:175], v[8:11], v[112:115], v[172:175]
	v_mfma_f32_16x16x32_bf16 v[180:183], v[8:11], v[120:123], v[180:183]
	v_mfma_f32_16x16x32_bf16 v[4:7], v[8:11], v[160:163], v[4:7]
	v_mfma_f32_16x16x32_bf16 v[8:11], v[12:15], v[124:127], 0
	v_mfma_f32_16x16x32_bf16 v[168:171], v[12:15], v[60:63], 0
	v_mfma_f32_16x16x32_bf16 v[176:179], v[12:15], v[108:111], 0
	v_mfma_f32_16x16x32_bf16 v[184:187], v[12:15], v[116:119], 0
	v_mfma_f32_16x16x32_bf16 v[8:11], v[16:19], v[160:163], v[8:11]
	v_mfma_f32_16x16x32_bf16 v[168:171], v[16:19], v[104:107], v[168:171]
	v_mfma_f32_16x16x32_bf16 v[176:179], v[16:19], v[112:115], v[176:179]
	v_mfma_f32_16x16x32_bf16 v[184:187], v[16:19], v[120:123], v[184:187]
	s_setprio 0
	s_setprio 1
	v_mfma_f32_16x16x32_bf16 v[12:15], v[20:23], v[60:63], 0
	v_mfma_f32_16x16x32_bf16 v[16:19], v[28:31], v[60:63], 0
	v_mfma_f32_16x16x32_bf16 v[12:15], v[24:27], v[104:107], v[12:15]
	v_mfma_f32_16x16x32_bf16 v[16:19], v[32:35], v[104:107], v[16:19]
	v_mfma_f32_16x16x32_bf16 v[60:63], v[20:23], v[108:111], 0
	v_mfma_f32_16x16x32_bf16 v[104:107], v[28:31], v[108:111], 0
	v_mfma_f32_16x16x32_bf16 v[108:111], v[20:23], v[116:119], 0
	v_mfma_f32_16x16x32_bf16 v[20:23], v[20:23], v[124:127], 0
	v_mfma_f32_16x16x32_bf16 v[60:63], v[24:27], v[112:115], v[60:63]
	v_mfma_f32_16x16x32_bf16 v[104:107], v[32:35], v[112:115], v[104:107]
	v_mfma_f32_16x16x32_bf16 v[108:111], v[24:27], v[120:123], v[108:111]
	v_mfma_f32_16x16x32_bf16 v[112:115], v[28:31], v[116:119], 0
	v_mfma_f32_16x16x32_bf16 v[20:23], v[24:27], v[160:163], v[20:23]
	v_mfma_f32_16x16x32_bf16 v[24:27], v[28:31], v[124:127], 0
	v_mfma_f32_16x16x32_bf16 v[112:115], v[32:35], v[120:123], v[112:115]
	v_mfma_f32_16x16x32_bf16 v[24:27], v[32:35], v[160:163], v[24:27]
	s_setprio 0
	s_barrier
	s_add_i32 s89, 0, 0x18000
	s_add_i32 s90, 0, 0x1c000
	v_add_u32_e32 v159, s89, v136
	v_add_u32_e32 v160, s90, v136
	ds_read_b128 v[28:31], v159
	ds_read_b128 v[32:35], v159 offset:1024
	ds_read_b128 v[116:119], v159 offset:2048
	ds_read_b128 v[120:123], v159 offset:3072
	ds_read_b128 v[124:127], v160
	ds_read_b128 v[188:191], v160 offset:1024
	ds_read_b128 v[192:195], v160 offset:2048
	ds_read_b128 v[196:199], v160 offset:3072
	s_add_u32 s34, s56, 0x10000
	s_addc_u32 s35, s57, 0
	s_mov_b32 m0, s70
	v_lshl_add_u64 v[144:145], s[34:35], 0, v[134:135]
	ds_read_b128 v[200:203], v137 offset:32768
	ds_read_b128 v[204:207], v137 offset:33792
	ds_read_b128 v[208:211], v137 offset:34816
	ds_read_b128 v[212:215], v137 offset:35840
	ds_read_b128 v[216:219], v137 offset:36864
	ds_read_b128 v[220:223], v137 offset:37888
	ds_read_b128 v[224:227], v137 offset:38912
	ds_read_b128 v[228:231], v137 offset:39936
	global_load_lds_dwordx4 v[144:145], off
	v_lshl_add_u64 v[144:145], s[34:35], 0, v[130:131]
	s_mov_b32 m0, s71
	s_nop 0
	global_load_lds_dwordx4 v[144:145], off
	s_waitcnt vmcnt(8)
	s_waitcnt lgkmcnt(0)
	s_barrier
	s_setprio 1
	v_mfma_f32_16x16x32_bf16 v[64:67], v[28:31], v[200:203], v[64:67]
	v_mfma_f32_16x16x32_bf16 v[68:71], v[116:119], v[200:203], v[68:71]
	v_mfma_f32_16x16x32_bf16 v[72:75], v[28:31], v[208:211], v[72:75]
	v_mfma_f32_16x16x32_bf16 v[76:79], v[116:119], v[208:211], v[76:79]
	v_mfma_f32_16x16x32_bf16 v[80:83], v[28:31], v[216:219], v[80:83]
	v_mfma_f32_16x16x32_bf16 v[84:87], v[116:119], v[216:219], v[84:87]
	v_mfma_f32_16x16x32_bf16 v[88:91], v[28:31], v[224:227], v[88:91]
	v_mfma_f32_16x16x32_bf16 v[92:95], v[116:119], v[224:227], v[92:95]
	v_mfma_f32_16x16x32_bf16 v[64:67], v[32:35], v[204:207], v[64:67]
	v_mfma_f32_16x16x32_bf16 v[68:71], v[120:123], v[204:207], v[68:71]
	v_mfma_f32_16x16x32_bf16 v[72:75], v[32:35], v[212:215], v[72:75]
	v_mfma_f32_16x16x32_bf16 v[76:79], v[120:123], v[212:215], v[76:79]
	v_mfma_f32_16x16x32_bf16 v[80:83], v[32:35], v[220:223], v[80:83]
	v_mfma_f32_16x16x32_bf16 v[84:87], v[120:123], v[220:223], v[84:87]
	v_mfma_f32_16x16x32_bf16 v[88:91], v[32:35], v[228:231], v[88:91]
	v_mfma_f32_16x16x32_bf16 v[92:95], v[120:123], v[228:231], v[92:95]
	s_setprio 0
	s_setprio 1
	v_mfma_f32_16x16x32_bf16 v[96:99], v[124:127], v[200:203], v[96:99]
	v_mfma_f32_16x16x32_bf16 v[36:39], v[192:195], v[200:203], v[36:39]
	v_mfma_f32_16x16x32_bf16 v[100:103], v[124:127], v[208:211], v[100:103]
	v_mfma_f32_16x16x32_bf16 v[40:43], v[192:195], v[208:211], v[40:43]
	v_mfma_f32_16x16x32_bf16 v[44:47], v[124:127], v[216:219], v[44:47]
	v_mfma_f32_16x16x32_bf16 v[48:51], v[192:195], v[216:219], v[48:51]
	v_mfma_f32_16x16x32_bf16 v[52:55], v[124:127], v[224:227], v[52:55]
	v_mfma_f32_16x16x32_bf16 v[56:59], v[192:195], v[224:227], v[56:59]
	v_mfma_f32_16x16x32_bf16 v[96:99], v[188:191], v[204:207], v[96:99]
	v_mfma_f32_16x16x32_bf16 v[36:39], v[196:199], v[204:207], v[36:39]
	v_mfma_f32_16x16x32_bf16 v[100:103], v[188:191], v[212:215], v[100:103]
	v_mfma_f32_16x16x32_bf16 v[40:43], v[196:199], v[212:215], v[40:43]
	v_mfma_f32_16x16x32_bf16 v[44:47], v[188:191], v[220:223], v[44:47]
	v_mfma_f32_16x16x32_bf16 v[48:51], v[196:199], v[220:223], v[48:51]
	v_mfma_f32_16x16x32_bf16 v[52:55], v[188:191], v[228:231], v[52:55]
	v_mfma_f32_16x16x32_bf16 v[56:59], v[196:199], v[228:231], v[56:59]
	s_setprio 0
	s_barrier
; #define PG8_STAGE(bufoff, gbase, voff) do { _Pragma("unroll") for (int _i = 0; _i < 2; ++_i) \
;         __builtin_amdgcn_global_load_lds((const unsigned*)((const char*)(gbase) + (voff)[_i]), (LAS unsigned*)(lds + (bufoff) + ldsw + _i * 8192), 16, 0, 0); } while (0)
; #define PG8_LDA(dst, b, h) do { _Pragma("unroll") for (int m = 0; m < 4; ++m) _Pragma("unroll") for (int k = 0; k < 2; ++k) dst[m][k] = *(const LAS bf16x8*)(lds + PG8_SA(b, h) + aoff + m * 2048 + k * 1024); } while (0)
; #define PG8_LDB(dst, b, h) do { _Pragma("unroll") for (int n = 0; n < 2; ++n) _Pragma("unroll") for (int k = 0; k < 2; ++k) dst[n][k] = *(const LAS bf16x8*)(lds + PG8_SB(b, h) + boff + n * 2048 + k * 1024); } while (0)
; #define PG8_MMA(ai, bj, At, Bt) do { __builtin_amdgcn_s_setprio(1); _Pragma("unroll") for (int m = 0; m < 4; ++m) _Pragma("unroll") for (int n = 0; n < 2; ++n) _Pragma("unroll") for (int k = 0; k < 2; ++k) \
;         acc[ai][bj][m][n] = __builtin_amdgcn_mfma_f32_16x16x32_bf16(Bt[n][k], At[m][k], acc[ai][bj][m][n], 0, 0, 0); __builtin_amdgcn_s_setprio(0); } while (0)
; #define PG8_BAR __builtin_amdgcn_s_barrier()
; template <class Epi, class Sched, bool ALIGN_EPI = false, bool SP2 = false, bool TWOA = false, bool AGM = false>
; __device__ __forceinline__ void gemm_phase(LAS unsigned char* lds, const Gemm g, const Sched& S, const Epi& E, int wid) {
;     ...
;             PG8_LDB(B0, 0, 0); PG8_LDB(B1, 0, 1); PG8_SCHED; PG8_LDA(At, 0, 0); PG8_STAGE(PG8_SA(1, 1), a1 + hstepA, voffA);
;             PG8_WAIT_V(8); PG8_WAIT_L(0); PG8_BAR; PG8_MMA(0, 0, At, B0); PG8_MMA(0, 1, At, B1); PG8_BAR; PG8_SCHED;
;             PG8_LDA(At, 0, 1); PG8_STAGE(PG8_SB(0, 0), b2, voffB); PG8_STAGE(PG8_SB(0, 1), b2 + hstep, voffB); PG8_STAGE(PG8_SA(0, 0), a2, voffA);
;             PG8_WAIT_V(8); PG8_WAIT_L(0); PG8_BAR; PG8_MMA(1, 0, At, B0); PG8_MMA(1, 1, At, B1); PG8_BAR; PG8_SCHED;
;             PG8_LDB(B0, 1, 0); PG8_LDB(B1, 1, 1); PG8_SCHED; PG8_LDA(At, 1, 0); PG8_STAGE(PG8_SA(0, 1), a2 + hstepA, voffA);
;             PG8_WAIT_V(8); PG8_WAIT_L(0); PG8_BAR; PG8_MMA(0, 0, At, B0); PG8_MMA(0, 1, At, B1); PG8_BAR; PG8_SCHED;
;             PG8_LDA(At, 1, 1); PG8_STAGE(PG8_SB(1, 0), b3, voffB); PG8_STAGE(PG8_SB(1, 1), b3 + hstep, voffB); PG8_STAGE(PG8_SA(1, 0), a3, voffA);
;             PG8_WAIT_V(8); PG8_WAIT_L(0); PG8_BAR; PG8_MMA(1, 0, At, B0); PG8_MMA(1, 1, At, B1); PG8_BAR; PG8_SCHED;
	s_add_i32 s56, s89, s3
	s_add_i32 s57, s56, 0x2000
	v_lshl_add_u64 v[144:145], v[0:1], 0, s[24:25]
	s_mov_b32 m0, s56
	s_add_u32 s34, s52, 0x20180
	ds_read_b128 v[200:203], v137 offset:49152
	ds_read_b128 v[204:207], v137 offset:50176
	ds_read_b128 v[208:211], v137 offset:51200
	ds_read_b128 v[212:215], v137 offset:52224
	ds_read_b128 v[216:219], v137 offset:53248
	ds_read_b128 v[220:223], v137 offset:54272
	ds_read_b128 v[224:227], v137 offset:55296
	ds_read_b128 v[228:231], v137 offset:56320
	global_load_lds_dwordx4 v[144:145], off
	v_lshl_add_u64 v[144:145], v[2:3], 0, s[24:25]
	s_mov_b32 m0, s57
	s_addc_u32 s35, s53, 0
	s_add_i32 s89, s90, s3
	global_load_lds_dwordx4 v[144:145], off
	v_lshl_add_u64 v[144:145], s[34:35], 0, v[132:133]
	s_mov_b32 m0, s89
	s_add_i32 s90, s89, 0x2000
	global_load_lds_dwordx4 v[144:145], off
	v_lshl_add_u64 v[144:145], s[34:35], 0, v[128:129]
	s_mov_b32 m0, s90
	v_lshl_add_u64 v[140:141], v[140:141], 0, s[12:13]
	global_load_lds_dwordx4 v[144:145], off
	s_mov_b32 m0, s74
	s_nop 0
	global_load_lds_dwordx4 v[140:141], off
	v_lshl_add_u64 v[140:141], v[142:143], 0, s[12:13]
	s_mov_b32 m0, s75
	s_nop 0
	global_load_lds_dwordx4 v[140:141], off
	s_waitcnt vmcnt(8)
	s_waitcnt lgkmcnt(0)
	s_barrier
	s_setprio 1
	v_mfma_f32_16x16x32_bf16 v[4:7], v[28:31], v[224:227], v[4:7]
	v_mfma_f32_16x16x32_bf16 v[8:11], v[116:119], v[224:227], v[8:11]
	v_mfma_f32_16x16x32_bf16 v[162:165], v[28:31], v[200:203], v[164:167]
	v_mfma_f32_16x16x32_bf16 v[166:169], v[116:119], v[200:203], v[168:171]
	v_mfma_f32_16x16x32_bf16 v[170:173], v[28:31], v[208:211], v[172:175]
	v_mfma_f32_16x16x32_bf16 v[174:177], v[116:119], v[208:211], v[176:179]
	v_mfma_f32_16x16x32_bf16 v[178:181], v[28:31], v[216:219], v[180:183]
	v_mfma_f32_16x16x32_bf16 v[182:185], v[116:119], v[216:219], v[184:187]
	v_mfma_f32_16x16x32_bf16 v[4:7], v[32:35], v[228:231], v[4:7]
	v_mfma_f32_16x16x32_bf16 v[8:11], v[120:123], v[228:231], v[8:11]
	v_mfma_f32_16x16x32_bf16 v[162:165], v[32:35], v[204:207], v[162:165]
	v_mfma_f32_16x16x32_bf16 v[166:169], v[120:123], v[204:207], v[166:169]
	v_mfma_f32_16x16x32_bf16 v[170:173], v[32:35], v[212:215], v[170:173]
	v_mfma_f32_16x16x32_bf16 v[174:177], v[120:123], v[212:215], v[174:177]
	v_mfma_f32_16x16x32_bf16 v[178:181], v[32:35], v[220:223], v[178:181]
	v_mfma_f32_16x16x32_bf16 v[182:185], v[120:123], v[220:223], v[182:185]
	s_setprio 0
	s_setprio 1
	v_mfma_f32_16x16x32_bf16 v[12:15], v[124:127], v[200:203], v[12:15]
	v_mfma_f32_16x16x32_bf16 v[16:19], v[192:195], v[200:203], v[16:19]
	v_mfma_f32_16x16x32_bf16 v[28:31], v[124:127], v[208:211], v[60:63]
	v_mfma_f32_16x16x32_bf16 v[32:35], v[192:195], v[208:211], v[104:107]
	v_mfma_f32_16x16x32_bf16 v[60:63], v[124:127], v[216:219], v[108:111]
	v_mfma_f32_16x16x32_bf16 v[104:107], v[192:195], v[216:219], v[112:115]
	v_mfma_f32_16x16x32_bf16 v[20:23], v[124:127], v[224:227], v[20:23]
	v_mfma_f32_16x16x32_bf16 v[24:27], v[192:195], v[224:227], v[24:27]
	v_mfma_f32_16x16x32_bf16 v[12:15], v[188:191], v[204:207], v[12:15]
	v_mfma_f32_16x16x32_bf16 v[16:19], v[196:199], v[204:207], v[16:19]
	v_mfma_f32_16x16x32_bf16 v[28:31], v[188:191], v[212:215], v[28:31]
	v_mfma_f32_16x16x32_bf16 v[32:35], v[196:199], v[212:215], v[32:35]
	v_mfma_f32_16x16x32_bf16 v[60:63], v[188:191], v[220:223], v[60:63]
	v_mfma_f32_16x16x32_bf16 v[104:107], v[196:199], v[220:223], v[104:107]
	v_mfma_f32_16x16x32_bf16 v[20:23], v[188:191], v[228:231], v[20:23]
	v_mfma_f32_16x16x32_bf16 v[24:27], v[196:199], v[228:231], v[24:27]
	s_setprio 0
	s_barrier
	s_add_u32 s34, s54, 0x180
	s_addc_u32 s35, s55, 0
	s_mov_b64 s[54:55], s[50:51]
	ds_read_b128 v[108:111], v157
	ds_read_b128 v[112:115], v157 offset:1024
	ds_read_b128 v[116:119], v157 offset:2048
	ds_read_b128 v[120:123], v157 offset:3072
	ds_read_b128 v[124:127], v158
	ds_read_b128 v[186:189], v158 offset:1024
	ds_read_b128 v[190:193], v158 offset:2048
	ds_read_b128 v[194:197], v158 offset:3072
	s_add_u32 s34, s34, 0x10000
	s_addc_u32 s35, s35, 0
	s_mov_b32 m0, s83
	v_lshl_add_u64 v[140:141], s[34:35], 0, v[134:135]
	ds_read_b128 v[198:201], v137
	ds_read_b128 v[202:205], v137 offset:1024
	ds_read_b128 v[206:209], v137 offset:2048
	ds_read_b128 v[210:213], v137 offset:3072
	ds_read_b128 v[214:217], v137 offset:4096
	ds_read_b128 v[218:221], v137 offset:5120
	ds_read_b128 v[222:225], v137 offset:6144
	ds_read_b128 v[226:229], v137 offset:7168
	global_load_lds_dwordx4 v[140:141], off
	v_lshl_add_u64 v[140:141], s[34:35], 0, v[130:131]
	s_mov_b32 m0, s84
	s_nop 0
	global_load_lds_dwordx4 v[140:141], off
	s_waitcnt vmcnt(8)
	s_waitcnt lgkmcnt(0)
	s_barrier
; #define PG8_STAGE(bufoff, gbase, voff) do { _Pragma("unroll") for (int _i = 0; _i < 2; ++_i) \
;         __builtin_amdgcn_global_load_lds((const unsigned*)((const char*)(gbase) + (voff)[_i]), (LAS unsigned*)(lds + (bufoff) + ldsw + _i * 8192), 16, 0, 0); } while (0)
; #define PG8_LDA(dst, b, h) do { _Pragma("unroll") for (int m = 0; m < 4; ++m) _Pragma("unroll") for (int k = 0; k < 2; ++k) dst[m][k] = *(const LAS bf16x8*)(lds + PG8_SA(b, h) + aoff + m * 2048 + k * 1024); } while (0)
; #define PG8_LDB(dst, b, h) do { _Pragma("unroll") for (int n = 0; n < 2; ++n) _Pragma("unroll") for (int k = 0; k < 2; ++k) dst[n][k] = *(const LAS bf16x8*)(lds + PG8_SB(b, h) + boff + n * 2048 + k * 1024); } while (0)
; #define PG8_MMA(ai, bj, At, Bt) do { __builtin_amdgcn_s_setprio(1); _Pragma("unroll") for (int m = 0; m < 4; ++m) _Pragma("unroll") for (int n = 0; n < 2; ++n) _Pragma("unroll") for (int k = 0; k < 2; ++k) \
;         acc[ai][bj][m][n] = __builtin_amdgcn_mfma_f32_16x16x32_bf16(Bt[n][k], At[m][k], acc[ai][bj][m][n], 0, 0, 0); __builtin_amdgcn_s_setprio(0); } while (0)
; #define PG8_WAIT_V(n) asm volatile("s_waitcnt vmcnt(" #n ")" ::: "memory")
; #define PG8_WAIT_L(n) asm volatile("s_waitcnt lgkmcnt(" #n ")" ::: "memory")
; #define PG8_BAR __builtin_amdgcn_s_barrier()
; #define PG8_SCHED __builtin_amdgcn_sched_barrier(0)
; template <class Epi, class Sched, bool ALIGN_EPI = false, bool SP2 = false, bool TWOA = false, bool AGM = false>
; __device__ __forceinline__ void gemm_phase(LAS unsigned char* lds, const Gemm g, const Sched& S, const Epi& E, int wid) {
;     ...
;             PG8_WAIT_V(8); PG8_WAIT_L(0); PG8_BAR; PG8_MMA(0, 0, At, B0); PG8_MMA(0, 1, At, B1); PG8_BAR; PG8_SCHED;
;             PG8_LDA(At, 0, 1); PG8_STAGE(PG8_SB(0, 0), b2, voffB); PG8_STAGE(PG8_SB(0, 1), b2 + hstep, voffB); PG8_STAGE(PG8_SA(0, 0), a2, voffA);
;             PG8_WAIT_V(8); PG8_WAIT_L(0); PG8_BAR; PG8_MMA(1, 0, At, B0); PG8_MMA(1, 1, At, B1); PG8_BAR; PG8_SCHED;
;             PG8_LDB(B0, 1, 0); PG8_LDB(B1, 1, 1); PG8_SCHED; PG8_LDA(At, 1, 0); PG8_STAGE(PG8_SA(0, 1), a2 + hstepA, voffA);
;             PG8_WAIT_V(8); PG8_WAIT_L(0); PG8_BAR; PG8_MMA(0, 0, At, B0); PG8_MMA(0, 1, At, B1); PG8_BAR; PG8_SCHED;
	s_setprio 1
	v_mfma_f32_16x16x32_bf16 v[64:67], v[108:111], v[198:201], v[64:67]
	v_mfma_f32_16x16x32_bf16 v[68:71], v[116:119], v[198:201], v[68:71]
	v_mfma_f32_16x16x32_bf16 v[72:75], v[108:111], v[206:209], v[72:75]
	v_mfma_f32_16x16x32_bf16 v[76:79], v[116:119], v[206:209], v[76:79]
	v_mfma_f32_16x16x32_bf16 v[80:83], v[108:111], v[214:217], v[80:83]
	v_mfma_f32_16x16x32_bf16 v[84:87], v[116:119], v[214:217], v[84:87]
	v_mfma_f32_16x16x32_bf16 v[88:91], v[108:111], v[222:225], v[88:91]
	v_mfma_f32_16x16x32_bf16 v[64:67], v[112:115], v[202:205], v[64:67]
	v_mfma_f32_16x16x32_bf16 v[68:71], v[120:123], v[202:205], v[68:71]
	v_mfma_f32_16x16x32_bf16 v[72:75], v[112:115], v[210:213], v[72:75]
	v_mfma_f32_16x16x32_bf16 v[76:79], v[120:123], v[210:213], v[76:79]
	v_mfma_f32_16x16x32_bf16 v[80:83], v[112:115], v[218:221], v[80:83]
	v_mfma_f32_16x16x32_bf16 v[84:87], v[120:123], v[218:221], v[84:87]
	v_mfma_f32_16x16x32_bf16 v[230:233], v[112:115], v[226:229], v[88:91]
	v_mfma_f32_16x16x32_bf16 v[88:91], v[116:119], v[222:225], v[92:95]
	v_mfma_f32_16x16x32_bf16 v[234:237], v[120:123], v[226:229], v[88:91]
	s_setprio 0
	s_setprio 1
	v_mfma_f32_16x16x32_bf16 v[88:91], v[124:127], v[198:201], v[96:99]
	v_mfma_f32_16x16x32_bf16 v[96:99], v[186:189], v[202:205], v[88:91]
	v_mfma_f32_16x16x32_bf16 v[36:39], v[190:193], v[198:201], v[36:39]
	v_mfma_f32_16x16x32_bf16 v[88:91], v[124:127], v[206:209], v[100:103]
	v_mfma_f32_16x16x32_bf16 v[40:43], v[190:193], v[206:209], v[40:43]
	v_mfma_f32_16x16x32_bf16 v[44:47], v[124:127], v[214:217], v[44:47]
	v_mfma_f32_16x16x32_bf16 v[48:51], v[190:193], v[214:217], v[48:51]
	v_mfma_f32_16x16x32_bf16 v[52:55], v[124:127], v[222:225], v[52:55]
	v_mfma_f32_16x16x32_bf16 v[56:59], v[190:193], v[222:225], v[56:59]
	v_mfma_f32_16x16x32_bf16 v[36:39], v[194:197], v[202:205], v[36:39]
	v_mfma_f32_16x16x32_bf16 v[100:103], v[186:189], v[210:213], v[88:91]
	v_mfma_f32_16x16x32_bf16 v[40:43], v[194:197], v[210:213], v[40:43]
	v_mfma_f32_16x16x32_bf16 v[44:47], v[186:189], v[218:221], v[44:47]
	v_mfma_f32_16x16x32_bf16 v[48:51], v[194:197], v[218:221], v[48:51]
	v_mfma_f32_16x16x32_bf16 v[52:55], v[186:189], v[226:229], v[52:55]
	v_mfma_f32_16x16x32_bf16 v[56:59], v[194:197], v[226:229], v[56:59]
	s_setprio 0
	s_barrier
	s_mov_b32 m0, s85
	v_lshl_add_u64 v[140:141], v[0:1], 0, s[26:27]
	s_add_u32 s34, s52, 0x20200
	ds_read_b128 v[88:91], v137 offset:16384
	ds_read_b128 v[92:95], v137 offset:17408
	ds_read_b128 v[198:201], v137 offset:18432
	ds_read_b128 v[202:205], v137 offset:19456
	ds_read_b128 v[206:209], v137 offset:20480
	ds_read_b128 v[210:213], v137 offset:21504
	ds_read_b128 v[214:217], v137 offset:22528
	ds_read_b128 v[218:221], v137 offset:23552
	global_load_lds_dwordx4 v[140:141], off
	v_lshl_add_u64 v[140:141], v[2:3], 0, s[26:27]
	s_mov_b32 m0, s86
	s_addc_u32 s35, s53, 0
	global_load_lds_dwordx4 v[140:141], off
	v_lshl_add_u64 v[140:141], s[34:35], 0, v[132:133]
	s_mov_b32 m0, s87
	v_lshl_add_u64 v[148:149], s[54:55], 0, v[134:135]
	global_load_lds_dwordx4 v[140:141], off
	v_lshl_add_u64 v[140:141], s[34:35], 0, v[128:129]
	s_mov_b32 m0, s88
	v_lshl_add_u64 v[150:151], s[54:55], 0, v[130:131]
	global_load_lds_dwordx4 v[140:141], off
	s_mov_b32 m0, s45
	s_nop 0
	global_load_lds_dwordx4 v[148:149], off
	s_mov_b32 m0, s47
	s_nop 0
	global_load_lds_dwordx4 v[150:151], off
	s_waitcnt vmcnt(8)
	s_waitcnt lgkmcnt(0)
	s_barrier
	s_setprio 1
	v_mfma_f32_16x16x32_bf16 v[4:7], v[108:111], v[214:217], v[4:7]
	v_mfma_f32_16x16x32_bf16 v[8:11], v[116:119], v[214:217], v[8:11]
	v_mfma_f32_16x16x32_bf16 v[162:165], v[108:111], v[88:91], v[162:165]
	v_mfma_f32_16x16x32_bf16 v[166:169], v[116:119], v[88:91], v[166:169]
	v_mfma_f32_16x16x32_bf16 v[170:173], v[108:111], v[198:201], v[170:173]
	v_mfma_f32_16x16x32_bf16 v[174:177], v[116:119], v[198:201], v[174:177]
	v_mfma_f32_16x16x32_bf16 v[178:181], v[108:111], v[206:209], v[178:181]
	v_mfma_f32_16x16x32_bf16 v[182:185], v[116:119], v[206:209], v[182:185]
	v_mfma_f32_16x16x32_bf16 v[4:7], v[112:115], v[218:221], v[4:7]
	v_mfma_f32_16x16x32_bf16 v[8:11], v[120:123], v[218:221], v[8:11]
	v_mfma_f32_16x16x32_bf16 v[162:165], v[112:115], v[92:95], v[162:165]
	v_mfma_f32_16x16x32_bf16 v[166:169], v[120:123], v[92:95], v[166:169]
	v_mfma_f32_16x16x32_bf16 v[170:173], v[112:115], v[202:205], v[170:173]
	v_mfma_f32_16x16x32_bf16 v[174:177], v[120:123], v[202:205], v[174:177]
	v_mfma_f32_16x16x32_bf16 v[178:181], v[112:115], v[210:213], v[178:181]
	v_mfma_f32_16x16x32_bf16 v[182:185], v[120:123], v[210:213], v[182:185]
	s_setprio 0
	s_setprio 1
	v_mfma_f32_16x16x32_bf16 v[12:15], v[124:127], v[88:91], v[12:15]
	v_mfma_f32_16x16x32_bf16 v[222:225], v[186:189], v[92:95], v[12:15]
	v_mfma_f32_16x16x32_bf16 v[12:15], v[190:193], v[88:91], v[16:19]
	v_mfma_f32_16x16x32_bf16 v[16:19], v[194:197], v[92:95], v[12:15]
	v_mfma_f32_16x16x32_bf16 v[12:15], v[124:127], v[198:201], v[28:31]
	v_mfma_f32_16x16x32_bf16 v[226:229], v[186:189], v[202:205], v[12:15]
	v_mfma_f32_16x16x32_bf16 v[12:15], v[190:193], v[198:201], v[32:35]
	v_mfma_f32_16x16x32_bf16 v[32:35], v[194:197], v[202:205], v[12:15]
	v_mfma_f32_16x16x32_bf16 v[12:15], v[124:127], v[206:209], v[60:63]
	v_mfma_f32_16x16x32_bf16 v[198:201], v[186:189], v[210:213], v[12:15]
	v_mfma_f32_16x16x32_bf16 v[12:15], v[190:193], v[206:209], v[104:107]
	v_mfma_f32_16x16x32_bf16 v[202:205], v[194:197], v[210:213], v[12:15]
	v_mfma_f32_16x16x32_bf16 v[12:15], v[124:127], v[214:217], v[20:23]
	v_mfma_f32_16x16x32_bf16 v[186:189], v[186:189], v[218:221], v[12:15]
	v_mfma_f32_16x16x32_bf16 v[12:15], v[190:193], v[214:217], v[24:27]
	v_mfma_f32_16x16x32_bf16 v[190:193], v[194:197], v[218:221], v[12:15]
	s_setprio 0
	s_barrier
; #define PG8_STAGE(bufoff, gbase, voff) do { _Pragma("unroll") for (int _i = 0; _i < 2; ++_i) \
;         __builtin_amdgcn_global_load_lds((const unsigned*)((const char*)(gbase) + (voff)[_i]), (LAS unsigned*)(lds + (bufoff) + ldsw + _i * 8192), 16, 0, 0); } while (0)
; #define PG8_LDA(dst, b, h) do { _Pragma("unroll") for (int m = 0; m < 4; ++m) _Pragma("unroll") for (int k = 0; k < 2; ++k) dst[m][k] = *(const LAS bf16x8*)(lds + PG8_SA(b, h) + aoff + m * 2048 + k * 1024); } while (0)
; #define PG8_LDB(dst, b, h) do { _Pragma("unroll") for (int n = 0; n < 2; ++n) _Pragma("unroll") for (int k = 0; k < 2; ++k) dst[n][k] = *(const LAS bf16x8*)(lds + PG8_SB(b, h) + boff + n * 2048 + k * 1024); } while (0)
; #define PG8_MMA(ai, bj, At, Bt) do { __builtin_amdgcn_s_setprio(1); _Pragma("unroll") for (int m = 0; m < 4; ++m) _Pragma("unroll") for (int n = 0; n < 2; ++n) _Pragma("unroll") for (int k = 0; k < 2; ++k) \
;         acc[ai][bj][m][n] = __builtin_amdgcn_mfma_f32_16x16x32_bf16(Bt[n][k], At[m][k], acc[ai][bj][m][n], 0, 0, 0); __builtin_amdgcn_s_setprio(0); } while (0)
; #define PG8_WAIT_V(n) asm volatile("s_waitcnt vmcnt(" #n ")" ::: "memory")
; #define PG8_WAIT_L(n) asm volatile("s_waitcnt lgkmcnt(" #n ")" ::: "memory")
; #define PG8_BAR __builtin_amdgcn_s_barrier()
; #define PG8_SCHED __builtin_amdgcn_sched_barrier(0)
; template <class Epi, class Sched, bool ALIGN_EPI = false, bool SP2 = false, bool TWOA = false, bool AGM = false>
; __device__ __forceinline__ void gemm_phase(LAS unsigned char* lds, const Gemm g, const Sched& S, const Epi& E, int wid) {
;     ...
;             PG8_LDB(B0, 1, 0); PG8_LDB(B1, 1, 1); PG8_SCHED; PG8_LDA(At, 1, 0); PG8_STAGE(PG8_SA(0, 1), a2 + hstepA, voffA);
;             PG8_WAIT_V(8); PG8_WAIT_L(0); PG8_BAR; PG8_MMA(0, 0, At, B0); PG8_MMA(0, 1, At, B1); PG8_BAR; PG8_SCHED;
;             PG8_LDA(At, 1, 1); PG8_STAGE(PG8_SB(1, 0), b3, voffB); PG8_STAGE(PG8_SB(1, 1), b3 + hstep, voffB); PG8_STAGE(PG8_SA(1, 0), a3, voffA);
;             PG8_WAIT_V(8); PG8_WAIT_L(0); PG8_BAR; PG8_MMA(1, 0, At, B0); PG8_MMA(1, 1, At, B1); PG8_BAR; PG8_SCHED;
	s_nop 4
	ds_read_b128 v[12:15], v159
	ds_read_b128 v[20:23], v159 offset:1024
	ds_read_b128 v[194:197], v159 offset:2048
	ds_read_b128 v[206:209], v159 offset:3072
	ds_read_b128 v[210:213], v160
	ds_read_b128 v[214:217], v160 offset:1024
	ds_read_b128 v[218:221], v160 offset:2048
	ds_read_b128 v[238:241], v160 offset:3072
	s_add_u32 s34, s54, 0x10000
	s_addc_u32 s35, s55, 0
	s_mov_b32 m0, s70
	v_lshl_add_u64 v[88:89], s[34:35], 0, v[134:135]
	ds_read_b128 v[24:27], v137 offset:32768
	ds_read_b128 v[28:31], v137 offset:33792
	ds_read_b128 v[60:63], v137 offset:34816
	ds_read_b128 v[242:245], v137 offset:35840
	ds_read_b128 v[246:249], v137 offset:36864
	ds_read_b128 v[250:253], v137 offset:37888
	ds_read_b128 v[140:143], v137 offset:38912
	ds_read_b128 v[144:147], v137 offset:39936
	global_load_lds_dwordx4 v[88:89], off
	v_lshl_add_u64 v[88:89], s[34:35], 0, v[130:131]
	s_mov_b32 m0, s71
	s_nop 0
	global_load_lds_dwordx4 v[88:89], off
	s_waitcnt vmcnt(8)
	s_waitcnt lgkmcnt(0)
	s_barrier
	s_setprio 1
	v_mfma_f32_16x16x32_bf16 v[64:67], v[12:15], v[24:27], v[64:67]
	v_mfma_f32_16x16x32_bf16 v[124:127], v[20:23], v[28:31], v[64:67]
	v_mfma_f32_16x16x32_bf16 v[64:67], v[194:197], v[24:27], v[68:71]
	v_mfma_f32_16x16x32_bf16 v[120:123], v[206:209], v[28:31], v[64:67]
	v_mfma_f32_16x16x32_bf16 v[64:67], v[12:15], v[60:63], v[72:75]
	v_mfma_f32_16x16x32_bf16 v[108:111], v[20:23], v[242:245], v[64:67]
	v_mfma_f32_16x16x32_bf16 v[64:67], v[194:197], v[60:63], v[76:79]
	v_mfma_f32_16x16x32_bf16 v[104:107], v[206:209], v[242:245], v[64:67]
	v_mfma_f32_16x16x32_bf16 v[64:67], v[12:15], v[246:249], v[80:83]
	v_mfma_f32_16x16x32_bf16 v[92:95], v[20:23], v[250:253], v[64:67]
	v_mfma_f32_16x16x32_bf16 v[64:67], v[194:197], v[246:249], v[84:87]
	v_mfma_f32_16x16x32_bf16 v[88:91], v[206:209], v[250:253], v[64:67]
	v_mfma_f32_16x16x32_bf16 v[64:67], v[12:15], v[140:143], v[230:233]
	v_mfma_f32_16x16x32_bf16 v[76:79], v[20:23], v[144:147], v[64:67]
	v_mfma_f32_16x16x32_bf16 v[64:67], v[194:197], v[140:143], v[234:237]
	v_mfma_f32_16x16x32_bf16 v[72:75], v[206:209], v[144:147], v[64:67]
	s_setprio 0
	s_setprio 1
	v_mfma_f32_16x16x32_bf16 v[64:67], v[210:213], v[24:27], v[96:99]
	v_mfma_f32_16x16x32_bf16 v[24:27], v[218:221], v[24:27], v[36:39]
	v_mfma_f32_16x16x32_bf16 v[112:115], v[238:241], v[28:31], v[24:27]
	v_mfma_f32_16x16x32_bf16 v[24:27], v[210:213], v[60:63], v[100:103]
	v_mfma_f32_16x16x32_bf16 v[100:103], v[214:217], v[242:245], v[24:27]
	v_mfma_f32_16x16x32_bf16 v[24:27], v[218:221], v[60:63], v[40:43]
	v_mfma_f32_16x16x32_bf16 v[96:99], v[238:241], v[242:245], v[24:27]
	v_mfma_f32_16x16x32_bf16 v[24:27], v[210:213], v[246:249], v[44:47]
	v_mfma_f32_16x16x32_bf16 v[84:87], v[214:217], v[250:253], v[24:27]
	v_mfma_f32_16x16x32_bf16 v[24:27], v[218:221], v[246:249], v[48:51]
	v_mfma_f32_16x16x32_bf16 v[80:83], v[238:241], v[250:253], v[24:27]
	v_mfma_f32_16x16x32_bf16 v[24:27], v[210:213], v[140:143], v[52:55]
	v_mfma_f32_16x16x32_bf16 v[68:71], v[214:217], v[144:147], v[24:27]
	v_mfma_f32_16x16x32_bf16 v[24:27], v[218:221], v[140:143], v[56:59]
	v_mfma_f32_16x16x32_bf16 v[116:119], v[214:217], v[28:31], v[64:67]
	v_mfma_f32_16x16x32_bf16 v[64:67], v[238:241], v[144:147], v[24:27]
	s_setprio 0
	s_barrier
	s_mov_b32 m0, s56
	v_lshl_add_u64 v[0:1], v[0:1], 0, s[28:29]
	s_add_u32 s34, s52, 0x20280
	ds_read_b128 v[36:39], v137 offset:49152
	ds_read_b128 v[48:51], v137 offset:50176
	ds_read_b128 v[140:143], v137 offset:51200
	ds_read_b128 v[144:147], v137 offset:52224
	ds_read_b128 v[230:233], v137 offset:53248
	ds_read_b128 v[234:237], v137 offset:54272
	ds_read_b128 v[242:245], v137 offset:55296
	ds_read_b128 v[246:249], v137 offset:56320
	global_load_lds_dwordx4 v[0:1], off
	v_lshl_add_u64 v[0:1], v[2:3], 0, s[28:29]
	s_mov_b32 m0, s57
	s_addc_u32 s35, s53, 0
	global_load_lds_dwordx4 v[0:1], off
	v_lshl_add_u64 v[0:1], s[34:35], 0, v[132:133]
	s_mov_b32 m0, s89
	s_nop 0
	global_load_lds_dwordx4 v[0:1], off
	v_lshl_add_u64 v[0:1], s[34:35], 0, v[128:129]
	s_mov_b32 m0, s90
	s_nop 0
	global_load_lds_dwordx4 v[0:1], off
	v_lshl_add_u64 v[0:1], v[148:149], 0, s[12:13]
	s_mov_b32 m0, s74
	s_nop 0
	global_load_lds_dwordx4 v[0:1], off
	v_lshl_add_u64 v[0:1], v[150:151], 0, s[12:13]
	s_mov_b32 m0, s75
	s_nop 0
	global_load_lds_dwordx4 v[0:1], off
	s_waitcnt vmcnt(8)
	s_waitcnt lgkmcnt(0)
	s_barrier
	s_setprio 1
	v_mfma_f32_16x16x32_bf16 v[0:3], v[12:15], v[36:39], v[162:165]
	v_mfma_f32_16x16x32_bf16 v[60:63], v[20:23], v[48:51], v[0:3]
	v_mfma_f32_16x16x32_bf16 v[0:3], v[194:197], v[36:39], v[166:169]
	v_mfma_f32_16x16x32_bf16 v[56:59], v[206:209], v[48:51], v[0:3]
	v_mfma_f32_16x16x32_bf16 v[0:3], v[12:15], v[140:143], v[170:173]
	v_mfma_f32_16x16x32_bf16 v[44:47], v[20:23], v[144:147], v[0:3]
	v_mfma_f32_16x16x32_bf16 v[0:3], v[194:197], v[140:143], v[174:177]
	v_mfma_f32_16x16x32_bf16 v[40:43], v[206:209], v[144:147], v[0:3]
	v_mfma_f32_16x16x32_bf16 v[0:3], v[12:15], v[230:233], v[178:181]
	v_mfma_f32_16x16x32_bf16 v[28:31], v[20:23], v[234:237], v[0:3]
	v_mfma_f32_16x16x32_bf16 v[0:3], v[194:197], v[230:233], v[182:185]
	v_mfma_f32_16x16x32_bf16 v[24:27], v[206:209], v[234:237], v[0:3]
	v_mfma_f32_16x16x32_bf16 v[0:3], v[12:15], v[242:245], v[4:7]
	v_mfma_f32_16x16x32_bf16 v[12:15], v[20:23], v[246:249], v[0:3]
	v_mfma_f32_16x16x32_bf16 v[0:3], v[194:197], v[242:245], v[8:11]
	v_mfma_f32_16x16x32_bf16 v[8:11], v[206:209], v[246:249], v[0:3]
	s_setprio 0
	s_setprio 1
	v_mfma_f32_16x16x32_bf16 v[0:3], v[210:213], v[36:39], v[222:225]
	v_mfma_f32_16x16x32_bf16 v[52:55], v[214:217], v[48:51], v[0:3]
	v_mfma_f32_16x16x32_bf16 v[0:3], v[218:221], v[36:39], v[16:19]
	v_mfma_f32_16x16x32_bf16 v[48:51], v[238:241], v[48:51], v[0:3]
	v_mfma_f32_16x16x32_bf16 v[0:3], v[210:213], v[140:143], v[226:229]
	v_mfma_f32_16x16x32_bf16 v[36:39], v[214:217], v[144:147], v[0:3]
	v_mfma_f32_16x16x32_bf16 v[0:3], v[218:221], v[140:143], v[32:35]
	v_mfma_f32_16x16x32_bf16 v[32:35], v[238:241], v[144:147], v[0:3]
	v_mfma_f32_16x16x32_bf16 v[0:3], v[210:213], v[230:233], v[198:201]
	v_mfma_f32_16x16x32_bf16 v[20:23], v[214:217], v[234:237], v[0:3]
	v_mfma_f32_16x16x32_bf16 v[0:3], v[218:221], v[230:233], v[202:205]
	v_mfma_f32_16x16x32_bf16 v[16:19], v[238:241], v[234:237], v[0:3]
	v_mfma_f32_16x16x32_bf16 v[0:3], v[210:213], v[242:245], v[186:189]
	v_mfma_f32_16x16x32_bf16 v[4:7], v[214:217], v[246:249], v[0:3]
	v_mfma_f32_16x16x32_bf16 v[0:3], v[218:221], v[242:245], v[190:193]
	v_mfma_f32_16x16x32_bf16 v[0:3], v[238:241], v[246:249], v[0:3]
	s_setprio 0
	s_barrier
	s_add_u32 s91, s52, 0x300
	s_addc_u32 s92, s53, 0
	s_mov_b32 s93, 2
; #define PG8_STAGE(bufoff, gbase, voff) do { _Pragma("unroll") for (int _i = 0; _i < 2; ++_i) \
;         __builtin_amdgcn_global_load_lds((const unsigned*)((const char*)(gbase) + (voff)[_i]), (LAS unsigned*)(lds + (bufoff) + ldsw + _i * 8192), 16, 0, 0); } while (0)
; #define PG8_LDA(dst, b, h) do { _Pragma("unroll") for (int m = 0; m < 4; ++m) _Pragma("unroll") for (int k = 0; k < 2; ++k) dst[m][k] = *(const LAS bf16x8*)(lds + PG8_SA(b, h) + aoff + m * 2048 + k * 1024); } while (0)
; #define PG8_WAIT_V(n) asm volatile("s_waitcnt vmcnt(" #n ")" ::: "memory")
; #define PG8_WAIT_L(n) asm volatile("s_waitcnt lgkmcnt(" #n ")" ::: "memory")
; template <class Epi, class Sched, bool ALIGN_EPI = false, bool SP2 = false, bool TWOA = false, bool AGM = false>
; __device__ __forceinline__ void gemm_phase(LAS unsigned char* lds, const Gemm g, const Sched& S, const Epi& E, int wid) {
;     ...
;         const bool has_next = S.next(ui + 1, nxt);
;         const char* nA = has_next ? (const char*)g.A + (size_t)nxt.pm * tstepA : cA; const char* nB = has_next ? (const char*)g.Bt + (size_t)nxt.pn * tstep : cB;
;         for (int t = 0; t < nt; t += 2) {
;             const bool last = (t == nt - 2);
;             const char* cA2 = TWOA ? (const char*)g.A2 + (cA - (const char*)g.A) - (size_t)nh * kstepA : cA;
;             const char* a1_ = (TWOA && t + 1 >= nh ? cA2 : cA) + (size_t)(t + 1) * kstepA;
;             const char* a2_ = last ? nA : (TWOA && t + 2 >= nh ? cA2 : cA) + (size_t)(t + 2) * kstepA; const char* a1 = a1_; const char* a2 = a2_; const char* b2 = last ? nB : cB + (size_t)(t + 2) * kstep;
;             if constexpr (TWOA) { asm volatile("" : "+s"(a1)); asm volatile("" : "+s"(a2)); }
;             const char* a3 = a2 + kstepA; const char* b3 = b2 + kstep;
;             if (last && has_next) S.a_ready(nxt);
;             if constexpr (has_mid<Epi>::value) { if (t == nh) E.mid(acc, cur, wr, wc, fr, fq); }
;             if constexpr (SP2) {
;             PG8_LDB(B0, 0, 0); PG8_LDB(B1, 0, 1); PG8_SCHED; PG8_LDA(At, 0, 0); PG8_STAGE(PG8_SA(1, 1), a1 + hstepA, voffA);
;             PG8_WAIT_V(8); PG8_WAIT_L(0); PG8_BAR; PG8_MMA(0, 0, At, B0); PG8_MMA(0, 1, At, B1); PG8_BAR; PG8_SCHED;
;             PG8_LDA(At, 0, 1); PG8_STAGE(PG8_SB(0, 0), b2, voffB); PG8_STAGE(PG8_SB(0, 1), b2 + hstep, voffB); PG8_STAGE(PG8_SA(0, 0), a2, voffA);
.LBB0_683:
	s_add_u32 s34, s50, 0x80
	s_addc_u32 s35, s51, 0
	s_add_u32 s50, s50, 0x100
	s_addc_u32 s51, s51, 0
	s_cmp_eq_u32 s93, 4
	s_cselect_b32 s55, s37, s51
	s_cselect_b32 s54, s80, s50
	ds_read_b128 v[140:143], v157
	ds_read_b128 v[144:147], v157 offset:1024
	ds_read_b128 v[162:165], v157 offset:2048
	ds_read_b128 v[166:169], v157 offset:3072
	ds_read_b128 v[170:173], v158
	ds_read_b128 v[174:177], v158 offset:1024
	ds_read_b128 v[178:181], v158 offset:2048
	ds_read_b128 v[182:185], v158 offset:3072
	s_cselect_b32 s53, s31, s92
	s_cselect_b32 s52, s82, s91
	s_add_u32 s34, s34, 0x10000
	s_addc_u32 s35, s35, 0
	s_mov_b32 m0, s83
	v_lshl_add_u64 v[148:149], s[34:35], 0, v[134:135]
	ds_read_b128 v[186:189], v137
	ds_read_b128 v[190:193], v137 offset:1024
	ds_read_b128 v[194:197], v137 offset:2048
	ds_read_b128 v[198:201], v137 offset:3072
	ds_read_b128 v[202:205], v137 offset:4096
	ds_read_b128 v[206:209], v137 offset:5120
	ds_read_b128 v[210:213], v137 offset:6144
	ds_read_b128 v[214:217], v137 offset:7168
	global_load_lds_dwordx4 v[148:149], off
	v_lshl_add_u64 v[148:149], s[34:35], 0, v[130:131]
	s_mov_b32 m0, s84
	s_nop 0
	global_load_lds_dwordx4 v[148:149], off
	s_waitcnt vmcnt(8)
	s_waitcnt lgkmcnt(0)
	s_barrier
	s_setprio 1
	v_mfma_f32_16x16x32_bf16 v[124:127], v[140:143], v[186:189], v[124:127]
	v_mfma_f32_16x16x32_bf16 v[120:123], v[162:165], v[186:189], v[120:123]
	v_mfma_f32_16x16x32_bf16 v[108:111], v[140:143], v[194:197], v[108:111]
	v_mfma_f32_16x16x32_bf16 v[104:107], v[162:165], v[194:197], v[104:107]
	v_mfma_f32_16x16x32_bf16 v[92:95], v[140:143], v[202:205], v[92:95]
	v_mfma_f32_16x16x32_bf16 v[88:91], v[162:165], v[202:205], v[88:91]
	v_mfma_f32_16x16x32_bf16 v[76:79], v[140:143], v[210:213], v[76:79]
	v_mfma_f32_16x16x32_bf16 v[72:75], v[162:165], v[210:213], v[72:75]
	v_mfma_f32_16x16x32_bf16 v[124:127], v[144:147], v[190:193], v[124:127]
	v_mfma_f32_16x16x32_bf16 v[120:123], v[166:169], v[190:193], v[120:123]
	v_mfma_f32_16x16x32_bf16 v[108:111], v[144:147], v[198:201], v[108:111]
	v_mfma_f32_16x16x32_bf16 v[104:107], v[166:169], v[198:201], v[104:107]
	v_mfma_f32_16x16x32_bf16 v[92:95], v[144:147], v[206:209], v[92:95]
	v_mfma_f32_16x16x32_bf16 v[88:91], v[166:169], v[206:209], v[88:91]
	v_mfma_f32_16x16x32_bf16 v[76:79], v[144:147], v[214:217], v[76:79]
	v_mfma_f32_16x16x32_bf16 v[72:75], v[166:169], v[214:217], v[72:75]
	s_setprio 0
	s_setprio 1
	v_mfma_f32_16x16x32_bf16 v[116:119], v[170:173], v[186:189], v[116:119]
	v_mfma_f32_16x16x32_bf16 v[112:115], v[178:181], v[186:189], v[112:115]
	v_mfma_f32_16x16x32_bf16 v[100:103], v[170:173], v[194:197], v[100:103]
	v_mfma_f32_16x16x32_bf16 v[96:99], v[178:181], v[194:197], v[96:99]
	v_mfma_f32_16x16x32_bf16 v[84:87], v[170:173], v[202:205], v[84:87]
	v_mfma_f32_16x16x32_bf16 v[80:83], v[178:181], v[202:205], v[80:83]
	v_mfma_f32_16x16x32_bf16 v[68:71], v[170:173], v[210:213], v[68:71]
	v_mfma_f32_16x16x32_bf16 v[64:67], v[178:181], v[210:213], v[64:67]
	v_mfma_f32_16x16x32_bf16 v[116:119], v[174:177], v[190:193], v[116:119]
	v_mfma_f32_16x16x32_bf16 v[112:115], v[182:185], v[190:193], v[112:115]
	v_mfma_f32_16x16x32_bf16 v[100:103], v[174:177], v[198:201], v[100:103]
	v_mfma_f32_16x16x32_bf16 v[96:99], v[182:185], v[198:201], v[96:99]
	v_mfma_f32_16x16x32_bf16 v[84:87], v[174:177], v[206:209], v[84:87]
	v_mfma_f32_16x16x32_bf16 v[80:83], v[182:185], v[206:209], v[80:83]
	v_mfma_f32_16x16x32_bf16 v[68:71], v[174:177], v[214:217], v[68:71]
	v_mfma_f32_16x16x32_bf16 v[64:67], v[182:185], v[214:217], v[64:67]
	s_setprio 0
	s_barrier
	s_mov_b32 m0, s85
	v_lshl_add_u64 v[148:149], s[52:53], 0, v[132:133]
	s_add_u32 s34, s52, 0x20000
	ds_read_b128 v[186:189], v137 offset:16384
	ds_read_b128 v[190:193], v137 offset:17408
	ds_read_b128 v[194:197], v137 offset:18432
	ds_read_b128 v[198:201], v137 offset:19456
	ds_read_b128 v[202:205], v137 offset:20480
	ds_read_b128 v[206:209], v137 offset:21504
	ds_read_b128 v[210:213], v137 offset:22528
	ds_read_b128 v[214:217], v137 offset:23552
	global_load_lds_dwordx4 v[148:149], off
	v_lshl_add_u64 v[150:151], s[52:53], 0, v[128:129]
	s_mov_b32 m0, s86
	s_addc_u32 s35, s53, 0
	global_load_lds_dwordx4 v[150:151], off
	v_lshl_add_u64 v[218:219], s[34:35], 0, v[132:133]
	s_mov_b32 m0, s87
	v_lshl_add_u64 v[220:221], s[54:55], 0, v[130:131]
	global_load_lds_dwordx4 v[218:219], off
	v_lshl_add_u64 v[218:219], s[34:35], 0, v[128:129]
	s_mov_b32 m0, s88
	s_nop 0
	global_load_lds_dwordx4 v[218:219], off
	v_lshl_add_u64 v[218:219], s[54:55], 0, v[134:135]
	s_mov_b32 m0, s45
	s_nop 0
	global_load_lds_dwordx4 v[218:219], off
	s_mov_b32 m0, s47
	s_nop 0
	global_load_lds_dwordx4 v[220:221], off
	s_waitcnt vmcnt(8)
	s_waitcnt lgkmcnt(0)
	s_barrier
; #define PG8_STAGE(bufoff, gbase, voff) do { _Pragma("unroll") for (int _i = 0; _i < 2; ++_i) \
;         __builtin_amdgcn_global_load_lds((const unsigned*)((const char*)(gbase) + (voff)[_i]), (LAS unsigned*)(lds + (bufoff) + ldsw + _i * 8192), 16, 0, 0); } while (0)
; #define PG8_LDA(dst, b, h) do { _Pragma("unroll") for (int m = 0; m < 4; ++m) _Pragma("unroll") for (int k = 0; k < 2; ++k) dst[m][k] = *(const LAS bf16x8*)(lds + PG8_SA(b, h) + aoff + m * 2048 + k * 1024); } while (0)
; #define PG8_LDB(dst, b, h) do { _Pragma("unroll") for (int n = 0; n < 2; ++n) _Pragma("unroll") for (int k = 0; k < 2; ++k) dst[n][k] = *(const LAS bf16x8*)(lds + PG8_SB(b, h) + boff + n * 2048 + k * 1024); } while (0)
; #define PG8_MMA(ai, bj, At, Bt) do { __builtin_amdgcn_s_setprio(1); _Pragma("unroll") for (int m = 0; m < 4; ++m) _Pragma("unroll") for (int n = 0; n < 2; ++n) _Pragma("unroll") for (int k = 0; k < 2; ++k) \
;         acc[ai][bj][m][n] = __builtin_amdgcn_mfma_f32_16x16x32_bf16(Bt[n][k], At[m][k], acc[ai][bj][m][n], 0, 0, 0); __builtin_amdgcn_s_setprio(0); } while (0)
; #define PG8_WAIT_V(n) asm volatile("s_waitcnt vmcnt(" #n ")" ::: "memory")
; #define PG8_WAIT_L(n) asm volatile("s_waitcnt lgkmcnt(" #n ")" ::: "memory")
; #define PG8_BAR __builtin_amdgcn_s_barrier()
; #define PG8_SCHED __builtin_amdgcn_sched_barrier(0)
; template <class Epi, class Sched, bool ALIGN_EPI = false, bool SP2 = false, bool TWOA = false, bool AGM = false>
; __device__ __forceinline__ void gemm_phase(LAS unsigned char* lds, const Gemm g, const Sched& S, const Epi& E, int wid) {
;     ...
;             PG8_WAIT_V(8); PG8_WAIT_L(0); PG8_BAR; PG8_MMA(1, 0, At, B0); PG8_MMA(1, 1, At, B1); PG8_BAR; PG8_SCHED;
;             PG8_LDB(B0, 1, 0); PG8_LDB(B1, 1, 1); PG8_SCHED; PG8_LDA(At, 1, 0); PG8_STAGE(PG8_SA(0, 1), a2 + hstepA, voffA);
;             PG8_WAIT_V(8); PG8_WAIT_L(0); PG8_BAR; PG8_MMA(0, 0, At, B0); PG8_MMA(0, 1, At, B1); PG8_BAR; PG8_SCHED;
	s_setprio 1
	v_mfma_f32_16x16x32_bf16 v[60:63], v[140:143], v[186:189], v[60:63]
	v_mfma_f32_16x16x32_bf16 v[56:59], v[162:165], v[186:189], v[56:59]
	v_mfma_f32_16x16x32_bf16 v[44:47], v[140:143], v[194:197], v[44:47]
	v_mfma_f32_16x16x32_bf16 v[40:43], v[162:165], v[194:197], v[40:43]
	v_mfma_f32_16x16x32_bf16 v[28:31], v[140:143], v[202:205], v[28:31]
	v_mfma_f32_16x16x32_bf16 v[24:27], v[162:165], v[202:205], v[24:27]
	v_mfma_f32_16x16x32_bf16 v[12:15], v[140:143], v[210:213], v[12:15]
	v_mfma_f32_16x16x32_bf16 v[8:11], v[162:165], v[210:213], v[8:11]
	v_mfma_f32_16x16x32_bf16 v[60:63], v[144:147], v[190:193], v[60:63]
	v_mfma_f32_16x16x32_bf16 v[56:59], v[166:169], v[190:193], v[56:59]
	v_mfma_f32_16x16x32_bf16 v[44:47], v[144:147], v[198:201], v[44:47]
	v_mfma_f32_16x16x32_bf16 v[40:43], v[166:169], v[198:201], v[40:43]
	v_mfma_f32_16x16x32_bf16 v[28:31], v[144:147], v[206:209], v[28:31]
	v_mfma_f32_16x16x32_bf16 v[24:27], v[166:169], v[206:209], v[24:27]
	v_mfma_f32_16x16x32_bf16 v[12:15], v[144:147], v[214:217], v[12:15]
	v_mfma_f32_16x16x32_bf16 v[8:11], v[166:169], v[214:217], v[8:11]
	s_setprio 0
	s_setprio 1
	v_mfma_f32_16x16x32_bf16 v[52:55], v[170:173], v[186:189], v[52:55]
	v_mfma_f32_16x16x32_bf16 v[48:51], v[178:181], v[186:189], v[48:51]
	v_mfma_f32_16x16x32_bf16 v[36:39], v[170:173], v[194:197], v[36:39]
	v_mfma_f32_16x16x32_bf16 v[32:35], v[178:181], v[194:197], v[32:35]
	v_mfma_f32_16x16x32_bf16 v[20:23], v[170:173], v[202:205], v[20:23]
	v_mfma_f32_16x16x32_bf16 v[16:19], v[178:181], v[202:205], v[16:19]
	v_mfma_f32_16x16x32_bf16 v[4:7], v[170:173], v[210:213], v[4:7]
	v_mfma_f32_16x16x32_bf16 v[0:3], v[178:181], v[210:213], v[0:3]
	v_mfma_f32_16x16x32_bf16 v[52:55], v[174:177], v[190:193], v[52:55]
	v_mfma_f32_16x16x32_bf16 v[48:51], v[182:185], v[190:193], v[48:51]
	v_mfma_f32_16x16x32_bf16 v[36:39], v[174:177], v[198:201], v[36:39]
	v_mfma_f32_16x16x32_bf16 v[32:35], v[182:185], v[198:201], v[32:35]
	v_mfma_f32_16x16x32_bf16 v[20:23], v[174:177], v[206:209], v[20:23]
	v_mfma_f32_16x16x32_bf16 v[16:19], v[182:185], v[206:209], v[16:19]
	v_mfma_f32_16x16x32_bf16 v[4:7], v[174:177], v[214:217], v[4:7]
	v_mfma_f32_16x16x32_bf16 v[0:3], v[182:185], v[214:217], v[0:3]
	s_setprio 0
	s_barrier
	ds_read_b128 v[140:143], v159
	ds_read_b128 v[144:147], v159 offset:1024
	ds_read_b128 v[162:165], v159 offset:2048
	ds_read_b128 v[166:169], v159 offset:3072
	ds_read_b128 v[170:173], v160
	ds_read_b128 v[174:177], v160 offset:1024
	ds_read_b128 v[178:181], v160 offset:2048
	ds_read_b128 v[182:185], v160 offset:3072
	s_add_u32 s34, s54, 0x10000
	s_addc_u32 s35, s55, 0
	s_mov_b32 m0, s70
	v_lshl_add_u64 v[222:223], s[34:35], 0, v[134:135]
	ds_read_b128 v[186:189], v137 offset:32768
	ds_read_b128 v[190:193], v137 offset:33792
	ds_read_b128 v[194:197], v137 offset:34816
	ds_read_b128 v[198:201], v137 offset:35840
	ds_read_b128 v[202:205], v137 offset:36864
	ds_read_b128 v[206:209], v137 offset:37888
	ds_read_b128 v[210:213], v137 offset:38912
	ds_read_b128 v[214:217], v137 offset:39936
	global_load_lds_dwordx4 v[222:223], off
	v_lshl_add_u64 v[222:223], s[34:35], 0, v[130:131]
	s_mov_b32 m0, s71
	s_nop 0
	global_load_lds_dwordx4 v[222:223], off
	s_waitcnt vmcnt(8)
	s_waitcnt lgkmcnt(0)
	s_barrier
	s_setprio 1
	v_mfma_f32_16x16x32_bf16 v[124:127], v[140:143], v[186:189], v[124:127]
	v_mfma_f32_16x16x32_bf16 v[120:123], v[162:165], v[186:189], v[120:123]
	v_mfma_f32_16x16x32_bf16 v[108:111], v[140:143], v[194:197], v[108:111]
	v_mfma_f32_16x16x32_bf16 v[104:107], v[162:165], v[194:197], v[104:107]
	v_mfma_f32_16x16x32_bf16 v[92:95], v[140:143], v[202:205], v[92:95]
	v_mfma_f32_16x16x32_bf16 v[88:91], v[162:165], v[202:205], v[88:91]
	v_mfma_f32_16x16x32_bf16 v[76:79], v[140:143], v[210:213], v[76:79]
	v_mfma_f32_16x16x32_bf16 v[72:75], v[162:165], v[210:213], v[72:75]
	v_mfma_f32_16x16x32_bf16 v[124:127], v[144:147], v[190:193], v[124:127]
	v_mfma_f32_16x16x32_bf16 v[120:123], v[166:169], v[190:193], v[120:123]
	v_mfma_f32_16x16x32_bf16 v[108:111], v[144:147], v[198:201], v[108:111]
	v_mfma_f32_16x16x32_bf16 v[104:107], v[166:169], v[198:201], v[104:107]
	v_mfma_f32_16x16x32_bf16 v[92:95], v[144:147], v[206:209], v[92:95]
	v_mfma_f32_16x16x32_bf16 v[88:91], v[166:169], v[206:209], v[88:91]
	v_mfma_f32_16x16x32_bf16 v[76:79], v[144:147], v[214:217], v[76:79]
	v_mfma_f32_16x16x32_bf16 v[72:75], v[166:169], v[214:217], v[72:75]
	s_setprio 0
	s_setprio 1
	v_mfma_f32_16x16x32_bf16 v[116:119], v[170:173], v[186:189], v[116:119]
	v_mfma_f32_16x16x32_bf16 v[112:115], v[178:181], v[186:189], v[112:115]
	v_mfma_f32_16x16x32_bf16 v[100:103], v[170:173], v[194:197], v[100:103]
	v_mfma_f32_16x16x32_bf16 v[96:99], v[178:181], v[194:197], v[96:99]
	v_mfma_f32_16x16x32_bf16 v[84:87], v[170:173], v[202:205], v[84:87]
	v_mfma_f32_16x16x32_bf16 v[80:83], v[178:181], v[202:205], v[80:83]
	v_mfma_f32_16x16x32_bf16 v[68:71], v[170:173], v[210:213], v[68:71]
	v_mfma_f32_16x16x32_bf16 v[64:67], v[178:181], v[210:213], v[64:67]
	v_mfma_f32_16x16x32_bf16 v[116:119], v[174:177], v[190:193], v[116:119]
	v_mfma_f32_16x16x32_bf16 v[112:115], v[182:185], v[190:193], v[112:115]
	v_mfma_f32_16x16x32_bf16 v[100:103], v[174:177], v[198:201], v[100:103]
	v_mfma_f32_16x16x32_bf16 v[96:99], v[182:185], v[198:201], v[96:99]
	v_mfma_f32_16x16x32_bf16 v[84:87], v[174:177], v[206:209], v[84:87]
	v_mfma_f32_16x16x32_bf16 v[80:83], v[182:185], v[206:209], v[80:83]
	v_mfma_f32_16x16x32_bf16 v[68:71], v[174:177], v[214:217], v[68:71]
	v_mfma_f32_16x16x32_bf16 v[64:67], v[182:185], v[214:217], v[64:67]
	s_setprio 0
	s_barrier
; #define PG8_STAGE(bufoff, gbase, voff) do { _Pragma("unroll") for (int _i = 0; _i < 2; ++_i) \
;         __builtin_amdgcn_global_load_lds((const unsigned*)((const char*)(gbase) + (voff)[_i]), (LAS unsigned*)(lds + (bufoff) + ldsw + _i * 8192), 16, 0, 0); } while (0)
; #define PG8_LDA(dst, b, h) do { _Pragma("unroll") for (int m = 0; m < 4; ++m) _Pragma("unroll") for (int k = 0; k < 2; ++k) dst[m][k] = *(const LAS bf16x8*)(lds + PG8_SA(b, h) + aoff + m * 2048 + k * 1024); } while (0)
; #define PG8_MMA(ai, bj, At, Bt) do { __builtin_amdgcn_s_setprio(1); _Pragma("unroll") for (int m = 0; m < 4; ++m) _Pragma("unroll") for (int n = 0; n < 2; ++n) _Pragma("unroll") for (int k = 0; k < 2; ++k) \
;         acc[ai][bj][m][n] = __builtin_amdgcn_mfma_f32_16x16x32_bf16(Bt[n][k], At[m][k], acc[ai][bj][m][n], 0, 0, 0); __builtin_amdgcn_s_setprio(0); } while (0)
; #define PG8_WAIT_V(n) asm volatile("s_waitcnt vmcnt(" #n ")" ::: "memory")
; #define PG8_WAIT_L(n) asm volatile("s_waitcnt lgkmcnt(" #n ")" ::: "memory")
; #define PG8_BAR __builtin_amdgcn_s_barrier()
; #define PG8_SCHED __builtin_amdgcn_sched_barrier(0)
; template <class Epi, class Sched, bool ALIGN_EPI = false, bool SP2 = false, bool TWOA = false, bool AGM = false>
; __device__ __forceinline__ void gemm_phase(LAS unsigned char* lds, const Gemm g, const Sched& S, const Epi& E, int wid) {
;     ...
;             PG8_LDA(At, 1, 1); PG8_STAGE(PG8_SB(1, 0), b3, voffB); PG8_STAGE(PG8_SB(1, 1), b3 + hstep, voffB); PG8_STAGE(PG8_SA(1, 0), a3, voffA);
;             PG8_WAIT_V(8); PG8_WAIT_L(0); PG8_BAR; PG8_MMA(1, 0, At, B0); PG8_MMA(1, 1, At, B1); PG8_BAR; PG8_SCHED;
	s_mov_b32 m0, s56
	v_lshl_add_u64 v[148:149], v[148:149], 0, s[12:13]
	s_add_u32 s34, s52, 0x20080
	ds_read_b128 v[186:189], v137 offset:49152
	ds_read_b128 v[190:193], v137 offset:50176
	ds_read_b128 v[194:197], v137 offset:51200
	ds_read_b128 v[198:201], v137 offset:52224
	ds_read_b128 v[202:205], v137 offset:53248
	ds_read_b128 v[206:209], v137 offset:54272
	ds_read_b128 v[210:213], v137 offset:55296
	ds_read_b128 v[214:217], v137 offset:56320
	global_load_lds_dwordx4 v[148:149], off
	v_lshl_add_u64 v[148:149], v[150:151], 0, s[12:13]
	s_mov_b32 m0, s57
	s_addc_u32 s35, s53, 0
	global_load_lds_dwordx4 v[148:149], off
	v_lshl_add_u64 v[148:149], s[34:35], 0, v[132:133]
	s_mov_b32 m0, s89
	s_nop 0
	global_load_lds_dwordx4 v[148:149], off
	v_lshl_add_u64 v[148:149], s[34:35], 0, v[128:129]
	s_mov_b32 m0, s90
	s_nop 0
	global_load_lds_dwordx4 v[148:149], off
	v_lshl_add_u64 v[148:149], v[218:219], 0, s[12:13]
	s_mov_b32 m0, s74
	s_nop 0
	global_load_lds_dwordx4 v[148:149], off
	v_lshl_add_u64 v[148:149], v[220:221], 0, s[12:13]
	s_mov_b32 m0, s75
	s_nop 0
	global_load_lds_dwordx4 v[148:149], off
	s_waitcnt vmcnt(8)
	s_waitcnt lgkmcnt(0)
	s_barrier
	s_setprio 1
	v_mfma_f32_16x16x32_bf16 v[60:63], v[140:143], v[186:189], v[60:63]
	v_mfma_f32_16x16x32_bf16 v[56:59], v[162:165], v[186:189], v[56:59]
	v_mfma_f32_16x16x32_bf16 v[44:47], v[140:143], v[194:197], v[44:47]
	v_mfma_f32_16x16x32_bf16 v[40:43], v[162:165], v[194:197], v[40:43]
	v_mfma_f32_16x16x32_bf16 v[28:31], v[140:143], v[202:205], v[28:31]
	v_mfma_f32_16x16x32_bf16 v[24:27], v[162:165], v[202:205], v[24:27]
	v_mfma_f32_16x16x32_bf16 v[12:15], v[140:143], v[210:213], v[12:15]
	v_mfma_f32_16x16x32_bf16 v[8:11], v[162:165], v[210:213], v[8:11]
	v_mfma_f32_16x16x32_bf16 v[60:63], v[144:147], v[190:193], v[60:63]
	v_mfma_f32_16x16x32_bf16 v[56:59], v[166:169], v[190:193], v[56:59]
	v_mfma_f32_16x16x32_bf16 v[44:47], v[144:147], v[198:201], v[44:47]
	v_mfma_f32_16x16x32_bf16 v[40:43], v[166:169], v[198:201], v[40:43]
	v_mfma_f32_16x16x32_bf16 v[28:31], v[144:147], v[206:209], v[28:31]
	v_mfma_f32_16x16x32_bf16 v[24:27], v[166:169], v[206:209], v[24:27]
	v_mfma_f32_16x16x32_bf16 v[12:15], v[144:147], v[214:217], v[12:15]
	v_mfma_f32_16x16x32_bf16 v[8:11], v[166:169], v[214:217], v[8:11]
	s_setprio 0
	s_setprio 1
	v_mfma_f32_16x16x32_bf16 v[52:55], v[170:173], v[186:189], v[52:55]
	v_mfma_f32_16x16x32_bf16 v[48:51], v[178:181], v[186:189], v[48:51]
	v_mfma_f32_16x16x32_bf16 v[36:39], v[170:173], v[194:197], v[36:39]
	v_mfma_f32_16x16x32_bf16 v[32:35], v[178:181], v[194:197], v[32:35]
	v_mfma_f32_16x16x32_bf16 v[20:23], v[170:173], v[202:205], v[20:23]
	v_mfma_f32_16x16x32_bf16 v[16:19], v[178:181], v[202:205], v[16:19]
	v_mfma_f32_16x16x32_bf16 v[4:7], v[170:173], v[210:213], v[4:7]
	v_mfma_f32_16x16x32_bf16 v[0:3], v[178:181], v[210:213], v[0:3]
	v_mfma_f32_16x16x32_bf16 v[52:55], v[174:177], v[190:193], v[52:55]
	v_mfma_f32_16x16x32_bf16 v[48:51], v[182:185], v[190:193], v[48:51]
	v_mfma_f32_16x16x32_bf16 v[36:39], v[174:177], v[198:201], v[36:39]
	v_mfma_f32_16x16x32_bf16 v[32:35], v[182:185], v[198:201], v[32:35]
	v_mfma_f32_16x16x32_bf16 v[20:23], v[174:177], v[206:209], v[20:23]
	v_mfma_f32_16x16x32_bf16 v[16:19], v[182:185], v[206:209], v[16:19]
	v_mfma_f32_16x16x32_bf16 v[4:7], v[174:177], v[214:217], v[4:7]
	v_mfma_f32_16x16x32_bf16 v[0:3], v[182:185], v[214:217], v[0:3]
	s_setprio 0
	s_barrier
	s_add_i32 s93, s93, 2
	s_add_u32 s91, s91, 0x100
	s_addc_u32 s92, s92, 0
	s_cmp_gt_u32 s93, 5
	s_cbranch_scc0 .LBB0_683
	s_and_b64 vcc, exec, s[20:21]
	s_cbranch_vccz .LBB0_686
	s_barrier

; #define PG8_STAGE(bufoff, gbase, voff) do { _Pragma("unroll") for (int _i = 0; _i < 2; ++_i) \
;         __builtin_amdgcn_global_load_lds((const unsigned*)((const char*)(gbase) + (voff)[_i]), (LAS unsigned*)(lds + (bufoff) + ldsw + _i * 8192), 16, 0, 0); } while (0)
; #define PG8_LDA(dst, b, h) do { _Pragma("unroll") for (int m = 0; m < 4; ++m) _Pragma("unroll") for (int k = 0; k < 2; ++k) dst[m][k] = *(const LAS bf16x8*)(lds + PG8_SA(b, h) + aoff + m * 2048 + k * 1024); } while (0)
; #define PG8_WAIT_V(n) asm volatile("s_waitcnt vmcnt(" #n ")" ::: "memory")
; #define PG8_WAIT_L(n) asm volatile("s_waitcnt lgkmcnt(" #n ")" ::: "memory")
; template <class Epi, class Sched, bool ALIGN_EPI = false, bool SP2 = false, bool TWOA = false, bool AGM = false>
; __device__ __forceinline__ void gemm_phase(LAS unsigned char* lds, const Gemm g, const Sched& S, const Epi& E, int wid) {
;     ...
;         const bool has_next = S.next(ui + 1, nxt);
;         const char* nA = has_next ? (const char*)g.A + (size_t)nxt.pm * tstepA : cA; const char* nB = has_next ? (const char*)g.Bt + (size_t)nxt.pn * tstep : cB;
;         for (int t = 0; t < nt; t += 2) {
;             const bool last = (t == nt - 2);
;             const char* cA2 = TWOA ? (const char*)g.A2 + (cA - (const char*)g.A) - (size_t)nh * kstepA : cA;
;             const char* a1_ = (TWOA && t + 1 >= nh ? cA2 : cA) + (size_t)(t + 1) * kstepA;
;             const char* a2_ = last ? nA : (TWOA && t + 2 >= nh ? cA2 : cA) + (size_t)(t + 2) * kstepA; const char* a1 = a1_; const char* a2 = a2_; const char* b2 = last ? nB : cB + (size_t)(t + 2) * kstep;
;             if constexpr (TWOA) { asm volatile("" : "+s"(a1)); asm volatile("" : "+s"(a2)); }
;             const char* a3 = a2 + kstepA; const char* b3 = b2 + kstep;
;             if (last && has_next) S.a_ready(nxt);
;             if constexpr (has_mid<Epi>::value) { if (t == nh) E.mid(acc, cur, wr, wc, fr, fq); }
;             if constexpr (SP2) {
;             PG8_LDB(B0, 0, 0); PG8_LDB(B1, 0, 1); PG8_SCHED; PG8_LDA(At, 0, 0); PG8_STAGE(PG8_SA(1, 1), a1 + hstepA, voffA);
;             PG8_WAIT_V(8); PG8_WAIT_L(0); PG8_BAR; PG8_MMA(0, 0, At, B0); PG8_MMA(0, 1, At, B1); PG8_BAR; PG8_SCHED;
;             PG8_LDA(At, 0, 1); PG8_STAGE(PG8_SB(0, 0), b2, voffB); PG8_STAGE(PG8_SB(0, 1), b2 + hstep, voffB); PG8_STAGE(PG8_SA(0, 0), a2, voffA);
.LBB0_753:
	ds_read_b128 v[146:149], v152
	ds_read_b128 v[156:159], v152 offset:1024
	ds_read_b128 v[160:163], v152 offset:2048
	ds_read_b128 v[164:167], v152 offset:3072
	ds_read_b128 v[168:171], v153
	ds_read_b128 v[172:175], v153 offset:1024
	ds_read_b128 v[176:179], v153 offset:2048
	ds_read_b128 v[180:183], v153 offset:3072
	s_add_u32 s38, s36, 0x600000
	s_addc_u32 s39, s37, 0
	s_cmp_eq_u32 s75, 28
	s_cselect_b32 s44, s71, s38
	s_cselect_b32 s45, s25, s39
	s_cselect_b32 s42, s72, s73
	s_cselect_b32 s43, s23, s74
	s_add_u32 s40, s44, 0x300000
	s_addc_u32 s41, s45, 0
	v_lshl_add_u64 v[216:217], s[36:37], 0, v[136:137]
	s_add_i32 m0, s50, 0xc000
	ds_read_b128 v[184:187], v154
	ds_read_b128 v[188:191], v154 offset:1024
	ds_read_b128 v[192:195], v154 offset:2048
	ds_read_b128 v[196:199], v154 offset:3072
	ds_read_b128 v[200:203], v154 offset:4096
	ds_read_b128 v[204:207], v154 offset:5120
	ds_read_b128 v[208:211], v154 offset:6144
	ds_read_b128 v[212:215], v154 offset:7168
	global_load_lds_dwordx4 v[216:217], off
	v_lshl_add_u64 v[216:217], s[36:37], 0, v[138:139]
	s_add_i32 m0, s50, 0xe000
	s_nop 0
	global_load_lds_dwordx4 v[216:217], off
	s_waitcnt vmcnt(8)
	s_waitcnt lgkmcnt(0)
	s_barrier
	s_setprio 1
	v_mfma_f32_16x16x32_bf16 v[116:119], v[146:149], v[184:187], v[116:119]
	v_mfma_f32_16x16x32_bf16 v[112:115], v[160:163], v[184:187], v[112:115]
	v_mfma_f32_16x16x32_bf16 v[100:103], v[146:149], v[192:195], v[100:103]
	v_mfma_f32_16x16x32_bf16 v[96:99], v[160:163], v[192:195], v[96:99]
	v_mfma_f32_16x16x32_bf16 v[84:87], v[146:149], v[200:203], v[84:87]
	v_mfma_f32_16x16x32_bf16 v[80:83], v[160:163], v[200:203], v[80:83]
	v_mfma_f32_16x16x32_bf16 v[68:71], v[146:149], v[208:211], v[68:71]
	v_mfma_f32_16x16x32_bf16 v[64:67], v[160:163], v[208:211], v[64:67]
	v_mfma_f32_16x16x32_bf16 v[116:119], v[156:159], v[188:191], v[116:119]
	v_mfma_f32_16x16x32_bf16 v[112:115], v[164:167], v[188:191], v[112:115]
	v_mfma_f32_16x16x32_bf16 v[100:103], v[156:159], v[196:199], v[100:103]
	v_mfma_f32_16x16x32_bf16 v[96:99], v[164:167], v[196:199], v[96:99]
	v_mfma_f32_16x16x32_bf16 v[84:87], v[156:159], v[204:207], v[84:87]
	v_mfma_f32_16x16x32_bf16 v[80:83], v[164:167], v[204:207], v[80:83]
	v_mfma_f32_16x16x32_bf16 v[68:71], v[156:159], v[212:215], v[68:71]
	v_mfma_f32_16x16x32_bf16 v[64:67], v[164:167], v[212:215], v[64:67]
	s_setprio 0
	s_setprio 1
	v_mfma_f32_16x16x32_bf16 v[124:127], v[168:171], v[184:187], v[124:127]
	v_mfma_f32_16x16x32_bf16 v[120:123], v[176:179], v[184:187], v[120:123]
	v_mfma_f32_16x16x32_bf16 v[108:111], v[168:171], v[192:195], v[108:111]
	v_mfma_f32_16x16x32_bf16 v[104:107], v[176:179], v[192:195], v[104:107]
	v_mfma_f32_16x16x32_bf16 v[92:95], v[168:171], v[200:203], v[92:95]
	v_mfma_f32_16x16x32_bf16 v[88:91], v[176:179], v[200:203], v[88:91]
	v_mfma_f32_16x16x32_bf16 v[76:79], v[168:171], v[208:211], v[76:79]
	v_mfma_f32_16x16x32_bf16 v[72:75], v[176:179], v[208:211], v[72:75]
	v_mfma_f32_16x16x32_bf16 v[124:127], v[172:175], v[188:191], v[124:127]
	v_mfma_f32_16x16x32_bf16 v[120:123], v[180:183], v[188:191], v[120:123]
	v_mfma_f32_16x16x32_bf16 v[108:111], v[172:175], v[196:199], v[108:111]
	v_mfma_f32_16x16x32_bf16 v[104:107], v[180:183], v[196:199], v[104:107]
	v_mfma_f32_16x16x32_bf16 v[92:95], v[172:175], v[204:207], v[92:95]
	v_mfma_f32_16x16x32_bf16 v[88:91], v[180:183], v[204:207], v[88:91]
	v_mfma_f32_16x16x32_bf16 v[76:79], v[172:175], v[212:215], v[76:79]
	v_mfma_f32_16x16x32_bf16 v[72:75], v[180:183], v[212:215], v[72:75]
	s_setprio 0
	s_barrier
	s_add_i32 s34, s65, s3
	v_lshl_add_u64 v[216:217], s[42:43], 0, v[132:133]
	s_mov_b32 m0, s34
	ds_read_b128 v[184:187], v154 offset:16384
	ds_read_b128 v[188:191], v154 offset:17408
	ds_read_b128 v[192:195], v154 offset:18432
	ds_read_b128 v[196:199], v154 offset:19456
	ds_read_b128 v[200:203], v154 offset:20480
	ds_read_b128 v[204:207], v154 offset:21504
	ds_read_b128 v[208:211], v154 offset:22528
	ds_read_b128 v[212:215], v154 offset:23552
	global_load_lds_dwordx4 v[216:217], off
	s_add_i32 m0, s34, 0x2000
	s_add_u32 s34, s42, 0x80000
	v_lshl_add_u64 v[218:219], s[42:43], 0, v[128:129]
	s_addc_u32 s35, s43, 0
	s_add_i32 s36, s66, s3
	global_load_lds_dwordx4 v[218:219], off
	v_lshl_add_u64 v[220:221], s[34:35], 0, v[132:133]
	s_mov_b32 m0, s36
	s_nop 0
	global_load_lds_dwordx4 v[220:221], off
	v_lshl_add_u64 v[220:221], s[34:35], 0, v[128:129]
	s_add_i32 m0, s36, 0x2000
	s_nop 0
	global_load_lds_dwordx4 v[220:221], off
	v_lshl_add_u64 v[220:221], s[44:45], 0, v[134:135]
	s_mov_b32 m0, s50
	s_nop 0
	global_load_lds_dwordx4 v[220:221], off
	v_lshl_add_u64 v[220:221], s[44:45], 0, v[130:131]
	s_mov_b32 m0, s51
	s_nop 0
	global_load_lds_dwordx4 v[220:221], off
	s_waitcnt vmcnt(8)
	s_waitcnt lgkmcnt(0)
	s_barrier
; #define PG8_STAGE(bufoff, gbase, voff) do { _Pragma("unroll") for (int _i = 0; _i < 2; ++_i) \
;         __builtin_amdgcn_global_load_lds((const unsigned*)((const char*)(gbase) + (voff)[_i]), (LAS unsigned*)(lds + (bufoff) + ldsw + _i * 8192), 16, 0, 0); } while (0)
; #define PG8_LDA(dst, b, h) do { _Pragma("unroll") for (int m = 0; m < 4; ++m) _Pragma("unroll") for (int k = 0; k < 2; ++k) dst[m][k] = *(const LAS bf16x8*)(lds + PG8_SA(b, h) + aoff + m * 2048 + k * 1024); } while (0)
; #define PG8_LDB(dst, b, h) do { _Pragma("unroll") for (int n = 0; n < 2; ++n) _Pragma("unroll") for (int k = 0; k < 2; ++k) dst[n][k] = *(const LAS bf16x8*)(lds + PG8_SB(b, h) + boff + n * 2048 + k * 1024); } while (0)
; #define PG8_MMA(ai, bj, At, Bt) do { __builtin_amdgcn_s_setprio(1); _Pragma("unroll") for (int m = 0; m < 4; ++m) _Pragma("unroll") for (int n = 0; n < 2; ++n) _Pragma("unroll") for (int k = 0; k < 2; ++k) \
;         acc[ai][bj][m][n] = __builtin_amdgcn_mfma_f32_16x16x32_bf16(Bt[n][k], At[m][k], acc[ai][bj][m][n], 0, 0, 0); __builtin_amdgcn_s_setprio(0); } while (0)
; #define PG8_WAIT_V(n) asm volatile("s_waitcnt vmcnt(" #n ")" ::: "memory")
; #define PG8_WAIT_L(n) asm volatile("s_waitcnt lgkmcnt(" #n ")" ::: "memory")
; #define PG8_BAR __builtin_amdgcn_s_barrier()
; #define PG8_SCHED __builtin_amdgcn_sched_barrier(0)
; template <class Epi, class Sched, bool ALIGN_EPI = false, bool SP2 = false, bool TWOA = false, bool AGM = false>
; __device__ __forceinline__ void gemm_phase(LAS unsigned char* lds, const Gemm g, const Sched& S, const Epi& E, int wid) {
;     ...
;             PG8_WAIT_V(8); PG8_WAIT_L(0); PG8_BAR; PG8_MMA(1, 0, At, B0); PG8_MMA(1, 1, At, B1); PG8_BAR; PG8_SCHED;
;             PG8_LDB(B0, 1, 0); PG8_LDB(B1, 1, 1); PG8_SCHED; PG8_LDA(At, 1, 0); PG8_STAGE(PG8_SA(0, 1), a2 + hstepA, voffA);
;             PG8_WAIT_V(8); PG8_WAIT_L(0); PG8_BAR; PG8_MMA(0, 0, At, B0); PG8_MMA(0, 1, At, B1); PG8_BAR; PG8_SCHED;
	s_setprio 1
	v_mfma_f32_16x16x32_bf16 v[52:55], v[146:149], v[184:187], v[52:55]
	v_mfma_f32_16x16x32_bf16 v[48:51], v[160:163], v[184:187], v[48:51]
	v_mfma_f32_16x16x32_bf16 v[36:39], v[146:149], v[192:195], v[36:39]
	v_mfma_f32_16x16x32_bf16 v[32:35], v[160:163], v[192:195], v[32:35]
	v_mfma_f32_16x16x32_bf16 v[20:23], v[146:149], v[200:203], v[20:23]
	v_mfma_f32_16x16x32_bf16 v[16:19], v[160:163], v[200:203], v[16:19]
	v_mfma_f32_16x16x32_bf16 v[4:7], v[146:149], v[208:211], v[4:7]
	v_mfma_f32_16x16x32_bf16 v[0:3], v[160:163], v[208:211], v[0:3]
	v_mfma_f32_16x16x32_bf16 v[52:55], v[156:159], v[188:191], v[52:55]
	v_mfma_f32_16x16x32_bf16 v[48:51], v[164:167], v[188:191], v[48:51]
	v_mfma_f32_16x16x32_bf16 v[36:39], v[156:159], v[196:199], v[36:39]
	v_mfma_f32_16x16x32_bf16 v[32:35], v[164:167], v[196:199], v[32:35]
	v_mfma_f32_16x16x32_bf16 v[20:23], v[156:159], v[204:207], v[20:23]
	v_mfma_f32_16x16x32_bf16 v[16:19], v[164:167], v[204:207], v[16:19]
	v_mfma_f32_16x16x32_bf16 v[4:7], v[156:159], v[212:215], v[4:7]
	v_mfma_f32_16x16x32_bf16 v[0:3], v[164:167], v[212:215], v[0:3]
	s_setprio 0
	s_setprio 1
	v_mfma_f32_16x16x32_bf16 v[60:63], v[168:171], v[184:187], v[60:63]
	v_mfma_f32_16x16x32_bf16 v[56:59], v[176:179], v[184:187], v[56:59]
	v_mfma_f32_16x16x32_bf16 v[44:47], v[168:171], v[192:195], v[44:47]
	v_mfma_f32_16x16x32_bf16 v[40:43], v[176:179], v[192:195], v[40:43]
	v_mfma_f32_16x16x32_bf16 v[28:31], v[168:171], v[200:203], v[28:31]
	v_mfma_f32_16x16x32_bf16 v[24:27], v[176:179], v[200:203], v[24:27]
	v_mfma_f32_16x16x32_bf16 v[12:15], v[168:171], v[208:211], v[12:15]
	v_mfma_f32_16x16x32_bf16 v[8:11], v[176:179], v[208:211], v[8:11]
	v_mfma_f32_16x16x32_bf16 v[60:63], v[172:175], v[188:191], v[60:63]
	v_mfma_f32_16x16x32_bf16 v[56:59], v[180:183], v[188:191], v[56:59]
	v_mfma_f32_16x16x32_bf16 v[44:47], v[172:175], v[196:199], v[44:47]
	v_mfma_f32_16x16x32_bf16 v[40:43], v[180:183], v[196:199], v[40:43]
	v_mfma_f32_16x16x32_bf16 v[28:31], v[172:175], v[204:207], v[28:31]
	v_mfma_f32_16x16x32_bf16 v[24:27], v[180:183], v[204:207], v[24:27]
	v_mfma_f32_16x16x32_bf16 v[12:15], v[172:175], v[212:215], v[12:15]
	v_mfma_f32_16x16x32_bf16 v[8:11], v[180:183], v[212:215], v[8:11]
	s_setprio 0
	s_barrier
	s_add_i32 s36, 0, 0x18000
	v_add_u32_e32 v155, s36, v151
	s_add_i32 s37, 0, 0x1c000
	ds_read_b128 v[146:149], v155
	ds_read_b128 v[156:159], v155 offset:1024
	ds_read_b128 v[160:163], v155 offset:2048
	ds_read_b128 v[164:167], v155 offset:3072
	v_add_u32_e32 v155, s37, v151
	ds_read_b128 v[168:171], v155
	ds_read_b128 v[172:175], v155 offset:1024
	ds_read_b128 v[176:179], v155 offset:2048
	ds_read_b128 v[180:183], v155 offset:3072
	s_add_u32 s34, s44, 0x1000
	s_addc_u32 s35, s45, 0
	s_mov_b32 m0, s52
	v_lshl_add_u64 v[220:221], s[34:35], 0, v[134:135]
	ds_read_b128 v[184:187], v154 offset:32768
	ds_read_b128 v[188:191], v154 offset:33792
	ds_read_b128 v[192:195], v154 offset:34816
	ds_read_b128 v[196:199], v154 offset:35840
	ds_read_b128 v[200:203], v154 offset:36864
	ds_read_b128 v[204:207], v154 offset:37888
	ds_read_b128 v[208:211], v154 offset:38912
	ds_read_b128 v[212:215], v154 offset:39936
	global_load_lds_dwordx4 v[220:221], off
	v_lshl_add_u64 v[220:221], s[34:35], 0, v[130:131]
	s_mov_b32 m0, s53
	s_nop 0
	global_load_lds_dwordx4 v[220:221], off
	s_waitcnt vmcnt(8)
	s_waitcnt lgkmcnt(0)
	s_barrier
	s_setprio 1
	v_mfma_f32_16x16x32_bf16 v[116:119], v[146:149], v[184:187], v[116:119]
	v_mfma_f32_16x16x32_bf16 v[112:115], v[160:163], v[184:187], v[112:115]
	v_mfma_f32_16x16x32_bf16 v[100:103], v[146:149], v[192:195], v[100:103]
	v_mfma_f32_16x16x32_bf16 v[96:99], v[160:163], v[192:195], v[96:99]
	v_mfma_f32_16x16x32_bf16 v[84:87], v[146:149], v[200:203], v[84:87]
	v_mfma_f32_16x16x32_bf16 v[80:83], v[160:163], v[200:203], v[80:83]
	v_mfma_f32_16x16x32_bf16 v[68:71], v[146:149], v[208:211], v[68:71]
	v_mfma_f32_16x16x32_bf16 v[64:67], v[160:163], v[208:211], v[64:67]
	v_mfma_f32_16x16x32_bf16 v[116:119], v[156:159], v[188:191], v[116:119]
	v_mfma_f32_16x16x32_bf16 v[112:115], v[164:167], v[188:191], v[112:115]
	v_mfma_f32_16x16x32_bf16 v[100:103], v[156:159], v[196:199], v[100:103]
	v_mfma_f32_16x16x32_bf16 v[96:99], v[164:167], v[196:199], v[96:99]
	v_mfma_f32_16x16x32_bf16 v[84:87], v[156:159], v[204:207], v[84:87]
	v_mfma_f32_16x16x32_bf16 v[80:83], v[164:167], v[204:207], v[80:83]
	v_mfma_f32_16x16x32_bf16 v[68:71], v[156:159], v[212:215], v[68:71]
	v_mfma_f32_16x16x32_bf16 v[64:67], v[164:167], v[212:215], v[64:67]
	s_setprio 0
	s_setprio 1
	v_mfma_f32_16x16x32_bf16 v[124:127], v[168:171], v[184:187], v[124:127]
	v_mfma_f32_16x16x32_bf16 v[120:123], v[176:179], v[184:187], v[120:123]
	v_mfma_f32_16x16x32_bf16 v[108:111], v[168:171], v[192:195], v[108:111]
	v_mfma_f32_16x16x32_bf16 v[104:107], v[176:179], v[192:195], v[104:107]
	v_mfma_f32_16x16x32_bf16 v[92:95], v[168:171], v[200:203], v[92:95]
	v_mfma_f32_16x16x32_bf16 v[88:91], v[176:179], v[200:203], v[88:91]
	v_mfma_f32_16x16x32_bf16 v[76:79], v[168:171], v[208:211], v[76:79]
	v_mfma_f32_16x16x32_bf16 v[72:75], v[176:179], v[208:211], v[72:75]
	v_mfma_f32_16x16x32_bf16 v[124:127], v[172:175], v[188:191], v[124:127]
	v_mfma_f32_16x16x32_bf16 v[120:123], v[180:183], v[188:191], v[120:123]
	v_mfma_f32_16x16x32_bf16 v[108:111], v[172:175], v[196:199], v[108:111]
	v_mfma_f32_16x16x32_bf16 v[104:107], v[180:183], v[196:199], v[104:107]
	v_mfma_f32_16x16x32_bf16 v[92:95], v[172:175], v[204:207], v[92:95]
	v_mfma_f32_16x16x32_bf16 v[88:91], v[180:183], v[204:207], v[88:91]
	v_mfma_f32_16x16x32_bf16 v[76:79], v[172:175], v[212:215], v[76:79]
	v_mfma_f32_16x16x32_bf16 v[72:75], v[180:183], v[212:215], v[72:75]
	s_setprio 0
	s_barrier
; #define PG8_STAGE(bufoff, gbase, voff) do { _Pragma("unroll") for (int _i = 0; _i < 2; ++_i) \
;         __builtin_amdgcn_global_load_lds((const unsigned*)((const char*)(gbase) + (voff)[_i]), (LAS unsigned*)(lds + (bufoff) + ldsw + _i * 8192), 16, 0, 0); } while (0)
; #define PG8_LDA(dst, b, h) do { _Pragma("unroll") for (int m = 0; m < 4; ++m) _Pragma("unroll") for (int k = 0; k < 2; ++k) dst[m][k] = *(const LAS bf16x8*)(lds + PG8_SA(b, h) + aoff + m * 2048 + k * 1024); } while (0)
; #define PG8_MMA(ai, bj, At, Bt) do { __builtin_amdgcn_s_setprio(1); _Pragma("unroll") for (int m = 0; m < 4; ++m) _Pragma("unroll") for (int n = 0; n < 2; ++n) _Pragma("unroll") for (int k = 0; k < 2; ++k) \
;         acc[ai][bj][m][n] = __builtin_amdgcn_mfma_f32_16x16x32_bf16(Bt[n][k], At[m][k], acc[ai][bj][m][n], 0, 0, 0); __builtin_amdgcn_s_setprio(0); } while (0)
; #define PG8_WAIT_V(n) asm volatile("s_waitcnt vmcnt(" #n ")" ::: "memory")
; #define PG8_WAIT_L(n) asm volatile("s_waitcnt lgkmcnt(" #n ")" ::: "memory")
; #define PG8_BAR __builtin_amdgcn_s_barrier()
; #define PG8_SCHED __builtin_amdgcn_sched_barrier(0)
; template <class Epi, class Sched, bool ALIGN_EPI = false, bool SP2 = false, bool TWOA = false, bool AGM = false>
; __device__ __forceinline__ void gemm_phase(LAS unsigned char* lds, const Gemm g, const Sched& S, const Epi& E, int wid) {
;     ...
;             PG8_LDA(At, 1, 1); PG8_STAGE(PG8_SB(1, 0), b3, voffB); PG8_STAGE(PG8_SB(1, 1), b3 + hstep, voffB); PG8_STAGE(PG8_SA(1, 0), a3, voffA);
;             PG8_WAIT_V(8); PG8_WAIT_L(0); PG8_BAR; PG8_MMA(1, 0, At, B0); PG8_MMA(1, 1, At, B1); PG8_BAR; PG8_SCHED;
	s_add_i32 s34, s36, s3
	v_lshl_add_u64 v[216:217], v[216:217], 0, s[12:13]
	s_mov_b32 m0, s34
	ds_read_b128 v[184:187], v154 offset:49152
	ds_read_b128 v[188:191], v154 offset:50176
	ds_read_b128 v[192:195], v154 offset:51200
	ds_read_b128 v[196:199], v154 offset:52224
	ds_read_b128 v[200:203], v154 offset:53248
	ds_read_b128 v[204:207], v154 offset:54272
	ds_read_b128 v[208:211], v154 offset:55296
	ds_read_b128 v[212:215], v154 offset:56320
	global_load_lds_dwordx4 v[216:217], off
	s_add_i32 m0, s34, 0x2000
	s_add_u32 s34, s42, 0x80080
	v_lshl_add_u64 v[216:217], v[218:219], 0, s[12:13]
	s_addc_u32 s35, s43, 0
	s_add_i32 s36, s37, s3
	global_load_lds_dwordx4 v[216:217], off
	v_lshl_add_u64 v[216:217], s[34:35], 0, v[132:133]
	s_mov_b32 m0, s36
	s_nop 0
	global_load_lds_dwordx4 v[216:217], off
	v_lshl_add_u64 v[216:217], s[34:35], 0, v[128:129]
	s_add_i32 m0, s36, 0x2000
	s_nop 0
	global_load_lds_dwordx4 v[216:217], off
	v_lshl_add_u64 v[216:217], s[40:41], 0, v[134:135]
	s_mov_b32 m0, s55
	s_nop 0
	global_load_lds_dwordx4 v[216:217], off
	v_lshl_add_u64 v[216:217], s[40:41], 0, v[130:131]
	s_mov_b32 m0, s56
	s_nop 0
	global_load_lds_dwordx4 v[216:217], off
	s_waitcnt vmcnt(8)
	s_waitcnt lgkmcnt(0)
	s_barrier
	s_setprio 1
	v_mfma_f32_16x16x32_bf16 v[52:55], v[146:149], v[184:187], v[52:55]
	v_mfma_f32_16x16x32_bf16 v[48:51], v[160:163], v[184:187], v[48:51]
	v_mfma_f32_16x16x32_bf16 v[36:39], v[146:149], v[192:195], v[36:39]
	v_mfma_f32_16x16x32_bf16 v[32:35], v[160:163], v[192:195], v[32:35]
	v_mfma_f32_16x16x32_bf16 v[20:23], v[146:149], v[200:203], v[20:23]
	v_mfma_f32_16x16x32_bf16 v[16:19], v[160:163], v[200:203], v[16:19]
	v_mfma_f32_16x16x32_bf16 v[4:7], v[146:149], v[208:211], v[4:7]
	v_mfma_f32_16x16x32_bf16 v[0:3], v[160:163], v[208:211], v[0:3]
	v_mfma_f32_16x16x32_bf16 v[52:55], v[156:159], v[188:191], v[52:55]
	v_mfma_f32_16x16x32_bf16 v[48:51], v[164:167], v[188:191], v[48:51]
	v_mfma_f32_16x16x32_bf16 v[36:39], v[156:159], v[196:199], v[36:39]
	v_mfma_f32_16x16x32_bf16 v[32:35], v[164:167], v[196:199], v[32:35]
	v_mfma_f32_16x16x32_bf16 v[20:23], v[156:159], v[204:207], v[20:23]
	v_mfma_f32_16x16x32_bf16 v[16:19], v[164:167], v[204:207], v[16:19]
	v_mfma_f32_16x16x32_bf16 v[4:7], v[156:159], v[212:215], v[4:7]
	v_mfma_f32_16x16x32_bf16 v[0:3], v[164:167], v[212:215], v[0:3]
	s_setprio 0
	s_setprio 1
	v_mfma_f32_16x16x32_bf16 v[60:63], v[168:171], v[184:187], v[60:63]
	v_mfma_f32_16x16x32_bf16 v[56:59], v[176:179], v[184:187], v[56:59]
	v_mfma_f32_16x16x32_bf16 v[44:47], v[168:171], v[192:195], v[44:47]
	v_mfma_f32_16x16x32_bf16 v[40:43], v[176:179], v[192:195], v[40:43]
	v_mfma_f32_16x16x32_bf16 v[28:31], v[168:171], v[200:203], v[28:31]
	v_mfma_f32_16x16x32_bf16 v[24:27], v[176:179], v[200:203], v[24:27]
	v_mfma_f32_16x16x32_bf16 v[12:15], v[168:171], v[208:211], v[12:15]
	v_mfma_f32_16x16x32_bf16 v[8:11], v[176:179], v[208:211], v[8:11]
	v_mfma_f32_16x16x32_bf16 v[60:63], v[172:175], v[188:191], v[60:63]
	v_mfma_f32_16x16x32_bf16 v[56:59], v[180:183], v[188:191], v[56:59]
	v_mfma_f32_16x16x32_bf16 v[44:47], v[172:175], v[196:199], v[44:47]
	v_mfma_f32_16x16x32_bf16 v[40:43], v[180:183], v[196:199], v[40:43]
	v_mfma_f32_16x16x32_bf16 v[28:31], v[172:175], v[204:207], v[28:31]
	v_mfma_f32_16x16x32_bf16 v[24:27], v[180:183], v[204:207], v[24:27]
	v_mfma_f32_16x16x32_bf16 v[12:15], v[172:175], v[212:215], v[12:15]
	v_mfma_f32_16x16x32_bf16 v[8:11], v[180:183], v[212:215], v[8:11]
	s_setprio 0
	s_barrier
	s_add_i32 s75, s75, 2
	s_add_u32 s73, s73, 0x100
	s_addc_u32 s74, s74, 0
	s_cmp_gt_u32 s75, 29
	s_mov_b64 s[36:37], s[38:39]
	s_cbranch_scc0 .LBB0_753
	s_and_b64 vcc, exec, s[20:21]
	s_cbranch_vccz .LBB0_756
	s_barrier

; #define PG8_STAGE(bufoff, gbase, voff) do { _Pragma("unroll") for (int _i = 0; _i < 2; ++_i) \
;         __builtin_amdgcn_global_load_lds((const unsigned*)((const char*)(gbase) + (voff)[_i]), (LAS unsigned*)(lds + (bufoff) + ldsw + _i * 8192), 16, 0, 0); } while (0)
; #define PG8_LDA(dst, b, h) do { _Pragma("unroll") for (int m = 0; m < 4; ++m) _Pragma("unroll") for (int k = 0; k < 2; ++k) dst[m][k] = *(const LAS bf16x8*)(lds + PG8_SA(b, h) + aoff + m * 2048 + k * 1024); } while (0)
; #define PG8_WAIT_V(n) asm volatile("s_waitcnt vmcnt(" #n ")" ::: "memory")
; #define PG8_WAIT_L(n) asm volatile("s_waitcnt lgkmcnt(" #n ")" ::: "memory")
; template <class Epi, class Sched, bool ALIGN_EPI = false, bool SP2 = false, bool TWOA = false, bool AGM = false>
; __device__ __forceinline__ void gemm_phase(LAS unsigned char* lds, const Gemm g, const Sched& S, const Epi& E, int wid) {
;     ...
;         const bool has_next = S.next(ui + 1, nxt);
;         const char* nA = has_next ? (const char*)g.A + (size_t)nxt.pm * tstepA : cA; const char* nB = has_next ? (const char*)g.Bt + (size_t)nxt.pn * tstep : cB;
;         for (int t = 0; t < nt; t += 2) {
;             const bool last = (t == nt - 2);
;             const char* cA2 = TWOA ? (const char*)g.A2 + (cA - (const char*)g.A) - (size_t)nh * kstepA : cA;
;             const char* a1_ = (TWOA && t + 1 >= nh ? cA2 : cA) + (size_t)(t + 1) * kstepA;
;             const char* a2_ = last ? nA : (TWOA && t + 2 >= nh ? cA2 : cA) + (size_t)(t + 2) * kstepA; const char* a1 = a1_; const char* a2 = a2_; const char* b2 = last ? nB : cB + (size_t)(t + 2) * kstep;
;             if constexpr (TWOA) { asm volatile("" : "+s"(a1)); asm volatile("" : "+s"(a2)); }
;             const char* a3 = a2 + kstepA; const char* b3 = b2 + kstep;
;             if (last && has_next) S.a_ready(nxt);
;             if constexpr (has_mid<Epi>::value) { if (t == nh) E.mid(acc, cur, wr, wc, fr, fq); }
;             if constexpr (SP2) {
;             PG8_LDB(B0, 0, 0); PG8_LDB(B1, 0, 1); PG8_SCHED; PG8_LDA(At, 0, 0); PG8_STAGE(PG8_SA(1, 1), a1 + hstepA, voffA);
;             PG8_WAIT_V(8); PG8_WAIT_L(0); PG8_BAR; PG8_MMA(0, 0, At, B0); PG8_MMA(0, 1, At, B1); PG8_BAR; PG8_SCHED;
;             PG8_LDA(At, 0, 1); PG8_STAGE(PG8_SB(0, 0), b2, voffB); PG8_STAGE(PG8_SB(0, 1), b2 + hstep, voffB); PG8_STAGE(PG8_SA(0, 0), a2, voffA);
.LBB0_826:
	v_add_u32_e32 v1, s65, v153
	ds_read_b128 v[132:135], v1
	ds_read_b128 v[136:139], v1 offset:1024
	ds_read_b128 v[158:161], v1 offset:2048
	ds_read_b128 v[162:165], v1 offset:3072
	v_add_u32_e32 v1, s66, v153
	ds_read_b128 v[166:169], v1
	ds_read_b128 v[170:173], v1 offset:1024
	ds_read_b128 v[174:177], v1 offset:2048
	ds_read_b128 v[178:181], v1 offset:3072
	s_add_u32 s74, s71, s36
	s_addc_u32 s75, s72, s37
	s_and_b64 s[34:35], s[42:43], exec
	s_cselect_b32 s43, s23, s75
	s_cselect_b32 s42, s68, s74
	s_add_u32 s34, s40, 0x80000
	s_addc_u32 s35, s41, 0
	v_lshl_add_u64 v[2:3], s[34:35], 0, v[146:147]
	s_add_i32 m0, s50, 0xc000
	ds_read_b128 v[182:185], v156
	ds_read_b128 v[186:189], v156 offset:1024
	ds_read_b128 v[190:193], v156 offset:2048
	ds_read_b128 v[194:197], v156 offset:3072
	ds_read_b128 v[198:201], v156 offset:4096
	ds_read_b128 v[202:205], v156 offset:5120
	ds_read_b128 v[206:209], v156 offset:6144
	ds_read_b128 v[210:213], v156 offset:7168
	global_load_lds_dwordx4 v[2:3], off
	v_lshl_add_u64 v[2:3], s[34:35], 0, v[142:143]
	s_add_i32 m0, s50, 0xe000
	s_nop 0
	global_load_lds_dwordx4 v[2:3], off
	s_waitcnt vmcnt(8)
	s_waitcnt lgkmcnt(0)
	s_barrier
	s_setprio 1
	v_mfma_f32_16x16x32_bf16 v[128:131], v[132:135], v[182:185], v[128:131]
	v_mfma_f32_16x16x32_bf16 v[124:127], v[158:161], v[182:185], v[124:127]
	v_mfma_f32_16x16x32_bf16 v[112:115], v[132:135], v[190:193], v[112:115]
	v_mfma_f32_16x16x32_bf16 v[108:111], v[158:161], v[190:193], v[108:111]
	v_mfma_f32_16x16x32_bf16 v[96:99], v[132:135], v[198:201], v[96:99]
	v_mfma_f32_16x16x32_bf16 v[92:95], v[158:161], v[198:201], v[92:95]
	v_mfma_f32_16x16x32_bf16 v[80:83], v[132:135], v[206:209], v[80:83]
	v_mfma_f32_16x16x32_bf16 v[76:79], v[158:161], v[206:209], v[76:79]
	v_mfma_f32_16x16x32_bf16 v[128:131], v[136:139], v[186:189], v[128:131]
	v_mfma_f32_16x16x32_bf16 v[124:127], v[162:165], v[186:189], v[124:127]
	v_mfma_f32_16x16x32_bf16 v[112:115], v[136:139], v[194:197], v[112:115]
	v_mfma_f32_16x16x32_bf16 v[108:111], v[162:165], v[194:197], v[108:111]
	v_mfma_f32_16x16x32_bf16 v[96:99], v[136:139], v[202:205], v[96:99]
	v_mfma_f32_16x16x32_bf16 v[92:95], v[162:165], v[202:205], v[92:95]
	v_mfma_f32_16x16x32_bf16 v[80:83], v[136:139], v[210:213], v[80:83]
	v_mfma_f32_16x16x32_bf16 v[76:79], v[162:165], v[210:213], v[76:79]
	s_setprio 0
	s_setprio 1
	v_mfma_f32_16x16x32_bf16 v[120:123], v[166:169], v[182:185], v[120:123]
	v_mfma_f32_16x16x32_bf16 v[116:119], v[174:177], v[182:185], v[116:119]
	v_mfma_f32_16x16x32_bf16 v[104:107], v[166:169], v[190:193], v[104:107]
	v_mfma_f32_16x16x32_bf16 v[100:103], v[174:177], v[190:193], v[100:103]
	v_mfma_f32_16x16x32_bf16 v[88:91], v[166:169], v[198:201], v[88:91]
	v_mfma_f32_16x16x32_bf16 v[84:87], v[174:177], v[198:201], v[84:87]
	v_mfma_f32_16x16x32_bf16 v[72:75], v[166:169], v[206:209], v[72:75]
	v_mfma_f32_16x16x32_bf16 v[68:71], v[174:177], v[206:209], v[68:71]
	v_mfma_f32_16x16x32_bf16 v[120:123], v[170:173], v[186:189], v[120:123]
	v_mfma_f32_16x16x32_bf16 v[116:119], v[178:181], v[186:189], v[116:119]
	v_mfma_f32_16x16x32_bf16 v[104:107], v[170:173], v[194:197], v[104:107]
	v_mfma_f32_16x16x32_bf16 v[100:103], v[178:181], v[194:197], v[100:103]
	v_mfma_f32_16x16x32_bf16 v[88:91], v[170:173], v[202:205], v[88:91]
	v_mfma_f32_16x16x32_bf16 v[84:87], v[178:181], v[202:205], v[84:87]
	v_mfma_f32_16x16x32_bf16 v[72:75], v[170:173], v[210:213], v[72:75]
	v_mfma_f32_16x16x32_bf16 v[68:71], v[178:181], v[210:213], v[68:71]
	s_setprio 0
	s_barrier
	s_add_i32 s34, s65, s47
	v_lshl_add_u64 v[214:215], s[42:43], 0, v[144:145]
	s_mov_b32 m0, s34
	ds_read_b128 v[182:185], v156 offset:16384
	ds_read_b128 v[186:189], v156 offset:17408
	ds_read_b128 v[190:193], v156 offset:18432
	ds_read_b128 v[194:197], v156 offset:19456
	ds_read_b128 v[198:201], v156 offset:20480
	ds_read_b128 v[202:205], v156 offset:21504
	ds_read_b128 v[206:209], v156 offset:22528
	ds_read_b128 v[210:213], v156 offset:23552
	global_load_lds_dwordx4 v[214:215], off
	s_add_i32 m0, s34, 0x2000
	s_add_u32 s34, s42, 0x100000
	v_lshl_add_u64 v[216:217], s[42:43], 0, v[140:141]
	s_addc_u32 s35, s43, 0
	s_add_i32 s40, s66, s47
	global_load_lds_dwordx4 v[216:217], off
	v_lshl_add_u64 v[2:3], s[34:35], 0, v[144:145]
	s_mov_b32 m0, s40
	v_lshl_add_u64 v[218:219], s[38:39], 0, v[146:147]
	global_load_lds_dwordx4 v[2:3], off
	v_lshl_add_u64 v[2:3], s[34:35], 0, v[140:141]
	s_add_i32 m0, s40, 0x2000
	v_lshl_add_u64 v[220:221], s[38:39], 0, v[142:143]
	global_load_lds_dwordx4 v[2:3], off
	s_mov_b32 m0, s50
	s_nop 0
	global_load_lds_dwordx4 v[218:219], off
	s_mov_b32 m0, s51
	s_nop 0
	global_load_lds_dwordx4 v[220:221], off
	s_waitcnt vmcnt(8)
	s_waitcnt lgkmcnt(0)
	s_barrier
; #define PG8_STAGE(bufoff, gbase, voff) do { _Pragma("unroll") for (int _i = 0; _i < 2; ++_i) \
;         __builtin_amdgcn_global_load_lds((const unsigned*)((const char*)(gbase) + (voff)[_i]), (LAS unsigned*)(lds + (bufoff) + ldsw + _i * 8192), 16, 0, 0); } while (0)
; #define PG8_LDA(dst, b, h) do { _Pragma("unroll") for (int m = 0; m < 4; ++m) _Pragma("unroll") for (int k = 0; k < 2; ++k) dst[m][k] = *(const LAS bf16x8*)(lds + PG8_SA(b, h) + aoff + m * 2048 + k * 1024); } while (0)
; #define PG8_LDB(dst, b, h) do { _Pragma("unroll") for (int n = 0; n < 2; ++n) _Pragma("unroll") for (int k = 0; k < 2; ++k) dst[n][k] = *(const LAS bf16x8*)(lds + PG8_SB(b, h) + boff + n * 2048 + k * 1024); } while (0)
; #define PG8_MMA(ai, bj, At, Bt) do { __builtin_amdgcn_s_setprio(1); _Pragma("unroll") for (int m = 0; m < 4; ++m) _Pragma("unroll") for (int n = 0; n < 2; ++n) _Pragma("unroll") for (int k = 0; k < 2; ++k) \
;         acc[ai][bj][m][n] = __builtin_amdgcn_mfma_f32_16x16x32_bf16(Bt[n][k], At[m][k], acc[ai][bj][m][n], 0, 0, 0); __builtin_amdgcn_s_setprio(0); } while (0)
; #define PG8_WAIT_V(n) asm volatile("s_waitcnt vmcnt(" #n ")" ::: "memory")
; #define PG8_WAIT_L(n) asm volatile("s_waitcnt lgkmcnt(" #n ")" ::: "memory")
; #define PG8_BAR __builtin_amdgcn_s_barrier()
; #define PG8_SCHED __builtin_amdgcn_sched_barrier(0)
; template <class Epi, class Sched, bool ALIGN_EPI = false, bool SP2 = false, bool TWOA = false, bool AGM = false>
; __device__ __forceinline__ void gemm_phase(LAS unsigned char* lds, const Gemm g, const Sched& S, const Epi& E, int wid) {
;     ...
;             PG8_WAIT_V(8); PG8_WAIT_L(0); PG8_BAR; PG8_MMA(1, 0, At, B0); PG8_MMA(1, 1, At, B1); PG8_BAR; PG8_SCHED;
;             PG8_LDB(B0, 1, 0); PG8_LDB(B1, 1, 1); PG8_SCHED; PG8_LDA(At, 1, 0); PG8_STAGE(PG8_SA(0, 1), a2 + hstepA, voffA);
;             PG8_WAIT_V(8); PG8_WAIT_L(0); PG8_BAR; PG8_MMA(0, 0, At, B0); PG8_MMA(0, 1, At, B1); PG8_BAR; PG8_SCHED;
	s_setprio 1
	v_mfma_f32_16x16x32_bf16 v[64:67], v[132:135], v[182:185], v[64:67]
	v_mfma_f32_16x16x32_bf16 v[60:63], v[158:161], v[182:185], v[60:63]
	v_mfma_f32_16x16x32_bf16 v[48:51], v[132:135], v[190:193], v[48:51]
	v_mfma_f32_16x16x32_bf16 v[44:47], v[158:161], v[190:193], v[44:47]
	v_mfma_f32_16x16x32_bf16 v[32:35], v[132:135], v[198:201], v[32:35]
	v_mfma_f32_16x16x32_bf16 v[28:31], v[158:161], v[198:201], v[28:31]
	v_mfma_f32_16x16x32_bf16 v[16:19], v[132:135], v[206:209], v[16:19]
	v_mfma_f32_16x16x32_bf16 v[12:15], v[158:161], v[206:209], v[12:15]
	v_mfma_f32_16x16x32_bf16 v[64:67], v[136:139], v[186:189], v[64:67]
	v_mfma_f32_16x16x32_bf16 v[60:63], v[162:165], v[186:189], v[60:63]
	v_mfma_f32_16x16x32_bf16 v[48:51], v[136:139], v[194:197], v[48:51]
	v_mfma_f32_16x16x32_bf16 v[44:47], v[162:165], v[194:197], v[44:47]
	v_mfma_f32_16x16x32_bf16 v[32:35], v[136:139], v[202:205], v[32:35]
	v_mfma_f32_16x16x32_bf16 v[28:31], v[162:165], v[202:205], v[28:31]
	v_mfma_f32_16x16x32_bf16 v[16:19], v[136:139], v[210:213], v[16:19]
	v_mfma_f32_16x16x32_bf16 v[12:15], v[162:165], v[210:213], v[12:15]
	s_setprio 0
	s_setprio 1
	v_mfma_f32_16x16x32_bf16 v[56:59], v[166:169], v[182:185], v[56:59]
	v_mfma_f32_16x16x32_bf16 v[52:55], v[174:177], v[182:185], v[52:55]
	v_mfma_f32_16x16x32_bf16 v[40:43], v[166:169], v[190:193], v[40:43]
	v_mfma_f32_16x16x32_bf16 v[36:39], v[174:177], v[190:193], v[36:39]
	v_mfma_f32_16x16x32_bf16 v[24:27], v[166:169], v[198:201], v[24:27]
	v_mfma_f32_16x16x32_bf16 v[20:23], v[174:177], v[198:201], v[20:23]
	v_mfma_f32_16x16x32_bf16 v[8:11], v[166:169], v[206:209], v[8:11]
	v_mfma_f32_16x16x32_bf16 v[2:5], v[174:177], v[206:209], v[4:7]
	v_mfma_f32_16x16x32_bf16 v[56:59], v[170:173], v[186:189], v[56:59]
	v_mfma_f32_16x16x32_bf16 v[52:55], v[178:181], v[186:189], v[52:55]
	v_mfma_f32_16x16x32_bf16 v[40:43], v[170:173], v[194:197], v[40:43]
	v_mfma_f32_16x16x32_bf16 v[36:39], v[178:181], v[194:197], v[36:39]
	v_mfma_f32_16x16x32_bf16 v[24:27], v[170:173], v[202:205], v[24:27]
	v_mfma_f32_16x16x32_bf16 v[20:23], v[178:181], v[202:205], v[20:23]
	v_mfma_f32_16x16x32_bf16 v[8:11], v[170:173], v[210:213], v[8:11]
	v_mfma_f32_16x16x32_bf16 v[2:5], v[178:181], v[210:213], v[2:5]
	s_setprio 0
	s_barrier
	s_add_i32 s40, 0, 0x18000
	v_add_u32_e32 v1, s40, v153
	s_add_i32 s41, 0, 0x1c000
	ds_read_b128 v[132:135], v1
	ds_read_b128 v[136:139], v1 offset:1024
	ds_read_b128 v[158:161], v1 offset:2048
	ds_read_b128 v[162:165], v1 offset:3072
	v_add_u32_e32 v1, s41, v153
	ds_read_b128 v[166:169], v1
	ds_read_b128 v[170:173], v1 offset:1024
	ds_read_b128 v[174:177], v1 offset:2048
	ds_read_b128 v[178:181], v1 offset:3072
	s_add_u32 s34, s38, 0x80000
	s_addc_u32 s35, s39, 0
	s_mov_b32 m0, s52
	v_lshl_add_u64 v[6:7], s[34:35], 0, v[146:147]
	ds_read_b128 v[182:185], v156 offset:32768
	ds_read_b128 v[186:189], v156 offset:33792
	ds_read_b128 v[190:193], v156 offset:34816
	ds_read_b128 v[194:197], v156 offset:35840
	ds_read_b128 v[198:201], v156 offset:36864
	ds_read_b128 v[202:205], v156 offset:37888
	ds_read_b128 v[206:209], v156 offset:38912
	ds_read_b128 v[210:213], v156 offset:39936
	global_load_lds_dwordx4 v[6:7], off
	v_lshl_add_u64 v[6:7], s[34:35], 0, v[142:143]
	s_mov_b32 m0, s53
	s_nop 0
	global_load_lds_dwordx4 v[6:7], off
	s_waitcnt vmcnt(8)
	s_waitcnt lgkmcnt(0)
	s_barrier
	s_setprio 1
	v_mfma_f32_16x16x32_bf16 v[128:131], v[132:135], v[182:185], v[128:131]
	v_mfma_f32_16x16x32_bf16 v[124:127], v[158:161], v[182:185], v[124:127]
	v_mfma_f32_16x16x32_bf16 v[112:115], v[132:135], v[190:193], v[112:115]
	v_mfma_f32_16x16x32_bf16 v[108:111], v[158:161], v[190:193], v[108:111]
	v_mfma_f32_16x16x32_bf16 v[96:99], v[132:135], v[198:201], v[96:99]
	v_mfma_f32_16x16x32_bf16 v[92:95], v[158:161], v[198:201], v[92:95]
	v_mfma_f32_16x16x32_bf16 v[80:83], v[132:135], v[206:209], v[80:83]
	v_mfma_f32_16x16x32_bf16 v[76:79], v[158:161], v[206:209], v[76:79]
	v_mfma_f32_16x16x32_bf16 v[128:131], v[136:139], v[186:189], v[128:131]
	v_mfma_f32_16x16x32_bf16 v[124:127], v[162:165], v[186:189], v[124:127]
	v_mfma_f32_16x16x32_bf16 v[112:115], v[136:139], v[194:197], v[112:115]
	v_mfma_f32_16x16x32_bf16 v[108:111], v[162:165], v[194:197], v[108:111]
	v_mfma_f32_16x16x32_bf16 v[96:99], v[136:139], v[202:205], v[96:99]
	v_mfma_f32_16x16x32_bf16 v[92:95], v[162:165], v[202:205], v[92:95]
	v_mfma_f32_16x16x32_bf16 v[80:83], v[136:139], v[210:213], v[80:83]
	v_mfma_f32_16x16x32_bf16 v[76:79], v[162:165], v[210:213], v[76:79]
	s_setprio 0
	s_setprio 1
	v_mfma_f32_16x16x32_bf16 v[120:123], v[166:169], v[182:185], v[120:123]
	v_mfma_f32_16x16x32_bf16 v[116:119], v[174:177], v[182:185], v[116:119]
	v_mfma_f32_16x16x32_bf16 v[104:107], v[166:169], v[190:193], v[104:107]
	v_mfma_f32_16x16x32_bf16 v[100:103], v[174:177], v[190:193], v[100:103]
	v_mfma_f32_16x16x32_bf16 v[88:91], v[166:169], v[198:201], v[88:91]
	v_mfma_f32_16x16x32_bf16 v[84:87], v[174:177], v[198:201], v[84:87]
	v_mfma_f32_16x16x32_bf16 v[72:75], v[166:169], v[206:209], v[72:75]
	v_mfma_f32_16x16x32_bf16 v[68:71], v[174:177], v[206:209], v[68:71]
	v_mfma_f32_16x16x32_bf16 v[120:123], v[170:173], v[186:189], v[120:123]
	v_mfma_f32_16x16x32_bf16 v[116:119], v[178:181], v[186:189], v[116:119]
	v_mfma_f32_16x16x32_bf16 v[104:107], v[170:173], v[194:197], v[104:107]
	v_mfma_f32_16x16x32_bf16 v[100:103], v[178:181], v[194:197], v[100:103]
	v_mfma_f32_16x16x32_bf16 v[88:91], v[170:173], v[202:205], v[88:91]
	v_mfma_f32_16x16x32_bf16 v[84:87], v[178:181], v[202:205], v[84:87]
	v_mfma_f32_16x16x32_bf16 v[72:75], v[170:173], v[210:213], v[72:75]
	v_mfma_f32_16x16x32_bf16 v[68:71], v[178:181], v[210:213], v[68:71]
	s_setprio 0
	s_barrier
; #define PG8_STAGE(bufoff, gbase, voff) do { _Pragma("unroll") for (int _i = 0; _i < 2; ++_i) \
;         __builtin_amdgcn_global_load_lds((const unsigned*)((const char*)(gbase) + (voff)[_i]), (LAS unsigned*)(lds + (bufoff) + ldsw + _i * 8192), 16, 0, 0); } while (0)
; #define PG8_LDA(dst, b, h) do { _Pragma("unroll") for (int m = 0; m < 4; ++m) _Pragma("unroll") for (int k = 0; k < 2; ++k) dst[m][k] = *(const LAS bf16x8*)(lds + PG8_SA(b, h) + aoff + m * 2048 + k * 1024); } while (0)
; #define PG8_MMA(ai, bj, At, Bt) do { __builtin_amdgcn_s_setprio(1); _Pragma("unroll") for (int m = 0; m < 4; ++m) _Pragma("unroll") for (int n = 0; n < 2; ++n) _Pragma("unroll") for (int k = 0; k < 2; ++k) \
;         acc[ai][bj][m][n] = __builtin_amdgcn_mfma_f32_16x16x32_bf16(Bt[n][k], At[m][k], acc[ai][bj][m][n], 0, 0, 0); __builtin_amdgcn_s_setprio(0); } while (0)
; #define PG8_WAIT_V(n) asm volatile("s_waitcnt vmcnt(" #n ")" ::: "memory")
; #define PG8_WAIT_L(n) asm volatile("s_waitcnt lgkmcnt(" #n ")" ::: "memory")
; #define PG8_BAR __builtin_amdgcn_s_barrier()
; #define PG8_SCHED __builtin_amdgcn_sched_barrier(0)
; template <class Epi, class Sched, bool ALIGN_EPI = false, bool SP2 = false, bool TWOA = false, bool AGM = false>
; __device__ __forceinline__ void gemm_phase(LAS unsigned char* lds, const Gemm g, const Sched& S, const Epi& E, int wid) {
;     ...
;             PG8_LDA(At, 1, 1); PG8_STAGE(PG8_SB(1, 0), b3, voffB); PG8_STAGE(PG8_SB(1, 1), b3 + hstep, voffB); PG8_STAGE(PG8_SA(1, 0), a3, voffA);
;             PG8_WAIT_V(8); PG8_WAIT_L(0); PG8_BAR; PG8_MMA(1, 0, At, B0); PG8_MMA(1, 1, At, B1); PG8_BAR; PG8_SCHED;
	s_add_i32 s34, s40, s47
	v_lshl_add_u64 v[6:7], v[214:215], 0, s[12:13]
	s_mov_b32 m0, s34
	ds_read_b128 v[182:185], v156 offset:49152
	ds_read_b128 v[186:189], v156 offset:50176
	ds_read_b128 v[190:193], v156 offset:51200
	ds_read_b128 v[194:197], v156 offset:52224
	ds_read_b128 v[198:201], v156 offset:53248
	ds_read_b128 v[202:205], v156 offset:54272
	ds_read_b128 v[206:209], v156 offset:55296
	ds_read_b128 v[210:213], v156 offset:56320
	global_load_lds_dwordx4 v[6:7], off
	s_add_i32 m0, s34, 0x2000
	s_add_u32 s34, s42, 0x100080
	v_lshl_add_u64 v[6:7], v[216:217], 0, s[12:13]
	s_addc_u32 s35, s43, 0
	s_add_i32 s38, s41, s47
	global_load_lds_dwordx4 v[6:7], off
	v_lshl_add_u64 v[6:7], s[34:35], 0, v[144:145]
	s_mov_b32 m0, s38
	s_nop 0
	global_load_lds_dwordx4 v[6:7], off
	v_lshl_add_u64 v[6:7], s[34:35], 0, v[140:141]
	s_add_i32 m0, s38, 0x2000
	s_nop 0
	global_load_lds_dwordx4 v[6:7], off
	v_lshl_add_u64 v[6:7], v[218:219], 0, s[12:13]
	s_mov_b32 m0, s55
	s_nop 0
	global_load_lds_dwordx4 v[6:7], off
	v_lshl_add_u64 v[6:7], v[220:221], 0, s[12:13]
	s_mov_b32 m0, s56
	s_nop 0
	global_load_lds_dwordx4 v[6:7], off
	s_waitcnt vmcnt(8)
	s_waitcnt lgkmcnt(0)
	s_barrier
	s_setprio 1
	v_mfma_f32_16x16x32_bf16 v[64:67], v[132:135], v[182:185], v[64:67]
	v_mfma_f32_16x16x32_bf16 v[60:63], v[158:161], v[182:185], v[60:63]
	v_mfma_f32_16x16x32_bf16 v[48:51], v[132:135], v[190:193], v[48:51]
	v_mfma_f32_16x16x32_bf16 v[44:47], v[158:161], v[190:193], v[44:47]
	v_mfma_f32_16x16x32_bf16 v[32:35], v[132:135], v[198:201], v[32:35]
	v_mfma_f32_16x16x32_bf16 v[28:31], v[158:161], v[198:201], v[28:31]
	v_mfma_f32_16x16x32_bf16 v[16:19], v[132:135], v[206:209], v[16:19]
	v_mfma_f32_16x16x32_bf16 v[12:15], v[158:161], v[206:209], v[12:15]
	v_mfma_f32_16x16x32_bf16 v[64:67], v[136:139], v[186:189], v[64:67]
	v_mfma_f32_16x16x32_bf16 v[60:63], v[162:165], v[186:189], v[60:63]
	v_mfma_f32_16x16x32_bf16 v[48:51], v[136:139], v[194:197], v[48:51]
	v_mfma_f32_16x16x32_bf16 v[44:47], v[162:165], v[194:197], v[44:47]
	v_mfma_f32_16x16x32_bf16 v[32:35], v[136:139], v[202:205], v[32:35]
	v_mfma_f32_16x16x32_bf16 v[28:31], v[162:165], v[202:205], v[28:31]
	v_mfma_f32_16x16x32_bf16 v[16:19], v[136:139], v[210:213], v[16:19]
	v_mfma_f32_16x16x32_bf16 v[12:15], v[162:165], v[210:213], v[12:15]
	s_setprio 0
	s_setprio 1
	v_mfma_f32_16x16x32_bf16 v[56:59], v[166:169], v[182:185], v[56:59]
	v_mfma_f32_16x16x32_bf16 v[52:55], v[174:177], v[182:185], v[52:55]
	v_mfma_f32_16x16x32_bf16 v[40:43], v[166:169], v[190:193], v[40:43]
	v_mfma_f32_16x16x32_bf16 v[36:39], v[174:177], v[190:193], v[36:39]
	v_mfma_f32_16x16x32_bf16 v[24:27], v[166:169], v[198:201], v[24:27]
	v_mfma_f32_16x16x32_bf16 v[20:23], v[174:177], v[198:201], v[20:23]
	v_mfma_f32_16x16x32_bf16 v[6:9], v[166:169], v[206:209], v[8:11]
	v_mfma_f32_16x16x32_bf16 v[2:5], v[174:177], v[206:209], v[2:5]
	v_mfma_f32_16x16x32_bf16 v[56:59], v[170:173], v[186:189], v[56:59]
	v_mfma_f32_16x16x32_bf16 v[52:55], v[178:181], v[186:189], v[52:55]
	v_mfma_f32_16x16x32_bf16 v[40:43], v[170:173], v[194:197], v[40:43]
	v_mfma_f32_16x16x32_bf16 v[36:39], v[178:181], v[194:197], v[36:39]
	v_mfma_f32_16x16x32_bf16 v[24:27], v[170:173], v[202:205], v[24:27]
	v_mfma_f32_16x16x32_bf16 v[20:23], v[178:181], v[202:205], v[20:23]
	v_mfma_f32_16x16x32_bf16 v[8:11], v[170:173], v[210:213], v[6:9]
	v_mfma_f32_16x16x32_bf16 v[4:7], v[178:181], v[210:213], v[2:5]
	s_setprio 0
	s_barrier
	s_add_u32 s36, s36, 0x100
	s_addc_u32 s37, s37, 0
	s_cmp_gt_u32 s73, 61
	s_cbranch_scc1 .LBB0_829

; #define PG8_STAGE(bufoff, gbase, voff) do { _Pragma("unroll") for (int _i = 0; _i < 2; ++_i) \
;         __builtin_amdgcn_global_load_lds((const unsigned*)((const char*)(gbase) + (voff)[_i]), (LAS unsigned*)(lds + (bufoff) + ldsw + _i * 8192), 16, 0, 0); } while (0)
; #define PG8_LDA(dst, b, h) do { _Pragma("unroll") for (int m = 0; m < 4; ++m) _Pragma("unroll") for (int k = 0; k < 2; ++k) dst[m][k] = *(const LAS bf16x8*)(lds + PG8_SA(b, h) + aoff + m * 2048 + k * 1024); } while (0)
; #define PG8_WAIT_V(n) asm volatile("s_waitcnt vmcnt(" #n ")" ::: "memory")
; #define PG8_WAIT_L(n) asm volatile("s_waitcnt lgkmcnt(" #n ")" ::: "memory")
; template <class Epi, class Sched, bool ALIGN_EPI = false, bool SP2 = false, bool TWOA = false, bool AGM = false>
; __device__ __forceinline__ void gemm_phase(LAS unsigned char* lds, const Gemm g, const Sched& S, const Epi& E, int wid) {
;     ...
;         const bool has_next = S.next(ui + 1, nxt);
;         const char* nA = has_next ? (const char*)g.A + (size_t)nxt.pm * tstepA : cA; const char* nB = has_next ? (const char*)g.Bt + (size_t)nxt.pn * tstep : cB;
;         for (int t = 0; t < nt; t += 2) {
;             const bool last = (t == nt - 2);
;             const char* cA2 = TWOA ? (const char*)g.A2 + (cA - (const char*)g.A) - (size_t)nh * kstepA : cA;
;             const char* a1_ = (TWOA && t + 1 >= nh ? cA2 : cA) + (size_t)(t + 1) * kstepA;
;             const char* a2_ = last ? nA : (TWOA && t + 2 >= nh ? cA2 : cA) + (size_t)(t + 2) * kstepA; const char* a1 = a1_; const char* a2 = a2_; const char* b2 = last ? nB : cB + (size_t)(t + 2) * kstep;
;             if constexpr (TWOA) { asm volatile("" : "+s"(a1)); asm volatile("" : "+s"(a2)); }
;             const char* a3 = a2 + kstepA; const char* b3 = b2 + kstep;
;             if (last && has_next) S.a_ready(nxt);
;             if constexpr (has_mid<Epi>::value) { if (t == nh) E.mid(acc, cur, wr, wc, fr, fq); }
;             if constexpr (SP2) {
;             PG8_LDB(B0, 0, 0); PG8_LDB(B1, 0, 1); PG8_SCHED; PG8_LDA(At, 0, 0); PG8_STAGE(PG8_SA(1, 1), a1 + hstepA, voffA);
;             PG8_WAIT_V(8); PG8_WAIT_L(0); PG8_BAR; PG8_MMA(0, 0, At, B0); PG8_MMA(0, 1, At, B1); PG8_BAR; PG8_SCHED;
;             PG8_LDA(At, 0, 1); PG8_STAGE(PG8_SB(0, 0), b2, voffB); PG8_STAGE(PG8_SB(0, 1), b2 + hstep, voffB); PG8_STAGE(PG8_SA(0, 0), a2, voffA);
.LBB0_901:
	ds_read_b128 v[146:149], v155
	ds_read_b128 v[158:161], v155 offset:1024
	ds_read_b128 v[162:165], v155 offset:2048
	ds_read_b128 v[166:169], v155 offset:3072
	ds_read_b128 v[170:173], v156
	ds_read_b128 v[174:177], v156 offset:1024
	ds_read_b128 v[178:181], v156 offset:2048
	ds_read_b128 v[182:185], v156 offset:3072
	s_add_u32 s38, s36, 0xfff00080
	s_addc_u32 s39, s37, -1
	s_cmp_eq_u32 s67, 60
	s_cselect_b32 s41, s27, s39
	s_cselect_b32 s40, s63, s38
	s_cselect_b32 s39, s25, s66
	s_cselect_b32 s38, s64, s65
	v_lshl_add_u64 v[150:151], s[36:37], 0, v[138:139]
	s_add_i32 m0, s35, 0xc000
	ds_read_b128 v[186:189], v157
	ds_read_b128 v[190:193], v157 offset:1024
	ds_read_b128 v[194:197], v157 offset:2048
	ds_read_b128 v[198:201], v157 offset:3072
	ds_read_b128 v[202:205], v157 offset:4096
	ds_read_b128 v[206:209], v157 offset:5120
	ds_read_b128 v[210:213], v157 offset:6144
	ds_read_b128 v[214:217], v157 offset:7168
	global_load_lds_dwordx4 v[150:151], off
	v_lshl_add_u64 v[150:151], s[36:37], 0, v[140:141]
	s_add_i32 m0, s35, 0xe000
	s_nop 0
	global_load_lds_dwordx4 v[150:151], off
	s_waitcnt vmcnt(8)
	s_waitcnt lgkmcnt(0)
	s_barrier
	s_setprio 1
	v_mfma_f32_16x16x32_bf16 v[124:127], v[146:149], v[186:189], v[124:127]
	v_mfma_f32_16x16x32_bf16 v[120:123], v[162:165], v[186:189], v[120:123]
	v_mfma_f32_16x16x32_bf16 v[116:119], v[146:149], v[194:197], v[116:119]
	v_mfma_f32_16x16x32_bf16 v[108:111], v[162:165], v[194:197], v[108:111]
	v_mfma_f32_16x16x32_bf16 v[100:103], v[146:149], v[202:205], v[100:103]
	v_mfma_f32_16x16x32_bf16 v[92:95], v[162:165], v[202:205], v[92:95]
	v_mfma_f32_16x16x32_bf16 v[84:87], v[146:149], v[210:213], v[84:87]
	v_mfma_f32_16x16x32_bf16 v[76:79], v[162:165], v[210:213], v[76:79]
	v_mfma_f32_16x16x32_bf16 v[124:127], v[158:161], v[190:193], v[124:127]
	v_mfma_f32_16x16x32_bf16 v[120:123], v[166:169], v[190:193], v[120:123]
	v_mfma_f32_16x16x32_bf16 v[116:119], v[158:161], v[198:201], v[116:119]
	v_mfma_f32_16x16x32_bf16 v[108:111], v[166:169], v[198:201], v[108:111]
	v_mfma_f32_16x16x32_bf16 v[100:103], v[158:161], v[206:209], v[100:103]
	v_mfma_f32_16x16x32_bf16 v[92:95], v[166:169], v[206:209], v[92:95]
	v_mfma_f32_16x16x32_bf16 v[84:87], v[158:161], v[214:217], v[84:87]
	v_mfma_f32_16x16x32_bf16 v[76:79], v[166:169], v[214:217], v[76:79]
	s_setprio 0
	s_setprio 1
	v_mfma_f32_16x16x32_bf16 v[112:115], v[170:173], v[186:189], v[112:115]
	v_mfma_f32_16x16x32_bf16 v[104:107], v[178:181], v[186:189], v[104:107]
	v_mfma_f32_16x16x32_bf16 v[96:99], v[170:173], v[194:197], v[96:99]
	v_mfma_f32_16x16x32_bf16 v[88:91], v[178:181], v[194:197], v[88:91]
	v_mfma_f32_16x16x32_bf16 v[80:83], v[170:173], v[202:205], v[80:83]
	v_mfma_f32_16x16x32_bf16 v[72:75], v[178:181], v[202:205], v[72:75]
	v_mfma_f32_16x16x32_bf16 v[68:71], v[170:173], v[210:213], v[68:71]
	v_mfma_f32_16x16x32_bf16 v[64:67], v[178:181], v[210:213], v[64:67]
	v_mfma_f32_16x16x32_bf16 v[112:115], v[174:177], v[190:193], v[112:115]
	v_mfma_f32_16x16x32_bf16 v[104:107], v[182:185], v[190:193], v[104:107]
	v_mfma_f32_16x16x32_bf16 v[96:99], v[174:177], v[198:201], v[96:99]
	v_mfma_f32_16x16x32_bf16 v[88:91], v[182:185], v[198:201], v[88:91]
	v_mfma_f32_16x16x32_bf16 v[80:83], v[174:177], v[206:209], v[80:83]
	v_mfma_f32_16x16x32_bf16 v[72:75], v[182:185], v[206:209], v[72:75]
	v_mfma_f32_16x16x32_bf16 v[68:71], v[174:177], v[214:217], v[68:71]
	v_mfma_f32_16x16x32_bf16 v[64:67], v[182:185], v[214:217], v[64:67]
	s_setprio 0
	s_barrier
	s_add_i32 s68, s54, s44
	v_lshl_add_u64 v[150:151], s[38:39], 0, v[132:133]
	s_mov_b32 m0, s68
	ds_read_b128 v[186:189], v157 offset:16384
	ds_read_b128 v[190:193], v157 offset:17408
	ds_read_b128 v[194:197], v157 offset:18432
	ds_read_b128 v[198:201], v157 offset:19456
	ds_read_b128 v[202:205], v157 offset:20480
	ds_read_b128 v[206:209], v157 offset:21504
	ds_read_b128 v[210:213], v157 offset:22528
	ds_read_b128 v[214:217], v157 offset:23552
	global_load_lds_dwordx4 v[150:151], off
	s_add_i32 m0, s68, 0x2000
	s_add_u32 s68, s38, 0x100000
	v_lshl_add_u64 v[218:219], s[38:39], 0, v[128:129]
	s_addc_u32 s69, s39, 0
	s_add_i32 s70, s55, s44
	global_load_lds_dwordx4 v[218:219], off
	v_lshl_add_u64 v[220:221], s[68:69], 0, v[132:133]
	s_mov_b32 m0, s70
	v_lshl_add_u64 v[222:223], s[40:41], 0, v[130:131]
	global_load_lds_dwordx4 v[220:221], off
	v_lshl_add_u64 v[220:221], s[68:69], 0, v[128:129]
	s_add_i32 m0, s70, 0x2000
	s_nop 0
	global_load_lds_dwordx4 v[220:221], off
	v_lshl_add_u64 v[220:221], s[40:41], 0, v[134:135]
	s_mov_b32 m0, s35
	s_nop 0
	global_load_lds_dwordx4 v[220:221], off
	s_mov_b32 m0, s47
	s_nop 0
	global_load_lds_dwordx4 v[222:223], off
	s_waitcnt vmcnt(8)
	s_waitcnt lgkmcnt(0)
	s_barrier
; #define PG8_STAGE(bufoff, gbase, voff) do { _Pragma("unroll") for (int _i = 0; _i < 2; ++_i) \
;         __builtin_amdgcn_global_load_lds((const unsigned*)((const char*)(gbase) + (voff)[_i]), (LAS unsigned*)(lds + (bufoff) + ldsw + _i * 8192), 16, 0, 0); } while (0)
; #define PG8_LDA(dst, b, h) do { _Pragma("unroll") for (int m = 0; m < 4; ++m) _Pragma("unroll") for (int k = 0; k < 2; ++k) dst[m][k] = *(const LAS bf16x8*)(lds + PG8_SA(b, h) + aoff + m * 2048 + k * 1024); } while (0)
; #define PG8_LDB(dst, b, h) do { _Pragma("unroll") for (int n = 0; n < 2; ++n) _Pragma("unroll") for (int k = 0; k < 2; ++k) dst[n][k] = *(const LAS bf16x8*)(lds + PG8_SB(b, h) + boff + n * 2048 + k * 1024); } while (0)
; #define PG8_MMA(ai, bj, At, Bt) do { __builtin_amdgcn_s_setprio(1); _Pragma("unroll") for (int m = 0; m < 4; ++m) _Pragma("unroll") for (int n = 0; n < 2; ++n) _Pragma("unroll") for (int k = 0; k < 2; ++k) \
;         acc[ai][bj][m][n] = __builtin_amdgcn_mfma_f32_16x16x32_bf16(Bt[n][k], At[m][k], acc[ai][bj][m][n], 0, 0, 0); __builtin_amdgcn_s_setprio(0); } while (0)
; #define PG8_WAIT_V(n) asm volatile("s_waitcnt vmcnt(" #n ")" ::: "memory")
; #define PG8_WAIT_L(n) asm volatile("s_waitcnt lgkmcnt(" #n ")" ::: "memory")
; #define PG8_BAR __builtin_amdgcn_s_barrier()
; #define PG8_SCHED __builtin_amdgcn_sched_barrier(0)
; template <class Epi, class Sched, bool ALIGN_EPI = false, bool SP2 = false, bool TWOA = false, bool AGM = false>
; __device__ __forceinline__ void gemm_phase(LAS unsigned char* lds, const Gemm g, const Sched& S, const Epi& E, int wid) {
;     ...
;             PG8_WAIT_V(8); PG8_WAIT_L(0); PG8_BAR; PG8_MMA(1, 0, At, B0); PG8_MMA(1, 1, At, B1); PG8_BAR; PG8_SCHED;
;             PG8_LDB(B0, 1, 0); PG8_LDB(B1, 1, 1); PG8_SCHED; PG8_LDA(At, 1, 0); PG8_STAGE(PG8_SA(0, 1), a2 + hstepA, voffA);
;             PG8_WAIT_V(8); PG8_WAIT_L(0); PG8_BAR; PG8_MMA(0, 0, At, B0); PG8_MMA(0, 1, At, B1); PG8_BAR; PG8_SCHED;
	s_setprio 1
	v_mfma_f32_16x16x32_bf16 v[60:63], v[146:149], v[186:189], v[60:63]
	v_mfma_f32_16x16x32_bf16 v[56:59], v[162:165], v[186:189], v[56:59]
	v_mfma_f32_16x16x32_bf16 v[52:55], v[146:149], v[194:197], v[52:55]
	v_mfma_f32_16x16x32_bf16 v[44:47], v[162:165], v[194:197], v[44:47]
	v_mfma_f32_16x16x32_bf16 v[36:39], v[146:149], v[202:205], v[36:39]
	v_mfma_f32_16x16x32_bf16 v[28:31], v[162:165], v[202:205], v[28:31]
	v_mfma_f32_16x16x32_bf16 v[20:23], v[146:149], v[210:213], v[20:23]
	v_mfma_f32_16x16x32_bf16 v[12:15], v[162:165], v[210:213], v[12:15]
	v_mfma_f32_16x16x32_bf16 v[60:63], v[158:161], v[190:193], v[60:63]
	v_mfma_f32_16x16x32_bf16 v[56:59], v[166:169], v[190:193], v[56:59]
	v_mfma_f32_16x16x32_bf16 v[52:55], v[158:161], v[198:201], v[52:55]
	v_mfma_f32_16x16x32_bf16 v[44:47], v[166:169], v[198:201], v[44:47]
	v_mfma_f32_16x16x32_bf16 v[36:39], v[158:161], v[206:209], v[36:39]
	v_mfma_f32_16x16x32_bf16 v[28:31], v[166:169], v[206:209], v[28:31]
	v_mfma_f32_16x16x32_bf16 v[20:23], v[158:161], v[214:217], v[20:23]
	v_mfma_f32_16x16x32_bf16 v[12:15], v[166:169], v[214:217], v[12:15]
	s_setprio 0
	s_setprio 1
	v_mfma_f32_16x16x32_bf16 v[48:51], v[170:173], v[186:189], v[48:51]
	v_mfma_f32_16x16x32_bf16 v[40:43], v[178:181], v[186:189], v[40:43]
	v_mfma_f32_16x16x32_bf16 v[32:35], v[170:173], v[194:197], v[32:35]
	v_mfma_f32_16x16x32_bf16 v[24:27], v[178:181], v[194:197], v[24:27]
	v_mfma_f32_16x16x32_bf16 v[16:19], v[170:173], v[202:205], v[16:19]
	v_mfma_f32_16x16x32_bf16 v[8:11], v[178:181], v[202:205], v[8:11]
	v_mfma_f32_16x16x32_bf16 v[4:7], v[170:173], v[210:213], v[4:7]
	v_mfma_f32_16x16x32_bf16 v[0:3], v[178:181], v[210:213], v[0:3]
	v_mfma_f32_16x16x32_bf16 v[48:51], v[174:177], v[190:193], v[48:51]
	v_mfma_f32_16x16x32_bf16 v[40:43], v[182:185], v[190:193], v[40:43]
	v_mfma_f32_16x16x32_bf16 v[32:35], v[174:177], v[198:201], v[32:35]
	v_mfma_f32_16x16x32_bf16 v[24:27], v[182:185], v[198:201], v[24:27]
	v_mfma_f32_16x16x32_bf16 v[16:19], v[174:177], v[206:209], v[16:19]
	v_mfma_f32_16x16x32_bf16 v[8:11], v[182:185], v[206:209], v[8:11]
	v_mfma_f32_16x16x32_bf16 v[4:7], v[174:177], v[214:217], v[4:7]
	v_mfma_f32_16x16x32_bf16 v[0:3], v[182:185], v[214:217], v[0:3]
	s_setprio 0
	s_barrier
	s_add_i32 s68, 0, 0x18000
	v_add_u32_e32 v136, s68, v153
	s_add_i32 s69, 0, 0x1c000
	ds_read_b128 v[146:149], v136
	ds_read_b128 v[158:161], v136 offset:1024
	ds_read_b128 v[162:165], v136 offset:2048
	ds_read_b128 v[166:169], v136 offset:3072
	v_add_u32_e32 v136, s69, v153
	ds_read_b128 v[170:173], v136
	ds_read_b128 v[174:177], v136 offset:1024
	ds_read_b128 v[178:181], v136 offset:2048
	ds_read_b128 v[182:185], v136 offset:3072
	s_add_u32 s40, s40, 0x100000
	s_addc_u32 s41, s41, 0
	s_mov_b32 m0, s48
	v_lshl_add_u64 v[224:225], s[40:41], 0, v[134:135]
	ds_read_b128 v[186:189], v157 offset:32768
	ds_read_b128 v[190:193], v157 offset:33792
	ds_read_b128 v[194:197], v157 offset:34816
	ds_read_b128 v[198:201], v157 offset:35840
	ds_read_b128 v[202:205], v157 offset:36864
	ds_read_b128 v[206:209], v157 offset:37888
	ds_read_b128 v[210:213], v157 offset:38912
	ds_read_b128 v[214:217], v157 offset:39936
	global_load_lds_dwordx4 v[224:225], off
	v_lshl_add_u64 v[224:225], s[40:41], 0, v[130:131]
	s_mov_b32 m0, s49
	s_nop 0
	global_load_lds_dwordx4 v[224:225], off
	s_waitcnt vmcnt(8)
	s_waitcnt lgkmcnt(0)
	s_barrier
	s_setprio 1
	v_mfma_f32_16x16x32_bf16 v[124:127], v[146:149], v[186:189], v[124:127]
	v_mfma_f32_16x16x32_bf16 v[120:123], v[162:165], v[186:189], v[120:123]
	v_mfma_f32_16x16x32_bf16 v[116:119], v[146:149], v[194:197], v[116:119]
	v_mfma_f32_16x16x32_bf16 v[108:111], v[162:165], v[194:197], v[108:111]
	v_mfma_f32_16x16x32_bf16 v[100:103], v[146:149], v[202:205], v[100:103]
	v_mfma_f32_16x16x32_bf16 v[92:95], v[162:165], v[202:205], v[92:95]
	v_mfma_f32_16x16x32_bf16 v[84:87], v[146:149], v[210:213], v[84:87]
	v_mfma_f32_16x16x32_bf16 v[76:79], v[162:165], v[210:213], v[76:79]
	v_mfma_f32_16x16x32_bf16 v[124:127], v[158:161], v[190:193], v[124:127]
	v_mfma_f32_16x16x32_bf16 v[120:123], v[166:169], v[190:193], v[120:123]
	v_mfma_f32_16x16x32_bf16 v[116:119], v[158:161], v[198:201], v[116:119]
	v_mfma_f32_16x16x32_bf16 v[108:111], v[166:169], v[198:201], v[108:111]
	v_mfma_f32_16x16x32_bf16 v[100:103], v[158:161], v[206:209], v[100:103]
	v_mfma_f32_16x16x32_bf16 v[92:95], v[166:169], v[206:209], v[92:95]
	v_mfma_f32_16x16x32_bf16 v[84:87], v[158:161], v[214:217], v[84:87]
	v_mfma_f32_16x16x32_bf16 v[76:79], v[166:169], v[214:217], v[76:79]
	s_setprio 0
	s_setprio 1
	v_mfma_f32_16x16x32_bf16 v[112:115], v[170:173], v[186:189], v[112:115]
	v_mfma_f32_16x16x32_bf16 v[104:107], v[178:181], v[186:189], v[104:107]
	v_mfma_f32_16x16x32_bf16 v[96:99], v[170:173], v[194:197], v[96:99]
	v_mfma_f32_16x16x32_bf16 v[88:91], v[178:181], v[194:197], v[88:91]
	v_mfma_f32_16x16x32_bf16 v[80:83], v[170:173], v[202:205], v[80:83]
	v_mfma_f32_16x16x32_bf16 v[72:75], v[178:181], v[202:205], v[72:75]
	v_mfma_f32_16x16x32_bf16 v[68:71], v[170:173], v[210:213], v[68:71]
	v_mfma_f32_16x16x32_bf16 v[64:67], v[178:181], v[210:213], v[64:67]
	v_mfma_f32_16x16x32_bf16 v[112:115], v[174:177], v[190:193], v[112:115]
	v_mfma_f32_16x16x32_bf16 v[104:107], v[182:185], v[190:193], v[104:107]
	v_mfma_f32_16x16x32_bf16 v[96:99], v[174:177], v[198:201], v[96:99]
	v_mfma_f32_16x16x32_bf16 v[88:91], v[182:185], v[198:201], v[88:91]
	v_mfma_f32_16x16x32_bf16 v[80:83], v[174:177], v[206:209], v[80:83]
	v_mfma_f32_16x16x32_bf16 v[72:75], v[182:185], v[206:209], v[72:75]
	v_mfma_f32_16x16x32_bf16 v[68:71], v[174:177], v[214:217], v[68:71]
	v_mfma_f32_16x16x32_bf16 v[64:67], v[182:185], v[214:217], v[64:67]
	s_setprio 0
	s_barrier
; #define PG8_STAGE(bufoff, gbase, voff) do { _Pragma("unroll") for (int _i = 0; _i < 2; ++_i) \
;         __builtin_amdgcn_global_load_lds((const unsigned*)((const char*)(gbase) + (voff)[_i]), (LAS unsigned*)(lds + (bufoff) + ldsw + _i * 8192), 16, 0, 0); } while (0)
; #define PG8_LDA(dst, b, h) do { _Pragma("unroll") for (int m = 0; m < 4; ++m) _Pragma("unroll") for (int k = 0; k < 2; ++k) dst[m][k] = *(const LAS bf16x8*)(lds + PG8_SA(b, h) + aoff + m * 2048 + k * 1024); } while (0)
; #define PG8_MMA(ai, bj, At, Bt) do { __builtin_amdgcn_s_setprio(1); _Pragma("unroll") for (int m = 0; m < 4; ++m) _Pragma("unroll") for (int n = 0; n < 2; ++n) _Pragma("unroll") for (int k = 0; k < 2; ++k) \
;         acc[ai][bj][m][n] = __builtin_amdgcn_mfma_f32_16x16x32_bf16(Bt[n][k], At[m][k], acc[ai][bj][m][n], 0, 0, 0); __builtin_amdgcn_s_setprio(0); } while (0)
; #define PG8_WAIT_V(n) asm volatile("s_waitcnt vmcnt(" #n ")" ::: "memory")
; #define PG8_WAIT_L(n) asm volatile("s_waitcnt lgkmcnt(" #n ")" ::: "memory")
; #define PG8_BAR __builtin_amdgcn_s_barrier()
; #define PG8_SCHED __builtin_amdgcn_sched_barrier(0)
; template <class Epi, class Sched, bool ALIGN_EPI = false, bool SP2 = false, bool TWOA = false, bool AGM = false>
; __device__ __forceinline__ void gemm_phase(LAS unsigned char* lds, const Gemm g, const Sched& S, const Epi& E, int wid) {
;     ...
;             PG8_LDA(At, 1, 1); PG8_STAGE(PG8_SB(1, 0), b3, voffB); PG8_STAGE(PG8_SB(1, 1), b3 + hstep, voffB); PG8_STAGE(PG8_SA(1, 0), a3, voffA);
;             PG8_WAIT_V(8); PG8_WAIT_L(0); PG8_BAR; PG8_MMA(1, 0, At, B0); PG8_MMA(1, 1, At, B1); PG8_BAR; PG8_SCHED;
	s_add_i32 s40, s68, s44
	v_lshl_add_u64 v[150:151], v[150:151], 0, s[6:7]
	s_mov_b32 m0, s40
	ds_read_b128 v[186:189], v157 offset:49152
	ds_read_b128 v[190:193], v157 offset:50176
	ds_read_b128 v[194:197], v157 offset:51200
	ds_read_b128 v[198:201], v157 offset:52224
	ds_read_b128 v[202:205], v157 offset:53248
	ds_read_b128 v[206:209], v157 offset:54272
	ds_read_b128 v[210:213], v157 offset:55296
	ds_read_b128 v[214:217], v157 offset:56320
	global_load_lds_dwordx4 v[150:151], off
	s_add_i32 m0, s40, 0x2000
	s_add_u32 s38, s38, 0x100080
	v_lshl_add_u64 v[150:151], v[218:219], 0, s[6:7]
	s_addc_u32 s39, s39, 0
	s_add_i32 s40, s69, s44
	global_load_lds_dwordx4 v[150:151], off
	v_lshl_add_u64 v[150:151], s[38:39], 0, v[132:133]
	s_mov_b32 m0, s40
	s_nop 0
	global_load_lds_dwordx4 v[150:151], off
	v_lshl_add_u64 v[150:151], s[38:39], 0, v[128:129]
	s_add_i32 m0, s40, 0x2000
	s_nop 0
	global_load_lds_dwordx4 v[150:151], off
	v_lshl_add_u64 v[150:151], v[220:221], 0, s[6:7]
	s_mov_b32 m0, s52
	s_nop 0
	global_load_lds_dwordx4 v[150:151], off
	v_lshl_add_u64 v[150:151], v[222:223], 0, s[6:7]
	s_mov_b32 m0, s53
	s_nop 0
	global_load_lds_dwordx4 v[150:151], off
	s_waitcnt vmcnt(8)
	s_waitcnt lgkmcnt(0)
	s_barrier
	s_setprio 1
	v_mfma_f32_16x16x32_bf16 v[60:63], v[146:149], v[186:189], v[60:63]
	v_mfma_f32_16x16x32_bf16 v[56:59], v[162:165], v[186:189], v[56:59]
	v_mfma_f32_16x16x32_bf16 v[52:55], v[146:149], v[194:197], v[52:55]
	v_mfma_f32_16x16x32_bf16 v[44:47], v[162:165], v[194:197], v[44:47]
	v_mfma_f32_16x16x32_bf16 v[36:39], v[146:149], v[202:205], v[36:39]
	v_mfma_f32_16x16x32_bf16 v[28:31], v[162:165], v[202:205], v[28:31]
	v_mfma_f32_16x16x32_bf16 v[20:23], v[146:149], v[210:213], v[20:23]
	v_mfma_f32_16x16x32_bf16 v[12:15], v[162:165], v[210:213], v[12:15]
	v_mfma_f32_16x16x32_bf16 v[60:63], v[158:161], v[190:193], v[60:63]
	v_mfma_f32_16x16x32_bf16 v[56:59], v[166:169], v[190:193], v[56:59]
	v_mfma_f32_16x16x32_bf16 v[52:55], v[158:161], v[198:201], v[52:55]
	v_mfma_f32_16x16x32_bf16 v[44:47], v[166:169], v[198:201], v[44:47]
	v_mfma_f32_16x16x32_bf16 v[36:39], v[158:161], v[206:209], v[36:39]
	v_mfma_f32_16x16x32_bf16 v[28:31], v[166:169], v[206:209], v[28:31]
	v_mfma_f32_16x16x32_bf16 v[20:23], v[158:161], v[214:217], v[20:23]
	v_mfma_f32_16x16x32_bf16 v[12:15], v[166:169], v[214:217], v[12:15]
	s_setprio 0
	s_setprio 1
	v_mfma_f32_16x16x32_bf16 v[48:51], v[170:173], v[186:189], v[48:51]
	v_mfma_f32_16x16x32_bf16 v[40:43], v[178:181], v[186:189], v[40:43]
	v_mfma_f32_16x16x32_bf16 v[32:35], v[170:173], v[194:197], v[32:35]
	v_mfma_f32_16x16x32_bf16 v[24:27], v[178:181], v[194:197], v[24:27]
	v_mfma_f32_16x16x32_bf16 v[16:19], v[170:173], v[202:205], v[16:19]
	v_mfma_f32_16x16x32_bf16 v[8:11], v[178:181], v[202:205], v[8:11]
	v_mfma_f32_16x16x32_bf16 v[4:7], v[170:173], v[210:213], v[4:7]
	v_mfma_f32_16x16x32_bf16 v[0:3], v[178:181], v[210:213], v[0:3]
	v_mfma_f32_16x16x32_bf16 v[48:51], v[174:177], v[190:193], v[48:51]
	v_mfma_f32_16x16x32_bf16 v[40:43], v[182:185], v[190:193], v[40:43]
	v_mfma_f32_16x16x32_bf16 v[32:35], v[174:177], v[198:201], v[32:35]
	v_mfma_f32_16x16x32_bf16 v[24:27], v[182:185], v[198:201], v[24:27]
	v_mfma_f32_16x16x32_bf16 v[16:19], v[174:177], v[206:209], v[16:19]
	v_mfma_f32_16x16x32_bf16 v[8:11], v[182:185], v[206:209], v[8:11]
	v_mfma_f32_16x16x32_bf16 v[4:7], v[174:177], v[214:217], v[4:7]
	v_mfma_f32_16x16x32_bf16 v[0:3], v[182:185], v[214:217], v[0:3]
	s_setprio 0
	s_barrier
	s_add_i32 s67, s67, 2
	s_add_u32 s36, s36, 0x100
	s_addc_u32 s37, s37, 0
	s_add_u32 s65, s65, 0x100
	s_addc_u32 s66, s66, 0
	s_cmp_gt_u32 s67, 61
	s_cbranch_scc0 .LBB0_901
	s_and_b64 vcc, exec, s[8:9]
	s_cbranch_vccz .LBB0_904
	s_barrier
